# phase_gla_prep: hand-written fast path for gridDim=256 (all 32 A fragments of the 64x16x2048 gate GEMM and the weight rows loaded up front, k words of the reverse decay sweep prefetched 32 tokens ahea
# speedup vs baseline: 1.0293x; 1.0168x over previous
; #define LAS __attribute__((address_space(3)))
; DI int otid() { int t = threadIdx.x; asm volatile("" : "+v"(t)); return t; }
; DI void phase_gla_prep(const Params& p, LAS unsigned char* lds) {
;     ...
;     const int tid = otid(), ch0 = tid * 2;
;     float wg0[16], wg1[16];
; #pragma unroll
;     for (int r = 0; r < 16; ++r) { wg0[r] = p.in[9][r * 1024 + ch0]; wg1[r] = p.in[9][r * 1024 + ch0 + 1]; }
;     const float bs0 = p.in[10][ch0], bs1 = p.in[10][ch0 + 1];
;     for (int u = blockIdx.x; u < 256; u += gridDim.x) {
;         const size_t tokb = (size_t)u * 64;
;         __syncthreads();
;         {
;             LAS bf16_t* wl = (LAS bf16_t*)(lds + 8192);
;             LAS float* part = (LAS float*)(lds + 4096);
;             const bf16_t* wsrc = (const bf16_t*)(p.ws + W_B_IN) + (size_t)6144 * 2048;
; #pragma unroll
;             for (int i = 0; i < 8; ++i) { const int c = tid + i * 512; *(LAS u32x4*)(wl + (c >> 8) * 2056 + (c & 255) * 8) = *(const u32x4*)(wsrc + (size_t)c * 8); }
;             __syncthreads();
;             const int w = tid >> 6, lane = tid & 63, i16 = lane & 15, quad = lane >> 4, mt = w & 3, kh = w >> 2;
;             const bf16_t* xr = (const bf16_t*)(p.ws + XG) + (tokb + 16 * mt + i16) * DM + kh * 1024 + 8 * quad;
;             f32x4 acc = {0.f, 0.f, 0.f, 0.f};
; #pragma unroll 8
;             for (int ks = 0; ks < 32; ++ks) {
;                 const bf16x8 a = *(const bf16x8*)(xr + 32 * ks);
.LBB0_506:
	s_or_b64 exec, exec, s[6:7]
	s_cmpk_lt_i32 s2, 0x100
	s_waitcnt lgkmcnt(0)
	v_mov_b32_e32 v0, v181
	s_cselect_b64 s[16:17], -1, 0
	s_cmpk_gt_i32 s2, 0xff
	s_movk_i32 s14, 0x100
	s_barrier
	s_cbranch_scc1 .LBB0_517
	s_cmp_eq_u32 s18, 0x100
	s_cbranch_scc0 .Lgp_orig
	s_load_dwordx2 s[6:7], s[0:1], 0xf0
	s_load_dwordx4 s[8:11], s[0:1], 0x48
	v_and_b32_e32 v96, 63, v181
	v_and_b32_e32 v97, 15, v181
	v_lshrrev_b32_e32 v98, 4, v96
	v_lshrrev_b32_e32 v99, 6, v181
	v_and_b32_e32 v100, 3, v99
	v_lshrrev_b32_e32 v101, 2, v99
	s_nop 1
	v_readfirstlane_b32 s40, v101
	v_lshl_add_u32 v102, v100, 4, v97
	v_lshlrev_b32_e32 v160, 12, v102
	v_lshl_add_u32 v160, v101, 11, v160
	v_lshl_add_u32 v160, v98, 4, v160
	v_mul_u32_u24_e32 v163, 0x1010, v97
	v_lshl_add_u32 v163, v101, 11, v163
	v_lshl_add_u32 v163, v98, 4, v163
	v_add_u32_e32 v163, 0x2000, v163
	v_lshlrev_b32_e32 v161, 4, v181
	v_lshrrev_b32_e32 v103, 8, v181
	v_and_b32_e32 v104, 0xff, v181
	v_mul_u32_u24_e32 v162, 0x1010, v103
	v_lshl_add_u32 v162, v104, 4, v162
	v_add_u32_e32 v162, 0x2000, v162
	v_lshlrev_b32_e32 v105, 2, v98
	v_lshl_add_u32 v105, v100, 4, v105
	v_lshlrev_b32_e32 v164, 6, v105
	v_lshl_add_u32 v164, v97, 2, v164
	v_lshlrev_b32_e32 v168, 2, v105
	v_lshlrev_b32_e32 v165, 3, v181
	v_lshlrev_b32_e32 v166, 2, v181
	v_mov_b32_e32 v167, 0
	v_mov_b32_e32 v186, 0x3fb8aa3b
	v_mov_b32_e32 v187, 0x3fb8aa3b
	v_mov_b32_e32 v188, 0x3d800000
	v_mov_b32_e32 v189, 0x3d800000
	v_mov_b32_e32 v190, 0x3f800000
	v_mov_b32_e32 v191, 0x3f800000
	s_mov_b32 s34, 0xbfb8aa3b
	s_mov_b32 s35, 0xbf317218
	s_mov_b32 s38, 0x3a000000
	s_waitcnt lgkmcnt(0)
	s_add_u32 s26, s6, 0x4000000
	s_addc_u32 s27, s7, 0
	s_lshl_b32 s41, s2, 18
	s_add_u32 s28, s6, 0x1bf00000
	s_addc_u32 s29, s7, 0
	s_add_u32 s28, s28, s41
	s_addc_u32 s29, s29, 0
	s_lshl_b32 s41, s2, 8
	s_add_u32 s42, s6, 0x1ff10000
	s_addc_u32 s43, s7, 0
	s_add_u32 s42, s42, s41
	s_addc_u32 s43, s43, 0
	s_mul_i32 s41, s2, 0xc8000
	s_mul_hi_u32 s44, s2, 0xc8000
	s_add_u32 s30, s6, 0xbf00800
	s_addc_u32 s31, s7, 0
	s_add_u32 s30, s30, s41
	s_addc_u32 s31, s31, s44
	s_add_u32 s30, s30, 0xc4e00
	s_addc_u32 s31, s31, 0
	s_mov_b64 s[46:47], s[30:31]
	s_lshl_b32 s41, s2, 12
	s_add_u32 s48, s6, 0x18700000
	s_addc_u32 s49, s7, 0
	s_add_u32 s48, s48, s41
	s_addc_u32 s49, s49, 0
	s_mov_b64 s[24:25], s[26:27]
	global_load_dwordx4 v[128:131], v161, s[24:25]
	s_add_u32 s24, s24, 0x2000
	s_addc_u32 s25, s25, 0
	global_load_dwordx4 v[132:135], v161, s[24:25]
	s_add_u32 s24, s24, 0x2000
	s_addc_u32 s25, s25, 0
	global_load_dwordx4 v[136:139], v161, s[24:25]
	s_add_u32 s24, s24, 0x2000
	s_addc_u32 s25, s25, 0
	global_load_dwordx4 v[140:143], v161, s[24:25]
	s_add_u32 s24, s24, 0x2000
	s_addc_u32 s25, s25, 0
	global_load_dwordx4 v[144:147], v161, s[24:25]
	s_add_u32 s24, s24, 0x2000
	s_addc_u32 s25, s25, 0
	global_load_dwordx4 v[148:151], v161, s[24:25]
	s_add_u32 s24, s24, 0x2000
	s_addc_u32 s25, s25, 0
	global_load_dwordx4 v[152:155], v161, s[24:25]
	s_add_u32 s24, s24, 0x2000
	s_addc_u32 s25, s25, 0
	global_load_dwordx4 v[156:159], v161, s[24:25]
	global_load_dwordx4 v[0:3], v160, s[28:29] offset:0
	global_load_dwordx4 v[4:7], v160, s[28:29] offset:64
	global_load_dwordx4 v[8:11], v160, s[28:29] offset:128
	global_load_dwordx4 v[12:15], v160, s[28:29] offset:192
	global_load_dwordx4 v[16:19], v160, s[28:29] offset:256
	global_load_dwordx4 v[20:23], v160, s[28:29] offset:320
	global_load_dwordx4 v[24:27], v160, s[28:29] offset:384
	global_load_dwordx4 v[28:31], v160, s[28:29] offset:448
	global_load_dwordx4 v[32:35], v160, s[28:29] offset:512
	global_load_dwordx4 v[36:39], v160, s[28:29] offset:576
	global_load_dwordx4 v[40:43], v160, s[28:29] offset:640
	global_load_dwordx4 v[44:47], v160, s[28:29] offset:704
	global_load_dwordx4 v[48:51], v160, s[28:29] offset:768
	global_load_dwordx4 v[52:55], v160, s[28:29] offset:832
	global_load_dwordx4 v[56:59], v160, s[28:29] offset:896
	global_load_dwordx4 v[60:63], v160, s[28:29] offset:960
	global_load_dwordx4 v[64:67], v160, s[28:29] offset:1024
	global_load_dwordx4 v[68:71], v160, s[28:29] offset:1088
	global_load_dwordx4 v[72:75], v160, s[28:29] offset:1152
	global_load_dwordx4 v[76:79], v160, s[28:29] offset:1216
	global_load_dwordx4 v[80:83], v160, s[28:29] offset:1280
	global_load_dwordx4 v[84:87], v160, s[28:29] offset:1344
	global_load_dwordx4 v[88:91], v160, s[28:29] offset:1408
	global_load_dwordx4 v[92:95], v160, s[28:29] offset:1472
	global_load_dwordx4 v[96:99], v160, s[28:29] offset:1536
	global_load_dwordx4 v[100:103], v160, s[28:29] offset:1600
	global_load_dwordx4 v[104:107], v160, s[28:29] offset:1664
	global_load_dwordx4 v[108:111], v160, s[28:29] offset:1728
	global_load_dwordx4 v[112:115], v160, s[28:29] offset:1792
	global_load_dwordx4 v[116:119], v160, s[28:29] offset:1856
	global_load_dwordx4 v[120:123], v160, s[28:29] offset:1920
	global_load_dwordx4 v[124:127], v160, s[28:29] offset:1984
	global_load_dwordx4 v[182:185], v168, s[42:43]
	s_mov_b64 s[24:25], s[8:9]
	global_load_dwordx2 v[232:233], v165, s[24:25]
	s_add_u32 s24, s24, 0x1000
	s_addc_u32 s25, s25, 0
	global_load_dwordx2 v[234:235], v165, s[24:25]
	s_add_u32 s24, s24, 0x1000
	s_addc_u32 s25, s25, 0
	global_load_dwordx2 v[236:237], v165, s[24:25]
	s_add_u32 s24, s24, 0x1000
	s_addc_u32 s25, s25, 0
	global_load_dwordx2 v[238:239], v165, s[24:25]
	s_add_u32 s24, s24, 0x1000
	s_addc_u32 s25, s25, 0
	global_load_dwordx2 v[240:241], v165, s[24:25]
	s_add_u32 s24, s24, 0x1000
	s_addc_u32 s25, s25, 0
	global_load_dwordx2 v[242:243], v165, s[24:25]
	s_add_u32 s24, s24, 0x1000
	s_addc_u32 s25, s25, 0
	global_load_dwordx2 v[244:245], v165, s[24:25]
	s_add_u32 s24, s24, 0x1000
	s_addc_u32 s25, s25, 0
	global_load_dwordx2 v[246:247], v165, s[24:25]
	s_add_u32 s24, s24, 0x1000
	s_addc_u32 s25, s25, 0
	global_load_dwordx2 v[248:249], v165, s[24:25]
	s_add_u32 s24, s24, 0x1000
	s_addc_u32 s25, s25, 0
	global_load_dwordx2 v[250:251], v165, s[24:25]
	s_add_u32 s24, s24, 0x1000
	s_addc_u32 s25, s25, 0
	global_load_dwordx2 v[252:253], v165, s[24:25]
	s_add_u32 s24, s24, 0x1000
	s_addc_u32 s25, s25, 0
	global_load_dwordx2 v[254:255], v165, s[24:25]
	s_add_u32 s24, s24, 0x1000
	s_addc_u32 s25, s25, 0
	global_load_dwordx2 v[220:221], v165, s[24:25]
	s_add_u32 s24, s24, 0x1000
	s_addc_u32 s25, s25, 0
	global_load_dwordx2 v[222:223], v165, s[24:25]
	s_add_u32 s24, s24, 0x1000
	s_addc_u32 s25, s25, 0
	global_load_dwordx2 v[224:225], v165, s[24:25]
	s_add_u32 s24, s24, 0x1000
	s_addc_u32 s25, s25, 0
	global_load_dwordx2 v[226:227], v165, s[24:25]
	global_load_dwordx2 v[198:199], v165, s[10:11]
	s_waitcnt vmcnt(50)
; #define LAS __attribute__((address_space(3)))
; DI void phase_gla_prep(const Params& p, LAS unsigned char* lds) {
;     ...
;             for (int i = 0; i < 8; ++i) { const int c = tid + i * 512; *(LAS u32x4*)(wl + (c >> 8) * 2056 + (c & 255) * 8) = *(const u32x4*)(wsrc + (size_t)c * 8); }
;             __syncthreads();
;             const int w = tid >> 6, lane = tid & 63, i16 = lane & 15, quad = lane >> 4, mt = w & 3, kh = w >> 2;
;             const bf16_t* xr = (const bf16_t*)(p.ws + XG) + (tokb + 16 * mt + i16) * DM + kh * 1024 + 8 * quad;
;             f32x4 acc = {0.f, 0.f, 0.f, 0.f};
; #pragma unroll 8
;             for (int ks = 0; ks < 32; ++ks) {
;                 const bf16x8 a = *(const bf16x8*)(xr + 32 * ks);
;                 const bf16x8 bb = *(LAS const bf16x8*)(wl + i16 * 2056 + kh * 1024 + 32 * ks + 8 * quad);
;                 acc = __builtin_amdgcn_mfma_f32_16x16x32_bf16(a, bb, acc, 0, 0, 0);
;             }
	ds_write_b128 v162, v[128:131] offset:0
	ds_write_b128 v162, v[132:135] offset:8224
	ds_write_b128 v162, v[136:139] offset:16448
	ds_write_b128 v162, v[140:143] offset:24672
	ds_write_b128 v162, v[144:147] offset:32896
	ds_write_b128 v162, v[148:151] offset:41120
	ds_write_b128 v162, v[152:155] offset:49344
	ds_write_b128 v162, v[156:159] offset:57568
	v_mov_b32_e32 v216, 0
	v_mov_b32_e32 v217, 0
	v_mov_b32_e32 v218, 0
	v_mov_b32_e32 v219, 0
	s_waitcnt lgkmcnt(0)
	s_barrier
	ds_read_b128 v[200:203], v163 offset:0
	ds_read_b128 v[204:207], v163 offset:64
	ds_read_b128 v[208:211], v163 offset:128
	ds_read_b128 v[212:215], v163 offset:192
	s_waitcnt vmcnt(49) lgkmcnt(3)
	v_mfma_f32_16x16x32_bf16 v[216:219], v[0:3], v[200:203], v[216:219]
	s_waitcnt vmcnt(48) lgkmcnt(2)
	v_mfma_f32_16x16x32_bf16 v[216:219], v[4:7], v[204:207], v[216:219]
	s_waitcnt vmcnt(47) lgkmcnt(1)
	v_mfma_f32_16x16x32_bf16 v[216:219], v[8:11], v[208:211], v[216:219]
	s_waitcnt vmcnt(46) lgkmcnt(0)
	v_mfma_f32_16x16x32_bf16 v[216:219], v[12:15], v[212:215], v[216:219]
	s_nop 3
	ds_read_b128 v[200:203], v163 offset:256
	ds_read_b128 v[204:207], v163 offset:320
	ds_read_b128 v[208:211], v163 offset:384
	ds_read_b128 v[212:215], v163 offset:448
	s_waitcnt vmcnt(45) lgkmcnt(3)
	v_mfma_f32_16x16x32_bf16 v[216:219], v[16:19], v[200:203], v[216:219]
	s_waitcnt vmcnt(44) lgkmcnt(2)
	v_mfma_f32_16x16x32_bf16 v[216:219], v[20:23], v[204:207], v[216:219]
	s_waitcnt vmcnt(43) lgkmcnt(1)
	v_mfma_f32_16x16x32_bf16 v[216:219], v[24:27], v[208:211], v[216:219]
	s_waitcnt vmcnt(42) lgkmcnt(0)
	v_mfma_f32_16x16x32_bf16 v[216:219], v[28:31], v[212:215], v[216:219]
	s_nop 3
	ds_read_b128 v[200:203], v163 offset:512
	ds_read_b128 v[204:207], v163 offset:576
	ds_read_b128 v[208:211], v163 offset:640
	ds_read_b128 v[212:215], v163 offset:704
	s_waitcnt vmcnt(41) lgkmcnt(3)
	v_mfma_f32_16x16x32_bf16 v[216:219], v[32:35], v[200:203], v[216:219]
	s_waitcnt vmcnt(40) lgkmcnt(2)
	v_mfma_f32_16x16x32_bf16 v[216:219], v[36:39], v[204:207], v[216:219]
	s_waitcnt vmcnt(39) lgkmcnt(1)
	v_mfma_f32_16x16x32_bf16 v[216:219], v[40:43], v[208:211], v[216:219]
	s_waitcnt vmcnt(38) lgkmcnt(0)
	v_mfma_f32_16x16x32_bf16 v[216:219], v[44:47], v[212:215], v[216:219]
	s_nop 3
	ds_read_b128 v[200:203], v163 offset:768
	ds_read_b128 v[204:207], v163 offset:832
	ds_read_b128 v[208:211], v163 offset:896
	ds_read_b128 v[212:215], v163 offset:960
	s_waitcnt vmcnt(37) lgkmcnt(3)
	v_mfma_f32_16x16x32_bf16 v[216:219], v[48:51], v[200:203], v[216:219]
	s_waitcnt vmcnt(36) lgkmcnt(2)
	v_mfma_f32_16x16x32_bf16 v[216:219], v[52:55], v[204:207], v[216:219]
	s_waitcnt vmcnt(35) lgkmcnt(1)
	v_mfma_f32_16x16x32_bf16 v[216:219], v[56:59], v[208:211], v[216:219]
	s_waitcnt vmcnt(34) lgkmcnt(0)
	v_mfma_f32_16x16x32_bf16 v[216:219], v[60:63], v[212:215], v[216:219]
	s_nop 3
	ds_read_b128 v[200:203], v163 offset:1024
	ds_read_b128 v[204:207], v163 offset:1088
	ds_read_b128 v[208:211], v163 offset:1152
	ds_read_b128 v[212:215], v163 offset:1216
	s_waitcnt vmcnt(33) lgkmcnt(3)
	v_mfma_f32_16x16x32_bf16 v[216:219], v[64:67], v[200:203], v[216:219]
	s_waitcnt vmcnt(32) lgkmcnt(2)
	v_mfma_f32_16x16x32_bf16 v[216:219], v[68:71], v[204:207], v[216:219]
	s_waitcnt vmcnt(31) lgkmcnt(1)
	v_mfma_f32_16x16x32_bf16 v[216:219], v[72:75], v[208:211], v[216:219]
	s_waitcnt vmcnt(30) lgkmcnt(0)
	v_mfma_f32_16x16x32_bf16 v[216:219], v[76:79], v[212:215], v[216:219]
	s_nop 3
	ds_read_b128 v[200:203], v163 offset:1280
	ds_read_b128 v[204:207], v163 offset:1344
	ds_read_b128 v[208:211], v163 offset:1408
	ds_read_b128 v[212:215], v163 offset:1472
	s_waitcnt vmcnt(29) lgkmcnt(3)
	v_mfma_f32_16x16x32_bf16 v[216:219], v[80:83], v[200:203], v[216:219]
	s_waitcnt vmcnt(28) lgkmcnt(2)
	v_mfma_f32_16x16x32_bf16 v[216:219], v[84:87], v[204:207], v[216:219]
	s_waitcnt vmcnt(27) lgkmcnt(1)
	v_mfma_f32_16x16x32_bf16 v[216:219], v[88:91], v[208:211], v[216:219]
	s_waitcnt vmcnt(26) lgkmcnt(0)
	v_mfma_f32_16x16x32_bf16 v[216:219], v[92:95], v[212:215], v[216:219]
	s_nop 3
	ds_read_b128 v[200:203], v163 offset:1536
	ds_read_b128 v[204:207], v163 offset:1600
	ds_read_b128 v[208:211], v163 offset:1664
	ds_read_b128 v[212:215], v163 offset:1728
	s_waitcnt vmcnt(25) lgkmcnt(3)
	v_mfma_f32_16x16x32_bf16 v[216:219], v[96:99], v[200:203], v[216:219]
	s_waitcnt vmcnt(24) lgkmcnt(2)
	v_mfma_f32_16x16x32_bf16 v[216:219], v[100:103], v[204:207], v[216:219]
	s_waitcnt vmcnt(23) lgkmcnt(1)
	v_mfma_f32_16x16x32_bf16 v[216:219], v[104:107], v[208:211], v[216:219]
	s_waitcnt vmcnt(22) lgkmcnt(0)
	v_mfma_f32_16x16x32_bf16 v[216:219], v[108:111], v[212:215], v[216:219]
	s_nop 3
	ds_read_b128 v[200:203], v163 offset:1792
	ds_read_b128 v[204:207], v163 offset:1856
	ds_read_b128 v[208:211], v163 offset:1920
	ds_read_b128 v[212:215], v163 offset:1984
	s_waitcnt vmcnt(21) lgkmcnt(3)
	v_mfma_f32_16x16x32_bf16 v[216:219], v[112:115], v[200:203], v[216:219]
	s_waitcnt vmcnt(20) lgkmcnt(2)
	v_mfma_f32_16x16x32_bf16 v[216:219], v[116:119], v[204:207], v[216:219]
	s_waitcnt vmcnt(19) lgkmcnt(1)
	v_mfma_f32_16x16x32_bf16 v[216:219], v[120:123], v[208:211], v[216:219]
	s_waitcnt vmcnt(18) lgkmcnt(0)
	v_mfma_f32_16x16x32_bf16 v[216:219], v[124:127], v[212:215], v[216:219]
	s_nop 3
	s_waitcnt vmcnt(0)
; DI unsigned pk2(float a, float b) { f32x2 v = {a, b}; bf16v2_t r = __builtin_convertvector(v, bf16v2_t); return __builtin_bit_cast(unsigned, r); }
; DI void phase_gla_prep(const Params& p, LAS unsigned char* lds) {
;     ...
;             if (kh == 1) {
; #pragma unroll
;                 for (int j = 0; j < 4; ++j) part[(16 * mt + 4 * quad + j) * 16 + i16] = acc[j]; }
;             __syncthreads();
;             if (kh == 0) {
; #pragma unroll
;                 for (int j = 0; j < 4; ++j) { const int tok = 16 * mt + 4 * quad + j;
;                     const float rs = rsqrtf(((const float*)(p.ws + X_SSQ))[tokb + tok] * (1.f / DM) + EPS);
;                     lrs[tok * 16 + i16] = (acc[j] + part[tok * 16 + i16]) * rs; } }
;         }
;         __syncthreads();
;         float t0 = 0.f, t1 = 0.f;
;     ...
;             unsigned kw[16];
; #pragma unroll
;             for (int i = 0; i < 16; ++i) kw[i] = *(const unsigned*)(big + (tokb + tg * 16 + i) * 6400 + 1024 + ch0);
; #pragma unroll
;             for (int i = 15; i >= 0; --i) { const int tok = tg * 16 + i;
;                 float z0 = bs0, z1 = bs1;
; #pragma unroll
;                 for (int r = 0; r < 16; ++r) { const float lv = lrs[tok * 16 + r]; z0 += lv * wg0[r]; z1 += lv * wg1[r]; }
;                 *(unsigned*)(big + (tokb + tok) * 6400 + 1024 + ch0) = pk2(__uint_as_float(kw[i] << 16) * __expf(t0), __uint_as_float(kw[i] & 0xffff0000u) * __expf(t1));
	global_load_dword v0, v166, s[30:31]
	s_sub_u32 s30, s30, 0x3200
	s_subb_u32 s31, s31, 0
	global_load_dword v1, v166, s[30:31]
	s_sub_u32 s30, s30, 0x3200
	s_subb_u32 s31, s31, 0
	global_load_dword v2, v166, s[30:31]
	s_sub_u32 s30, s30, 0x3200
	s_subb_u32 s31, s31, 0
	global_load_dword v3, v166, s[30:31]
	s_sub_u32 s30, s30, 0x3200
	s_subb_u32 s31, s31, 0
	global_load_dword v4, v166, s[30:31]
	s_sub_u32 s30, s30, 0x3200
	s_subb_u32 s31, s31, 0
	global_load_dword v5, v166, s[30:31]
	s_sub_u32 s30, s30, 0x3200
	s_subb_u32 s31, s31, 0
	global_load_dword v6, v166, s[30:31]
	s_sub_u32 s30, s30, 0x3200
	s_subb_u32 s31, s31, 0
	global_load_dword v7, v166, s[30:31]
	s_sub_u32 s30, s30, 0x3200
	s_subb_u32 s31, s31, 0
	global_load_dword v8, v166, s[30:31]
	s_sub_u32 s30, s30, 0x3200
	s_subb_u32 s31, s31, 0
	global_load_dword v9, v166, s[30:31]
	s_sub_u32 s30, s30, 0x3200
	s_subb_u32 s31, s31, 0
	global_load_dword v10, v166, s[30:31]
	s_sub_u32 s30, s30, 0x3200
	s_subb_u32 s31, s31, 0
	global_load_dword v11, v166, s[30:31]
	s_sub_u32 s30, s30, 0x3200
	s_subb_u32 s31, s31, 0
	global_load_dword v12, v166, s[30:31]
	s_sub_u32 s30, s30, 0x3200
	s_subb_u32 s31, s31, 0
	global_load_dword v13, v166, s[30:31]
	s_sub_u32 s30, s30, 0x3200
	s_subb_u32 s31, s31, 0
	global_load_dword v14, v166, s[30:31]
	s_sub_u32 s30, s30, 0x3200
	s_subb_u32 s31, s31, 0
	global_load_dword v15, v166, s[30:31]
	s_sub_u32 s30, s30, 0x3200
	s_subb_u32 s31, s31, 0
	global_load_dword v16, v166, s[30:31]
	s_sub_u32 s30, s30, 0x3200
	s_subb_u32 s31, s31, 0
	global_load_dword v17, v166, s[30:31]
	s_sub_u32 s30, s30, 0x3200
	s_subb_u32 s31, s31, 0
	global_load_dword v18, v166, s[30:31]
	s_sub_u32 s30, s30, 0x3200
	s_subb_u32 s31, s31, 0
	global_load_dword v19, v166, s[30:31]
	s_sub_u32 s30, s30, 0x3200
	s_subb_u32 s31, s31, 0
	global_load_dword v20, v166, s[30:31]
	s_sub_u32 s30, s30, 0x3200
	s_subb_u32 s31, s31, 0
	global_load_dword v21, v166, s[30:31]
	s_sub_u32 s30, s30, 0x3200
	s_subb_u32 s31, s31, 0
	global_load_dword v22, v166, s[30:31]
	s_sub_u32 s30, s30, 0x3200
	s_subb_u32 s31, s31, 0
	global_load_dword v23, v166, s[30:31]
	s_sub_u32 s30, s30, 0x3200
	s_subb_u32 s31, s31, 0
	global_load_dword v24, v166, s[30:31]
	s_sub_u32 s30, s30, 0x3200
	s_subb_u32 s31, s31, 0
	global_load_dword v25, v166, s[30:31]
	s_sub_u32 s30, s30, 0x3200
	s_subb_u32 s31, s31, 0
	global_load_dword v26, v166, s[30:31]
	s_sub_u32 s30, s30, 0x3200
	s_subb_u32 s31, s31, 0
	global_load_dword v27, v166, s[30:31]
	s_sub_u32 s30, s30, 0x3200
	s_subb_u32 s31, s31, 0
	global_load_dword v28, v166, s[30:31]
	s_sub_u32 s30, s30, 0x3200
	s_subb_u32 s31, s31, 0
	global_load_dword v29, v166, s[30:31]
	s_sub_u32 s30, s30, 0x3200
	s_subb_u32 s31, s31, 0
	global_load_dword v30, v166, s[30:31]
	s_sub_u32 s30, s30, 0x3200
	s_subb_u32 s31, s31, 0
	global_load_dword v31, v166, s[30:31]
	s_sub_u32 s30, s30, 0x3200
	s_subb_u32 s31, s31, 0
	s_nop 7
	s_nop 7
	s_cmp_eq_u32 s40, 0
	s_cbranch_scc1 .Lgp_k0a
	ds_write_b32 v164, v216 offset:4096
	ds_write_b32 v164, v217 offset:4160
	ds_write_b32 v164, v218 offset:4224
	ds_write_b32 v164, v219 offset:4288
.Lgp_k0a:
	s_waitcnt lgkmcnt(0)
	s_barrier
	s_cmp_eq_u32 s40, 0
	s_cbranch_scc0 .Lgp_k1b
	ds_read_b32 v110, v164 offset:4096
	ds_read_b32 v111, v164 offset:4160
	ds_read_b32 v112, v164 offset:4224
	ds_read_b32 v113, v164 offset:4288
	v_mov_b32_e32 v114, 0x358637bd
	v_fma_f32 v182, v182, s38, v114
	v_fma_f32 v183, v183, s38, v114
	v_fma_f32 v184, v184, s38, v114
	v_fma_f32 v185, v185, s38, v114
	v_rsq_f32_e32 v182, v182
	v_rsq_f32_e32 v183, v183
	v_rsq_f32_e32 v184, v184
	v_rsq_f32_e32 v185, v185
	s_waitcnt lgkmcnt(0)
	v_add_f32_e32 v110, v216, v110
	v_add_f32_e32 v111, v217, v111
	v_add_f32_e32 v112, v218, v112
	v_add_f32_e32 v113, v219, v113
	v_mul_f32_e32 v110, v110, v182
	v_mul_f32_e32 v111, v111, v183
	v_mul_f32_e32 v112, v112, v184
	v_mul_f32_e32 v113, v113, v185
	ds_write_b32 v164, v110 offset:0
	ds_write_b32 v164, v111 offset:64
	ds_write_b32 v164, v112 offset:128
	ds_write_b32 v164, v113 offset:192
.Lgp_k1b:
	s_waitcnt lgkmcnt(0)
	s_barrier
	v_mov_b32_e32 v192, 0
	v_mov_b32_e32 v193, 0
	ds_read_b128 v[64:67], v167 offset:4032
	ds_read_b128 v[68:71], v167 offset:4048
	ds_read_b128 v[72:75], v167 offset:4064
	ds_read_b128 v[76:79], v167 offset:4080
	ds_read_b128 v[80:83], v167 offset:3968
	ds_read_b128 v[84:87], v167 offset:3984
	ds_read_b128 v[88:91], v167 offset:4000
	ds_read_b128 v[92:95], v167 offset:4016
	v_pk_mul_f32 v[98:99], v[192:193], v[186:187]
	s_waitcnt vmcnt(31)
	v_lshlrev_b32_e32 v100, 16, v0
	v_exp_f32_e32 v98, v98
	v_exp_f32_e32 v99, v99
	v_and_b32_e32 v101, 0xffff0000, v0
	v_mov_b32_e32 v96, v198
	v_mov_b32_e32 v97, v199
	v_pk_mul_f32 v[102:103], v[100:101], v[98:99]
	s_waitcnt lgkmcnt(4)
; DI unsigned pk2(float a, float b) { f32x2 v = {a, b}; bf16v2_t r = __builtin_convertvector(v, bf16v2_t); return __builtin_bit_cast(unsigned, r); }
; DI void phase_gla_prep(const Params& p, LAS unsigned char* lds) {
;     ...
;             for (int i = 0; i < 16; ++i) kw[i] = *(const unsigned*)(big + (tokb + tg * 16 + i) * 6400 + 1024 + ch0);
; #pragma unroll
;             for (int i = 15; i >= 0; --i) { const int tok = tg * 16 + i;
;                 float z0 = bs0, z1 = bs1;
; #pragma unroll
;                 for (int r = 0; r < 16; ++r) { const float lv = lrs[tok * 16 + r]; z0 += lv * wg0[r]; z1 += lv * wg1[r]; }
;                 *(unsigned*)(big + (tokb + tok) * 6400 + 1024 + ch0) = pk2(__uint_as_float(kw[i] << 16) * __expf(t0), __uint_as_float(kw[i] & 0xffff0000u) * __expf(t1));
;                 t0 += (fminf(z0, 0.f) - __logf(1.f + __expf(-fabsf(z0)))) * (1.f / 16.f); t1 += (fminf(z1, 0.f) - __logf(1.f + __expf(-fabsf(z1)))) * (1.f / 16.f);
;             }
	v_pk_fma_f32 v[96:97], v[64:65], v[232:233], v[96:97] op_sel_hi:[0,1,1]
	v_cvt_pk_bf16_f32 v108, v102, v103
	v_pk_fma_f32 v[96:97], v[64:65], v[234:235], v[96:97] op_sel:[1,0,0] op_sel_hi:[1,1,1]
	global_store_dword v166, v108, s[46:47]
	s_sub_u32 s46, s46, 0x3200
	s_subb_u32 s47, s47, 0
	global_load_dword v32, v166, s[30:31]
	s_sub_u32 s30, s30, 0x3200
	s_subb_u32 s31, s31, 0
	v_pk_fma_f32 v[96:97], v[66:67], v[236:237], v[96:97] op_sel_hi:[0,1,1]
	v_pk_fma_f32 v[96:97], v[66:67], v[238:239], v[96:97] op_sel:[1,0,0] op_sel_hi:[1,1,1]
	v_pk_fma_f32 v[96:97], v[68:69], v[240:241], v[96:97] op_sel_hi:[0,1,1]
	v_pk_fma_f32 v[96:97], v[68:69], v[242:243], v[96:97] op_sel:[1,0,0] op_sel_hi:[1,1,1]
	v_pk_fma_f32 v[96:97], v[70:71], v[244:245], v[96:97] op_sel_hi:[0,1,1]
	v_pk_fma_f32 v[96:97], v[70:71], v[246:247], v[96:97] op_sel:[1,0,0] op_sel_hi:[1,1,1]
	v_pk_fma_f32 v[96:97], v[72:73], v[248:249], v[96:97] op_sel_hi:[0,1,1]
	v_pk_fma_f32 v[96:97], v[72:73], v[250:251], v[96:97] op_sel:[1,0,0] op_sel_hi:[1,1,1]
	v_pk_fma_f32 v[96:97], v[74:75], v[252:253], v[96:97] op_sel_hi:[0,1,1]
	v_pk_fma_f32 v[96:97], v[74:75], v[254:255], v[96:97] op_sel:[1,0,0] op_sel_hi:[1,1,1]
	v_pk_fma_f32 v[96:97], v[76:77], v[220:221], v[96:97] op_sel_hi:[0,1,1]
	v_pk_fma_f32 v[96:97], v[76:77], v[222:223], v[96:97] op_sel:[1,0,0] op_sel_hi:[1,1,1]
	v_pk_fma_f32 v[96:97], v[78:79], v[224:225], v[96:97] op_sel_hi:[0,1,1]
	v_pk_fma_f32 v[96:97], v[78:79], v[226:227], v[96:97] op_sel:[1,0,0] op_sel_hi:[1,1,1]
	v_mul_f32_e64 v104, |v96|, s34
	v_mul_f32_e64 v105, |v97|, s34
	v_exp_f32_e32 v104, v104
	v_exp_f32_e32 v105, v105
	v_min_f32_e32 v106, 0, v96
	v_min_f32_e32 v107, 0, v97
	v_pk_add_f32 v[104:105], v[104:105], v[190:191]
	v_log_f32_e32 v104, v104
	v_log_f32_e32 v105, v105
	s_nop 0
	v_fma_f32 v106, v104, s35, v106
	v_fma_f32 v107, v105, s35, v107
	v_pk_fma_f32 v[192:193], v[106:107], v[188:189], v[192:193]
	ds_read_b128 v[64:67], v167 offset:3904
	ds_read_b128 v[68:71], v167 offset:3920
	ds_read_b128 v[72:75], v167 offset:3936
	ds_read_b128 v[76:79], v167 offset:3952
	v_pk_mul_f32 v[98:99], v[192:193], v[186:187]
	s_waitcnt vmcnt(32)
	v_lshlrev_b32_e32 v100, 16, v1
	v_exp_f32_e32 v98, v98
	v_exp_f32_e32 v99, v99
	v_and_b32_e32 v101, 0xffff0000, v1
	v_mov_b32_e32 v96, v198
	v_mov_b32_e32 v97, v199
	v_pk_mul_f32 v[102:103], v[100:101], v[98:99]
	s_waitcnt lgkmcnt(4)
	v_pk_fma_f32 v[96:97], v[80:81], v[232:233], v[96:97] op_sel_hi:[0,1,1]
	v_cvt_pk_bf16_f32 v108, v102, v103
	v_pk_fma_f32 v[96:97], v[80:81], v[234:235], v[96:97] op_sel:[1,0,0] op_sel_hi:[1,1,1]
	global_store_dword v166, v108, s[46:47]
	s_sub_u32 s46, s46, 0x3200
	s_subb_u32 s47, s47, 0
	global_load_dword v33, v166, s[30:31]
	s_sub_u32 s30, s30, 0x3200
	s_subb_u32 s31, s31, 0
	v_pk_fma_f32 v[96:97], v[82:83], v[236:237], v[96:97] op_sel_hi:[0,1,1]
	v_pk_fma_f32 v[96:97], v[82:83], v[238:239], v[96:97] op_sel:[1,0,0] op_sel_hi:[1,1,1]
	v_pk_fma_f32 v[96:97], v[84:85], v[240:241], v[96:97] op_sel_hi:[0,1,1]
	v_pk_fma_f32 v[96:97], v[84:85], v[242:243], v[96:97] op_sel:[1,0,0] op_sel_hi:[1,1,1]
	v_pk_fma_f32 v[96:97], v[86:87], v[244:245], v[96:97] op_sel_hi:[0,1,1]
	v_pk_fma_f32 v[96:97], v[86:87], v[246:247], v[96:97] op_sel:[1,0,0] op_sel_hi:[1,1,1]
	v_pk_fma_f32 v[96:97], v[88:89], v[248:249], v[96:97] op_sel_hi:[0,1,1]
	v_pk_fma_f32 v[96:97], v[88:89], v[250:251], v[96:97] op_sel:[1,0,0] op_sel_hi:[1,1,1]
	v_pk_fma_f32 v[96:97], v[90:91], v[252:253], v[96:97] op_sel_hi:[0,1,1]
	v_pk_fma_f32 v[96:97], v[90:91], v[254:255], v[96:97] op_sel:[1,0,0] op_sel_hi:[1,1,1]
	v_pk_fma_f32 v[96:97], v[92:93], v[220:221], v[96:97] op_sel_hi:[0,1,1]
	v_pk_fma_f32 v[96:97], v[92:93], v[222:223], v[96:97] op_sel:[1,0,0] op_sel_hi:[1,1,1]
	v_pk_fma_f32 v[96:97], v[94:95], v[224:225], v[96:97] op_sel_hi:[0,1,1]
	v_pk_fma_f32 v[96:97], v[94:95], v[226:227], v[96:97] op_sel:[1,0,0] op_sel_hi:[1,1,1]
	v_mul_f32_e64 v104, |v96|, s34
	v_mul_f32_e64 v105, |v97|, s34
	v_exp_f32_e32 v104, v104
	v_exp_f32_e32 v105, v105
	v_min_f32_e32 v106, 0, v96
	v_min_f32_e32 v107, 0, v97
	v_pk_add_f32 v[104:105], v[104:105], v[190:191]
	v_log_f32_e32 v104, v104
	v_log_f32_e32 v105, v105
	s_nop 0
	v_fma_f32 v106, v104, s35, v106
	v_fma_f32 v107, v105, s35, v107
	v_pk_fma_f32 v[192:193], v[106:107], v[188:189], v[192:193]
	ds_read_b128 v[80:83], v167 offset:3840
	ds_read_b128 v[84:87], v167 offset:3856
	ds_read_b128 v[88:91], v167 offset:3872
	ds_read_b128 v[92:95], v167 offset:3888
	v_pk_mul_f32 v[98:99], v[192:193], v[186:187]
	s_waitcnt vmcnt(33)
	v_lshlrev_b32_e32 v100, 16, v2
	v_exp_f32_e32 v98, v98
	v_exp_f32_e32 v99, v99
	v_and_b32_e32 v101, 0xffff0000, v2
	v_mov_b32_e32 v96, v198
	v_mov_b32_e32 v97, v199
	v_pk_mul_f32 v[102:103], v[100:101], v[98:99]
	s_waitcnt lgkmcnt(4)
; DI unsigned pk2(float a, float b) { f32x2 v = {a, b}; bf16v2_t r = __builtin_convertvector(v, bf16v2_t); return __builtin_bit_cast(unsigned, r); }
; DI void phase_gla_prep(const Params& p, LAS unsigned char* lds) {
;     ...
;             for (int i = 0; i < 16; ++i) kw[i] = *(const unsigned*)(big + (tokb + tg * 16 + i) * 6400 + 1024 + ch0);
; #pragma unroll
;             for (int i = 15; i >= 0; --i) { const int tok = tg * 16 + i;
;                 float z0 = bs0, z1 = bs1;
; #pragma unroll
;                 for (int r = 0; r < 16; ++r) { const float lv = lrs[tok * 16 + r]; z0 += lv * wg0[r]; z1 += lv * wg1[r]; }
;                 *(unsigned*)(big + (tokb + tok) * 6400 + 1024 + ch0) = pk2(__uint_as_float(kw[i] << 16) * __expf(t0), __uint_as_float(kw[i] & 0xffff0000u) * __expf(t1));
;                 t0 += (fminf(z0, 0.f) - __logf(1.f + __expf(-fabsf(z0)))) * (1.f / 16.f); t1 += (fminf(z1, 0.f) - __logf(1.f + __expf(-fabsf(z1)))) * (1.f / 16.f);
;             }
	v_pk_fma_f32 v[96:97], v[64:65], v[232:233], v[96:97] op_sel_hi:[0,1,1]
	v_cvt_pk_bf16_f32 v108, v102, v103
	v_pk_fma_f32 v[96:97], v[64:65], v[234:235], v[96:97] op_sel:[1,0,0] op_sel_hi:[1,1,1]
	global_store_dword v166, v108, s[46:47]
	s_sub_u32 s46, s46, 0x3200
	s_subb_u32 s47, s47, 0
	global_load_dword v34, v166, s[30:31]
	s_sub_u32 s30, s30, 0x3200
	s_subb_u32 s31, s31, 0
	v_pk_fma_f32 v[96:97], v[66:67], v[236:237], v[96:97] op_sel_hi:[0,1,1]
	v_pk_fma_f32 v[96:97], v[66:67], v[238:239], v[96:97] op_sel:[1,0,0] op_sel_hi:[1,1,1]
	v_pk_fma_f32 v[96:97], v[68:69], v[240:241], v[96:97] op_sel_hi:[0,1,1]
	v_pk_fma_f32 v[96:97], v[68:69], v[242:243], v[96:97] op_sel:[1,0,0] op_sel_hi:[1,1,1]
	v_pk_fma_f32 v[96:97], v[70:71], v[244:245], v[96:97] op_sel_hi:[0,1,1]
	v_pk_fma_f32 v[96:97], v[70:71], v[246:247], v[96:97] op_sel:[1,0,0] op_sel_hi:[1,1,1]
	v_pk_fma_f32 v[96:97], v[72:73], v[248:249], v[96:97] op_sel_hi:[0,1,1]
	v_pk_fma_f32 v[96:97], v[72:73], v[250:251], v[96:97] op_sel:[1,0,0] op_sel_hi:[1,1,1]
	v_pk_fma_f32 v[96:97], v[74:75], v[252:253], v[96:97] op_sel_hi:[0,1,1]
	v_pk_fma_f32 v[96:97], v[74:75], v[254:255], v[96:97] op_sel:[1,0,0] op_sel_hi:[1,1,1]
	v_pk_fma_f32 v[96:97], v[76:77], v[220:221], v[96:97] op_sel_hi:[0,1,1]
	v_pk_fma_f32 v[96:97], v[76:77], v[222:223], v[96:97] op_sel:[1,0,0] op_sel_hi:[1,1,1]
	v_pk_fma_f32 v[96:97], v[78:79], v[224:225], v[96:97] op_sel_hi:[0,1,1]
	v_pk_fma_f32 v[96:97], v[78:79], v[226:227], v[96:97] op_sel:[1,0,0] op_sel_hi:[1,1,1]
	v_mul_f32_e64 v104, |v96|, s34
	v_mul_f32_e64 v105, |v97|, s34
	v_exp_f32_e32 v104, v104
	v_exp_f32_e32 v105, v105
	v_min_f32_e32 v106, 0, v96
	v_min_f32_e32 v107, 0, v97
	v_pk_add_f32 v[104:105], v[104:105], v[190:191]
	v_log_f32_e32 v104, v104
	v_log_f32_e32 v105, v105
	s_nop 0
	v_fma_f32 v106, v104, s35, v106
	v_fma_f32 v107, v105, s35, v107
	v_pk_fma_f32 v[192:193], v[106:107], v[188:189], v[192:193]
	ds_read_b128 v[64:67], v167 offset:3776
	ds_read_b128 v[68:71], v167 offset:3792
	ds_read_b128 v[72:75], v167 offset:3808
	ds_read_b128 v[76:79], v167 offset:3824
	v_pk_mul_f32 v[98:99], v[192:193], v[186:187]
	s_waitcnt vmcnt(34)
	v_lshlrev_b32_e32 v100, 16, v3
	v_exp_f32_e32 v98, v98
	v_exp_f32_e32 v99, v99
	v_and_b32_e32 v101, 0xffff0000, v3
	v_mov_b32_e32 v96, v198
	v_mov_b32_e32 v97, v199
	v_pk_mul_f32 v[102:103], v[100:101], v[98:99]
	s_waitcnt lgkmcnt(4)
	v_pk_fma_f32 v[96:97], v[80:81], v[232:233], v[96:97] op_sel_hi:[0,1,1]
	v_cvt_pk_bf16_f32 v108, v102, v103
	v_pk_fma_f32 v[96:97], v[80:81], v[234:235], v[96:97] op_sel:[1,0,0] op_sel_hi:[1,1,1]
	global_store_dword v166, v108, s[46:47]
	s_sub_u32 s46, s46, 0x3200
	s_subb_u32 s47, s47, 0
	global_load_dword v35, v166, s[30:31]
	s_sub_u32 s30, s30, 0x3200
	s_subb_u32 s31, s31, 0
	v_pk_fma_f32 v[96:97], v[82:83], v[236:237], v[96:97] op_sel_hi:[0,1,1]
	v_pk_fma_f32 v[96:97], v[82:83], v[238:239], v[96:97] op_sel:[1,0,0] op_sel_hi:[1,1,1]
	v_pk_fma_f32 v[96:97], v[84:85], v[240:241], v[96:97] op_sel_hi:[0,1,1]
	v_pk_fma_f32 v[96:97], v[84:85], v[242:243], v[96:97] op_sel:[1,0,0] op_sel_hi:[1,1,1]
	v_pk_fma_f32 v[96:97], v[86:87], v[244:245], v[96:97] op_sel_hi:[0,1,1]
	v_pk_fma_f32 v[96:97], v[86:87], v[246:247], v[96:97] op_sel:[1,0,0] op_sel_hi:[1,1,1]
	v_pk_fma_f32 v[96:97], v[88:89], v[248:249], v[96:97] op_sel_hi:[0,1,1]
	v_pk_fma_f32 v[96:97], v[88:89], v[250:251], v[96:97] op_sel:[1,0,0] op_sel_hi:[1,1,1]
	v_pk_fma_f32 v[96:97], v[90:91], v[252:253], v[96:97] op_sel_hi:[0,1,1]
	v_pk_fma_f32 v[96:97], v[90:91], v[254:255], v[96:97] op_sel:[1,0,0] op_sel_hi:[1,1,1]
	v_pk_fma_f32 v[96:97], v[92:93], v[220:221], v[96:97] op_sel_hi:[0,1,1]
	v_pk_fma_f32 v[96:97], v[92:93], v[222:223], v[96:97] op_sel:[1,0,0] op_sel_hi:[1,1,1]
	v_pk_fma_f32 v[96:97], v[94:95], v[224:225], v[96:97] op_sel_hi:[0,1,1]
	v_pk_fma_f32 v[96:97], v[94:95], v[226:227], v[96:97] op_sel:[1,0,0] op_sel_hi:[1,1,1]
	v_mul_f32_e64 v104, |v96|, s34
	v_mul_f32_e64 v105, |v97|, s34
	v_exp_f32_e32 v104, v104
	v_exp_f32_e32 v105, v105
	v_min_f32_e32 v106, 0, v96
	v_min_f32_e32 v107, 0, v97
	v_pk_add_f32 v[104:105], v[104:105], v[190:191]
	v_log_f32_e32 v104, v104
	v_log_f32_e32 v105, v105
	s_nop 0
	v_fma_f32 v106, v104, s35, v106
	v_fma_f32 v107, v105, s35, v107
	v_pk_fma_f32 v[192:193], v[106:107], v[188:189], v[192:193]
	ds_read_b128 v[80:83], v167 offset:3712
	ds_read_b128 v[84:87], v167 offset:3728
	ds_read_b128 v[88:91], v167 offset:3744
	ds_read_b128 v[92:95], v167 offset:3760
	v_pk_mul_f32 v[98:99], v[192:193], v[186:187]
	s_waitcnt vmcnt(35)
	v_lshlrev_b32_e32 v100, 16, v4
	v_exp_f32_e32 v98, v98
	v_exp_f32_e32 v99, v99
	v_and_b32_e32 v101, 0xffff0000, v4
	v_mov_b32_e32 v96, v198
	v_mov_b32_e32 v97, v199
	v_pk_mul_f32 v[102:103], v[100:101], v[98:99]
	s_waitcnt lgkmcnt(4)
; DI unsigned pk2(float a, float b) { f32x2 v = {a, b}; bf16v2_t r = __builtin_convertvector(v, bf16v2_t); return __builtin_bit_cast(unsigned, r); }
; DI void phase_gla_prep(const Params& p, LAS unsigned char* lds) {
;     ...
;             for (int i = 0; i < 16; ++i) kw[i] = *(const unsigned*)(big + (tokb + tg * 16 + i) * 6400 + 1024 + ch0);
; #pragma unroll
;             for (int i = 15; i >= 0; --i) { const int tok = tg * 16 + i;
;                 float z0 = bs0, z1 = bs1;
; #pragma unroll
;                 for (int r = 0; r < 16; ++r) { const float lv = lrs[tok * 16 + r]; z0 += lv * wg0[r]; z1 += lv * wg1[r]; }
;                 *(unsigned*)(big + (tokb + tok) * 6400 + 1024 + ch0) = pk2(__uint_as_float(kw[i] << 16) * __expf(t0), __uint_as_float(kw[i] & 0xffff0000u) * __expf(t1));
;                 t0 += (fminf(z0, 0.f) - __logf(1.f + __expf(-fabsf(z0)))) * (1.f / 16.f); t1 += (fminf(z1, 0.f) - __logf(1.f + __expf(-fabsf(z1)))) * (1.f / 16.f);
;             }
	v_pk_fma_f32 v[96:97], v[64:65], v[232:233], v[96:97] op_sel_hi:[0,1,1]
	v_cvt_pk_bf16_f32 v108, v102, v103
	v_pk_fma_f32 v[96:97], v[64:65], v[234:235], v[96:97] op_sel:[1,0,0] op_sel_hi:[1,1,1]
	global_store_dword v166, v108, s[46:47]
	s_sub_u32 s46, s46, 0x3200
	s_subb_u32 s47, s47, 0
	global_load_dword v36, v166, s[30:31]
	s_sub_u32 s30, s30, 0x3200
	s_subb_u32 s31, s31, 0
	v_pk_fma_f32 v[96:97], v[66:67], v[236:237], v[96:97] op_sel_hi:[0,1,1]
	v_pk_fma_f32 v[96:97], v[66:67], v[238:239], v[96:97] op_sel:[1,0,0] op_sel_hi:[1,1,1]
	v_pk_fma_f32 v[96:97], v[68:69], v[240:241], v[96:97] op_sel_hi:[0,1,1]
	v_pk_fma_f32 v[96:97], v[68:69], v[242:243], v[96:97] op_sel:[1,0,0] op_sel_hi:[1,1,1]
	v_pk_fma_f32 v[96:97], v[70:71], v[244:245], v[96:97] op_sel_hi:[0,1,1]
	v_pk_fma_f32 v[96:97], v[70:71], v[246:247], v[96:97] op_sel:[1,0,0] op_sel_hi:[1,1,1]
	v_pk_fma_f32 v[96:97], v[72:73], v[248:249], v[96:97] op_sel_hi:[0,1,1]
	v_pk_fma_f32 v[96:97], v[72:73], v[250:251], v[96:97] op_sel:[1,0,0] op_sel_hi:[1,1,1]
	v_pk_fma_f32 v[96:97], v[74:75], v[252:253], v[96:97] op_sel_hi:[0,1,1]
	v_pk_fma_f32 v[96:97], v[74:75], v[254:255], v[96:97] op_sel:[1,0,0] op_sel_hi:[1,1,1]
	v_pk_fma_f32 v[96:97], v[76:77], v[220:221], v[96:97] op_sel_hi:[0,1,1]
	v_pk_fma_f32 v[96:97], v[76:77], v[222:223], v[96:97] op_sel:[1,0,0] op_sel_hi:[1,1,1]
	v_pk_fma_f32 v[96:97], v[78:79], v[224:225], v[96:97] op_sel_hi:[0,1,1]
	v_pk_fma_f32 v[96:97], v[78:79], v[226:227], v[96:97] op_sel:[1,0,0] op_sel_hi:[1,1,1]
	v_mul_f32_e64 v104, |v96|, s34
	v_mul_f32_e64 v105, |v97|, s34
	v_exp_f32_e32 v104, v104
	v_exp_f32_e32 v105, v105
	v_min_f32_e32 v106, 0, v96
	v_min_f32_e32 v107, 0, v97
	v_pk_add_f32 v[104:105], v[104:105], v[190:191]
	v_log_f32_e32 v104, v104
	v_log_f32_e32 v105, v105
	s_nop 0
	v_fma_f32 v106, v104, s35, v106
	v_fma_f32 v107, v105, s35, v107
	v_pk_fma_f32 v[192:193], v[106:107], v[188:189], v[192:193]
	ds_read_b128 v[64:67], v167 offset:3648
	ds_read_b128 v[68:71], v167 offset:3664
	ds_read_b128 v[72:75], v167 offset:3680
	ds_read_b128 v[76:79], v167 offset:3696
	v_pk_mul_f32 v[98:99], v[192:193], v[186:187]
	s_waitcnt vmcnt(36)
	v_lshlrev_b32_e32 v100, 16, v5
	v_exp_f32_e32 v98, v98
	v_exp_f32_e32 v99, v99
	v_and_b32_e32 v101, 0xffff0000, v5
	v_mov_b32_e32 v96, v198
	v_mov_b32_e32 v97, v199
	v_pk_mul_f32 v[102:103], v[100:101], v[98:99]
	s_waitcnt lgkmcnt(4)
	v_pk_fma_f32 v[96:97], v[80:81], v[232:233], v[96:97] op_sel_hi:[0,1,1]
	v_cvt_pk_bf16_f32 v108, v102, v103
	v_pk_fma_f32 v[96:97], v[80:81], v[234:235], v[96:97] op_sel:[1,0,0] op_sel_hi:[1,1,1]
	global_store_dword v166, v108, s[46:47]
	s_sub_u32 s46, s46, 0x3200
	s_subb_u32 s47, s47, 0
	global_load_dword v37, v166, s[30:31]
	s_sub_u32 s30, s30, 0x3200
	s_subb_u32 s31, s31, 0
	v_pk_fma_f32 v[96:97], v[82:83], v[236:237], v[96:97] op_sel_hi:[0,1,1]
	v_pk_fma_f32 v[96:97], v[82:83], v[238:239], v[96:97] op_sel:[1,0,0] op_sel_hi:[1,1,1]
	v_pk_fma_f32 v[96:97], v[84:85], v[240:241], v[96:97] op_sel_hi:[0,1,1]
	v_pk_fma_f32 v[96:97], v[84:85], v[242:243], v[96:97] op_sel:[1,0,0] op_sel_hi:[1,1,1]
	v_pk_fma_f32 v[96:97], v[86:87], v[244:245], v[96:97] op_sel_hi:[0,1,1]
	v_pk_fma_f32 v[96:97], v[86:87], v[246:247], v[96:97] op_sel:[1,0,0] op_sel_hi:[1,1,1]
	v_pk_fma_f32 v[96:97], v[88:89], v[248:249], v[96:97] op_sel_hi:[0,1,1]
	v_pk_fma_f32 v[96:97], v[88:89], v[250:251], v[96:97] op_sel:[1,0,0] op_sel_hi:[1,1,1]
	v_pk_fma_f32 v[96:97], v[90:91], v[252:253], v[96:97] op_sel_hi:[0,1,1]
	v_pk_fma_f32 v[96:97], v[90:91], v[254:255], v[96:97] op_sel:[1,0,0] op_sel_hi:[1,1,1]
	v_pk_fma_f32 v[96:97], v[92:93], v[220:221], v[96:97] op_sel_hi:[0,1,1]
	v_pk_fma_f32 v[96:97], v[92:93], v[222:223], v[96:97] op_sel:[1,0,0] op_sel_hi:[1,1,1]
	v_pk_fma_f32 v[96:97], v[94:95], v[224:225], v[96:97] op_sel_hi:[0,1,1]
	v_pk_fma_f32 v[96:97], v[94:95], v[226:227], v[96:97] op_sel:[1,0,0] op_sel_hi:[1,1,1]
	v_mul_f32_e64 v104, |v96|, s34
	v_mul_f32_e64 v105, |v97|, s34
	v_exp_f32_e32 v104, v104
	v_exp_f32_e32 v105, v105
	v_min_f32_e32 v106, 0, v96
	v_min_f32_e32 v107, 0, v97
	v_pk_add_f32 v[104:105], v[104:105], v[190:191]
	v_log_f32_e32 v104, v104
	v_log_f32_e32 v105, v105
	s_nop 0
	v_fma_f32 v106, v104, s35, v106
	v_fma_f32 v107, v105, s35, v107
	v_pk_fma_f32 v[192:193], v[106:107], v[188:189], v[192:193]
	ds_read_b128 v[80:83], v167 offset:3584
	ds_read_b128 v[84:87], v167 offset:3600
	ds_read_b128 v[88:91], v167 offset:3616
	ds_read_b128 v[92:95], v167 offset:3632
	v_pk_mul_f32 v[98:99], v[192:193], v[186:187]
	s_waitcnt vmcnt(37)
	v_lshlrev_b32_e32 v100, 16, v6
	v_exp_f32_e32 v98, v98
	v_exp_f32_e32 v99, v99
	v_and_b32_e32 v101, 0xffff0000, v6
	v_mov_b32_e32 v96, v198
	v_mov_b32_e32 v97, v199
	v_pk_mul_f32 v[102:103], v[100:101], v[98:99]
	s_waitcnt lgkmcnt(4)
; DI unsigned pk2(float a, float b) { f32x2 v = {a, b}; bf16v2_t r = __builtin_convertvector(v, bf16v2_t); return __builtin_bit_cast(unsigned, r); }
; DI void phase_gla_prep(const Params& p, LAS unsigned char* lds) {
;     ...
;             for (int i = 0; i < 16; ++i) kw[i] = *(const unsigned*)(big + (tokb + tg * 16 + i) * 6400 + 1024 + ch0);
; #pragma unroll
;             for (int i = 15; i >= 0; --i) { const int tok = tg * 16 + i;
;                 float z0 = bs0, z1 = bs1;
; #pragma unroll
;                 for (int r = 0; r < 16; ++r) { const float lv = lrs[tok * 16 + r]; z0 += lv * wg0[r]; z1 += lv * wg1[r]; }
;                 *(unsigned*)(big + (tokb + tok) * 6400 + 1024 + ch0) = pk2(__uint_as_float(kw[i] << 16) * __expf(t0), __uint_as_float(kw[i] & 0xffff0000u) * __expf(t1));
;                 t0 += (fminf(z0, 0.f) - __logf(1.f + __expf(-fabsf(z0)))) * (1.f / 16.f); t1 += (fminf(z1, 0.f) - __logf(1.f + __expf(-fabsf(z1)))) * (1.f / 16.f);
;             }
	v_pk_fma_f32 v[96:97], v[64:65], v[232:233], v[96:97] op_sel_hi:[0,1,1]
	v_cvt_pk_bf16_f32 v108, v102, v103
	v_pk_fma_f32 v[96:97], v[64:65], v[234:235], v[96:97] op_sel:[1,0,0] op_sel_hi:[1,1,1]
	global_store_dword v166, v108, s[46:47]
	s_sub_u32 s46, s46, 0x3200
	s_subb_u32 s47, s47, 0
	global_load_dword v38, v166, s[30:31]
	s_sub_u32 s30, s30, 0x3200
	s_subb_u32 s31, s31, 0
	v_pk_fma_f32 v[96:97], v[66:67], v[236:237], v[96:97] op_sel_hi:[0,1,1]
	v_pk_fma_f32 v[96:97], v[66:67], v[238:239], v[96:97] op_sel:[1,0,0] op_sel_hi:[1,1,1]
	v_pk_fma_f32 v[96:97], v[68:69], v[240:241], v[96:97] op_sel_hi:[0,1,1]
	v_pk_fma_f32 v[96:97], v[68:69], v[242:243], v[96:97] op_sel:[1,0,0] op_sel_hi:[1,1,1]
	v_pk_fma_f32 v[96:97], v[70:71], v[244:245], v[96:97] op_sel_hi:[0,1,1]
	v_pk_fma_f32 v[96:97], v[70:71], v[246:247], v[96:97] op_sel:[1,0,0] op_sel_hi:[1,1,1]
	v_pk_fma_f32 v[96:97], v[72:73], v[248:249], v[96:97] op_sel_hi:[0,1,1]
	v_pk_fma_f32 v[96:97], v[72:73], v[250:251], v[96:97] op_sel:[1,0,0] op_sel_hi:[1,1,1]
	v_pk_fma_f32 v[96:97], v[74:75], v[252:253], v[96:97] op_sel_hi:[0,1,1]
	v_pk_fma_f32 v[96:97], v[74:75], v[254:255], v[96:97] op_sel:[1,0,0] op_sel_hi:[1,1,1]
	v_pk_fma_f32 v[96:97], v[76:77], v[220:221], v[96:97] op_sel_hi:[0,1,1]
	v_pk_fma_f32 v[96:97], v[76:77], v[222:223], v[96:97] op_sel:[1,0,0] op_sel_hi:[1,1,1]
	v_pk_fma_f32 v[96:97], v[78:79], v[224:225], v[96:97] op_sel_hi:[0,1,1]
	v_pk_fma_f32 v[96:97], v[78:79], v[226:227], v[96:97] op_sel:[1,0,0] op_sel_hi:[1,1,1]
	v_mul_f32_e64 v104, |v96|, s34
	v_mul_f32_e64 v105, |v97|, s34
	v_exp_f32_e32 v104, v104
	v_exp_f32_e32 v105, v105
	v_min_f32_e32 v106, 0, v96
	v_min_f32_e32 v107, 0, v97
	v_pk_add_f32 v[104:105], v[104:105], v[190:191]
	v_log_f32_e32 v104, v104
	v_log_f32_e32 v105, v105
	s_nop 0
	v_fma_f32 v106, v104, s35, v106
	v_fma_f32 v107, v105, s35, v107
	v_pk_fma_f32 v[192:193], v[106:107], v[188:189], v[192:193]
	ds_read_b128 v[64:67], v167 offset:3520
	ds_read_b128 v[68:71], v167 offset:3536
	ds_read_b128 v[72:75], v167 offset:3552
	ds_read_b128 v[76:79], v167 offset:3568
	v_pk_mul_f32 v[98:99], v[192:193], v[186:187]
	s_waitcnt vmcnt(38)
	v_lshlrev_b32_e32 v100, 16, v7
	v_exp_f32_e32 v98, v98
	v_exp_f32_e32 v99, v99
	v_and_b32_e32 v101, 0xffff0000, v7
	v_mov_b32_e32 v96, v198
	v_mov_b32_e32 v97, v199
	v_pk_mul_f32 v[102:103], v[100:101], v[98:99]
	s_waitcnt lgkmcnt(4)
	v_pk_fma_f32 v[96:97], v[80:81], v[232:233], v[96:97] op_sel_hi:[0,1,1]
	v_cvt_pk_bf16_f32 v108, v102, v103
	v_pk_fma_f32 v[96:97], v[80:81], v[234:235], v[96:97] op_sel:[1,0,0] op_sel_hi:[1,1,1]
	global_store_dword v166, v108, s[46:47]
	s_sub_u32 s46, s46, 0x3200
	s_subb_u32 s47, s47, 0
	global_load_dword v39, v166, s[30:31]
	s_sub_u32 s30, s30, 0x3200
	s_subb_u32 s31, s31, 0
	v_pk_fma_f32 v[96:97], v[82:83], v[236:237], v[96:97] op_sel_hi:[0,1,1]
	v_pk_fma_f32 v[96:97], v[82:83], v[238:239], v[96:97] op_sel:[1,0,0] op_sel_hi:[1,1,1]
	v_pk_fma_f32 v[96:97], v[84:85], v[240:241], v[96:97] op_sel_hi:[0,1,1]
	v_pk_fma_f32 v[96:97], v[84:85], v[242:243], v[96:97] op_sel:[1,0,0] op_sel_hi:[1,1,1]
	v_pk_fma_f32 v[96:97], v[86:87], v[244:245], v[96:97] op_sel_hi:[0,1,1]
	v_pk_fma_f32 v[96:97], v[86:87], v[246:247], v[96:97] op_sel:[1,0,0] op_sel_hi:[1,1,1]
	v_pk_fma_f32 v[96:97], v[88:89], v[248:249], v[96:97] op_sel_hi:[0,1,1]
	v_pk_fma_f32 v[96:97], v[88:89], v[250:251], v[96:97] op_sel:[1,0,0] op_sel_hi:[1,1,1]
	v_pk_fma_f32 v[96:97], v[90:91], v[252:253], v[96:97] op_sel_hi:[0,1,1]
	v_pk_fma_f32 v[96:97], v[90:91], v[254:255], v[96:97] op_sel:[1,0,0] op_sel_hi:[1,1,1]
	v_pk_fma_f32 v[96:97], v[92:93], v[220:221], v[96:97] op_sel_hi:[0,1,1]
	v_pk_fma_f32 v[96:97], v[92:93], v[222:223], v[96:97] op_sel:[1,0,0] op_sel_hi:[1,1,1]
	v_pk_fma_f32 v[96:97], v[94:95], v[224:225], v[96:97] op_sel_hi:[0,1,1]
	v_pk_fma_f32 v[96:97], v[94:95], v[226:227], v[96:97] op_sel:[1,0,0] op_sel_hi:[1,1,1]
	v_mul_f32_e64 v104, |v96|, s34
	v_mul_f32_e64 v105, |v97|, s34
	v_exp_f32_e32 v104, v104
	v_exp_f32_e32 v105, v105
	v_min_f32_e32 v106, 0, v96
	v_min_f32_e32 v107, 0, v97
	v_pk_add_f32 v[104:105], v[104:105], v[190:191]
	v_log_f32_e32 v104, v104
	v_log_f32_e32 v105, v105
	s_nop 0
	v_fma_f32 v106, v104, s35, v106
	v_fma_f32 v107, v105, s35, v107
	v_pk_fma_f32 v[192:193], v[106:107], v[188:189], v[192:193]
	ds_read_b128 v[80:83], v167 offset:3456
	ds_read_b128 v[84:87], v167 offset:3472
	ds_read_b128 v[88:91], v167 offset:3488
	ds_read_b128 v[92:95], v167 offset:3504
	v_pk_mul_f32 v[98:99], v[192:193], v[186:187]
	s_waitcnt vmcnt(39)
	v_lshlrev_b32_e32 v100, 16, v8
	v_exp_f32_e32 v98, v98
	v_exp_f32_e32 v99, v99
	v_and_b32_e32 v101, 0xffff0000, v8
	v_mov_b32_e32 v96, v198
	v_mov_b32_e32 v97, v199
	v_pk_mul_f32 v[102:103], v[100:101], v[98:99]
	s_waitcnt lgkmcnt(4)
; DI unsigned pk2(float a, float b) { f32x2 v = {a, b}; bf16v2_t r = __builtin_convertvector(v, bf16v2_t); return __builtin_bit_cast(unsigned, r); }
; DI void phase_gla_prep(const Params& p, LAS unsigned char* lds) {
;     ...
;             for (int i = 0; i < 16; ++i) kw[i] = *(const unsigned*)(big + (tokb + tg * 16 + i) * 6400 + 1024 + ch0);
; #pragma unroll
;             for (int i = 15; i >= 0; --i) { const int tok = tg * 16 + i;
;                 float z0 = bs0, z1 = bs1;
; #pragma unroll
;                 for (int r = 0; r < 16; ++r) { const float lv = lrs[tok * 16 + r]; z0 += lv * wg0[r]; z1 += lv * wg1[r]; }
;                 *(unsigned*)(big + (tokb + tok) * 6400 + 1024 + ch0) = pk2(__uint_as_float(kw[i] << 16) * __expf(t0), __uint_as_float(kw[i] & 0xffff0000u) * __expf(t1));
;                 t0 += (fminf(z0, 0.f) - __logf(1.f + __expf(-fabsf(z0)))) * (1.f / 16.f); t1 += (fminf(z1, 0.f) - __logf(1.f + __expf(-fabsf(z1)))) * (1.f / 16.f);
;             }
	v_pk_fma_f32 v[96:97], v[64:65], v[232:233], v[96:97] op_sel_hi:[0,1,1]
	v_cvt_pk_bf16_f32 v108, v102, v103
	v_pk_fma_f32 v[96:97], v[64:65], v[234:235], v[96:97] op_sel:[1,0,0] op_sel_hi:[1,1,1]
	global_store_dword v166, v108, s[46:47]
	s_sub_u32 s46, s46, 0x3200
	s_subb_u32 s47, s47, 0
	global_load_dword v40, v166, s[30:31]
	s_sub_u32 s30, s30, 0x3200
	s_subb_u32 s31, s31, 0
	v_pk_fma_f32 v[96:97], v[66:67], v[236:237], v[96:97] op_sel_hi:[0,1,1]
	v_pk_fma_f32 v[96:97], v[66:67], v[238:239], v[96:97] op_sel:[1,0,0] op_sel_hi:[1,1,1]
	v_pk_fma_f32 v[96:97], v[68:69], v[240:241], v[96:97] op_sel_hi:[0,1,1]
	v_pk_fma_f32 v[96:97], v[68:69], v[242:243], v[96:97] op_sel:[1,0,0] op_sel_hi:[1,1,1]
	v_pk_fma_f32 v[96:97], v[70:71], v[244:245], v[96:97] op_sel_hi:[0,1,1]
	v_pk_fma_f32 v[96:97], v[70:71], v[246:247], v[96:97] op_sel:[1,0,0] op_sel_hi:[1,1,1]
	v_pk_fma_f32 v[96:97], v[72:73], v[248:249], v[96:97] op_sel_hi:[0,1,1]
	v_pk_fma_f32 v[96:97], v[72:73], v[250:251], v[96:97] op_sel:[1,0,0] op_sel_hi:[1,1,1]
	v_pk_fma_f32 v[96:97], v[74:75], v[252:253], v[96:97] op_sel_hi:[0,1,1]
	v_pk_fma_f32 v[96:97], v[74:75], v[254:255], v[96:97] op_sel:[1,0,0] op_sel_hi:[1,1,1]
	v_pk_fma_f32 v[96:97], v[76:77], v[220:221], v[96:97] op_sel_hi:[0,1,1]
	v_pk_fma_f32 v[96:97], v[76:77], v[222:223], v[96:97] op_sel:[1,0,0] op_sel_hi:[1,1,1]
	v_pk_fma_f32 v[96:97], v[78:79], v[224:225], v[96:97] op_sel_hi:[0,1,1]
	v_pk_fma_f32 v[96:97], v[78:79], v[226:227], v[96:97] op_sel:[1,0,0] op_sel_hi:[1,1,1]
	v_mul_f32_e64 v104, |v96|, s34
	v_mul_f32_e64 v105, |v97|, s34
	v_exp_f32_e32 v104, v104
	v_exp_f32_e32 v105, v105
	v_min_f32_e32 v106, 0, v96
	v_min_f32_e32 v107, 0, v97
	v_pk_add_f32 v[104:105], v[104:105], v[190:191]
	v_log_f32_e32 v104, v104
	v_log_f32_e32 v105, v105
	s_nop 0
	v_fma_f32 v106, v104, s35, v106
	v_fma_f32 v107, v105, s35, v107
	v_pk_fma_f32 v[192:193], v[106:107], v[188:189], v[192:193]
	ds_read_b128 v[64:67], v167 offset:3392
	ds_read_b128 v[68:71], v167 offset:3408
	ds_read_b128 v[72:75], v167 offset:3424
	ds_read_b128 v[76:79], v167 offset:3440
	v_pk_mul_f32 v[98:99], v[192:193], v[186:187]
	s_waitcnt vmcnt(40)
	v_lshlrev_b32_e32 v100, 16, v9
	v_exp_f32_e32 v98, v98
	v_exp_f32_e32 v99, v99
	v_and_b32_e32 v101, 0xffff0000, v9
	v_mov_b32_e32 v96, v198
	v_mov_b32_e32 v97, v199
	v_pk_mul_f32 v[102:103], v[100:101], v[98:99]
	s_waitcnt lgkmcnt(4)
	v_pk_fma_f32 v[96:97], v[80:81], v[232:233], v[96:97] op_sel_hi:[0,1,1]
	v_cvt_pk_bf16_f32 v108, v102, v103
	v_pk_fma_f32 v[96:97], v[80:81], v[234:235], v[96:97] op_sel:[1,0,0] op_sel_hi:[1,1,1]
	global_store_dword v166, v108, s[46:47]
	s_sub_u32 s46, s46, 0x3200
	s_subb_u32 s47, s47, 0
	global_load_dword v41, v166, s[30:31]
	s_sub_u32 s30, s30, 0x3200
	s_subb_u32 s31, s31, 0
	v_pk_fma_f32 v[96:97], v[82:83], v[236:237], v[96:97] op_sel_hi:[0,1,1]
	v_pk_fma_f32 v[96:97], v[82:83], v[238:239], v[96:97] op_sel:[1,0,0] op_sel_hi:[1,1,1]
	v_pk_fma_f32 v[96:97], v[84:85], v[240:241], v[96:97] op_sel_hi:[0,1,1]
	v_pk_fma_f32 v[96:97], v[84:85], v[242:243], v[96:97] op_sel:[1,0,0] op_sel_hi:[1,1,1]
	v_pk_fma_f32 v[96:97], v[86:87], v[244:245], v[96:97] op_sel_hi:[0,1,1]
	v_pk_fma_f32 v[96:97], v[86:87], v[246:247], v[96:97] op_sel:[1,0,0] op_sel_hi:[1,1,1]
	v_pk_fma_f32 v[96:97], v[88:89], v[248:249], v[96:97] op_sel_hi:[0,1,1]
	v_pk_fma_f32 v[96:97], v[88:89], v[250:251], v[96:97] op_sel:[1,0,0] op_sel_hi:[1,1,1]
	v_pk_fma_f32 v[96:97], v[90:91], v[252:253], v[96:97] op_sel_hi:[0,1,1]
	v_pk_fma_f32 v[96:97], v[90:91], v[254:255], v[96:97] op_sel:[1,0,0] op_sel_hi:[1,1,1]
	v_pk_fma_f32 v[96:97], v[92:93], v[220:221], v[96:97] op_sel_hi:[0,1,1]
	v_pk_fma_f32 v[96:97], v[92:93], v[222:223], v[96:97] op_sel:[1,0,0] op_sel_hi:[1,1,1]
	v_pk_fma_f32 v[96:97], v[94:95], v[224:225], v[96:97] op_sel_hi:[0,1,1]
	v_pk_fma_f32 v[96:97], v[94:95], v[226:227], v[96:97] op_sel:[1,0,0] op_sel_hi:[1,1,1]
	v_mul_f32_e64 v104, |v96|, s34
	v_mul_f32_e64 v105, |v97|, s34
	v_exp_f32_e32 v104, v104
	v_exp_f32_e32 v105, v105
	v_min_f32_e32 v106, 0, v96
	v_min_f32_e32 v107, 0, v97
	v_pk_add_f32 v[104:105], v[104:105], v[190:191]
	v_log_f32_e32 v104, v104
	v_log_f32_e32 v105, v105
	s_nop 0
	v_fma_f32 v106, v104, s35, v106
	v_fma_f32 v107, v105, s35, v107
	v_pk_fma_f32 v[192:193], v[106:107], v[188:189], v[192:193]
	ds_read_b128 v[80:83], v167 offset:3328
	ds_read_b128 v[84:87], v167 offset:3344
	ds_read_b128 v[88:91], v167 offset:3360
	ds_read_b128 v[92:95], v167 offset:3376
	v_pk_mul_f32 v[98:99], v[192:193], v[186:187]
	s_waitcnt vmcnt(41)
	v_lshlrev_b32_e32 v100, 16, v10
	v_exp_f32_e32 v98, v98
	v_exp_f32_e32 v99, v99
	v_and_b32_e32 v101, 0xffff0000, v10
	v_mov_b32_e32 v96, v198
	v_mov_b32_e32 v97, v199
	v_pk_mul_f32 v[102:103], v[100:101], v[98:99]
	s_waitcnt lgkmcnt(4)
; DI unsigned pk2(float a, float b) { f32x2 v = {a, b}; bf16v2_t r = __builtin_convertvector(v, bf16v2_t); return __builtin_bit_cast(unsigned, r); }
; DI void phase_gla_prep(const Params& p, LAS unsigned char* lds) {
;     ...
;             for (int i = 0; i < 16; ++i) kw[i] = *(const unsigned*)(big + (tokb + tg * 16 + i) * 6400 + 1024 + ch0);
; #pragma unroll
;             for (int i = 15; i >= 0; --i) { const int tok = tg * 16 + i;
;                 float z0 = bs0, z1 = bs1;
; #pragma unroll
;                 for (int r = 0; r < 16; ++r) { const float lv = lrs[tok * 16 + r]; z0 += lv * wg0[r]; z1 += lv * wg1[r]; }
;                 *(unsigned*)(big + (tokb + tok) * 6400 + 1024 + ch0) = pk2(__uint_as_float(kw[i] << 16) * __expf(t0), __uint_as_float(kw[i] & 0xffff0000u) * __expf(t1));
;                 t0 += (fminf(z0, 0.f) - __logf(1.f + __expf(-fabsf(z0)))) * (1.f / 16.f); t1 += (fminf(z1, 0.f) - __logf(1.f + __expf(-fabsf(z1)))) * (1.f / 16.f);
;             }
	v_pk_fma_f32 v[96:97], v[64:65], v[232:233], v[96:97] op_sel_hi:[0,1,1]
	v_cvt_pk_bf16_f32 v108, v102, v103
	v_pk_fma_f32 v[96:97], v[64:65], v[234:235], v[96:97] op_sel:[1,0,0] op_sel_hi:[1,1,1]
	global_store_dword v166, v108, s[46:47]
	s_sub_u32 s46, s46, 0x3200
	s_subb_u32 s47, s47, 0
	global_load_dword v42, v166, s[30:31]
	s_sub_u32 s30, s30, 0x3200
	s_subb_u32 s31, s31, 0
	v_pk_fma_f32 v[96:97], v[66:67], v[236:237], v[96:97] op_sel_hi:[0,1,1]
	v_pk_fma_f32 v[96:97], v[66:67], v[238:239], v[96:97] op_sel:[1,0,0] op_sel_hi:[1,1,1]
	v_pk_fma_f32 v[96:97], v[68:69], v[240:241], v[96:97] op_sel_hi:[0,1,1]
	v_pk_fma_f32 v[96:97], v[68:69], v[242:243], v[96:97] op_sel:[1,0,0] op_sel_hi:[1,1,1]
	v_pk_fma_f32 v[96:97], v[70:71], v[244:245], v[96:97] op_sel_hi:[0,1,1]
	v_pk_fma_f32 v[96:97], v[70:71], v[246:247], v[96:97] op_sel:[1,0,0] op_sel_hi:[1,1,1]
	v_pk_fma_f32 v[96:97], v[72:73], v[248:249], v[96:97] op_sel_hi:[0,1,1]
	v_pk_fma_f32 v[96:97], v[72:73], v[250:251], v[96:97] op_sel:[1,0,0] op_sel_hi:[1,1,1]
	v_pk_fma_f32 v[96:97], v[74:75], v[252:253], v[96:97] op_sel_hi:[0,1,1]
	v_pk_fma_f32 v[96:97], v[74:75], v[254:255], v[96:97] op_sel:[1,0,0] op_sel_hi:[1,1,1]
	v_pk_fma_f32 v[96:97], v[76:77], v[220:221], v[96:97] op_sel_hi:[0,1,1]
	v_pk_fma_f32 v[96:97], v[76:77], v[222:223], v[96:97] op_sel:[1,0,0] op_sel_hi:[1,1,1]
	v_pk_fma_f32 v[96:97], v[78:79], v[224:225], v[96:97] op_sel_hi:[0,1,1]
	v_pk_fma_f32 v[96:97], v[78:79], v[226:227], v[96:97] op_sel:[1,0,0] op_sel_hi:[1,1,1]
	v_mul_f32_e64 v104, |v96|, s34
	v_mul_f32_e64 v105, |v97|, s34
	v_exp_f32_e32 v104, v104
	v_exp_f32_e32 v105, v105
	v_min_f32_e32 v106, 0, v96
	v_min_f32_e32 v107, 0, v97
	v_pk_add_f32 v[104:105], v[104:105], v[190:191]
	v_log_f32_e32 v104, v104
	v_log_f32_e32 v105, v105
	s_nop 0
	v_fma_f32 v106, v104, s35, v106
	v_fma_f32 v107, v105, s35, v107
	v_pk_fma_f32 v[192:193], v[106:107], v[188:189], v[192:193]
	ds_read_b128 v[64:67], v167 offset:3264
	ds_read_b128 v[68:71], v167 offset:3280
	ds_read_b128 v[72:75], v167 offset:3296
	ds_read_b128 v[76:79], v167 offset:3312
	v_pk_mul_f32 v[98:99], v[192:193], v[186:187]
	s_waitcnt vmcnt(42)
	v_lshlrev_b32_e32 v100, 16, v11
	v_exp_f32_e32 v98, v98
	v_exp_f32_e32 v99, v99
	v_and_b32_e32 v101, 0xffff0000, v11
	v_mov_b32_e32 v96, v198
	v_mov_b32_e32 v97, v199
	v_pk_mul_f32 v[102:103], v[100:101], v[98:99]
	s_waitcnt lgkmcnt(4)
	v_pk_fma_f32 v[96:97], v[80:81], v[232:233], v[96:97] op_sel_hi:[0,1,1]
	v_cvt_pk_bf16_f32 v108, v102, v103
	v_pk_fma_f32 v[96:97], v[80:81], v[234:235], v[96:97] op_sel:[1,0,0] op_sel_hi:[1,1,1]
	global_store_dword v166, v108, s[46:47]
	s_sub_u32 s46, s46, 0x3200
	s_subb_u32 s47, s47, 0
	global_load_dword v43, v166, s[30:31]
	s_sub_u32 s30, s30, 0x3200
	s_subb_u32 s31, s31, 0
	v_pk_fma_f32 v[96:97], v[82:83], v[236:237], v[96:97] op_sel_hi:[0,1,1]
	v_pk_fma_f32 v[96:97], v[82:83], v[238:239], v[96:97] op_sel:[1,0,0] op_sel_hi:[1,1,1]
	v_pk_fma_f32 v[96:97], v[84:85], v[240:241], v[96:97] op_sel_hi:[0,1,1]
	v_pk_fma_f32 v[96:97], v[84:85], v[242:243], v[96:97] op_sel:[1,0,0] op_sel_hi:[1,1,1]
	v_pk_fma_f32 v[96:97], v[86:87], v[244:245], v[96:97] op_sel_hi:[0,1,1]
	v_pk_fma_f32 v[96:97], v[86:87], v[246:247], v[96:97] op_sel:[1,0,0] op_sel_hi:[1,1,1]
	v_pk_fma_f32 v[96:97], v[88:89], v[248:249], v[96:97] op_sel_hi:[0,1,1]
	v_pk_fma_f32 v[96:97], v[88:89], v[250:251], v[96:97] op_sel:[1,0,0] op_sel_hi:[1,1,1]
	v_pk_fma_f32 v[96:97], v[90:91], v[252:253], v[96:97] op_sel_hi:[0,1,1]
	v_pk_fma_f32 v[96:97], v[90:91], v[254:255], v[96:97] op_sel:[1,0,0] op_sel_hi:[1,1,1]
	v_pk_fma_f32 v[96:97], v[92:93], v[220:221], v[96:97] op_sel_hi:[0,1,1]
	v_pk_fma_f32 v[96:97], v[92:93], v[222:223], v[96:97] op_sel:[1,0,0] op_sel_hi:[1,1,1]
	v_pk_fma_f32 v[96:97], v[94:95], v[224:225], v[96:97] op_sel_hi:[0,1,1]
	v_pk_fma_f32 v[96:97], v[94:95], v[226:227], v[96:97] op_sel:[1,0,0] op_sel_hi:[1,1,1]
	v_mul_f32_e64 v104, |v96|, s34
	v_mul_f32_e64 v105, |v97|, s34
	v_exp_f32_e32 v104, v104
	v_exp_f32_e32 v105, v105
	v_min_f32_e32 v106, 0, v96
	v_min_f32_e32 v107, 0, v97
	v_pk_add_f32 v[104:105], v[104:105], v[190:191]
	v_log_f32_e32 v104, v104
	v_log_f32_e32 v105, v105
	s_nop 0
	v_fma_f32 v106, v104, s35, v106
	v_fma_f32 v107, v105, s35, v107
	v_pk_fma_f32 v[192:193], v[106:107], v[188:189], v[192:193]
	ds_read_b128 v[80:83], v167 offset:3200
	ds_read_b128 v[84:87], v167 offset:3216
	ds_read_b128 v[88:91], v167 offset:3232
	ds_read_b128 v[92:95], v167 offset:3248
	v_pk_mul_f32 v[98:99], v[192:193], v[186:187]
	s_waitcnt vmcnt(43)
	v_lshlrev_b32_e32 v100, 16, v12
	v_exp_f32_e32 v98, v98
	v_exp_f32_e32 v99, v99
	v_and_b32_e32 v101, 0xffff0000, v12
	v_mov_b32_e32 v96, v198
	v_mov_b32_e32 v97, v199
	v_pk_mul_f32 v[102:103], v[100:101], v[98:99]
	s_waitcnt lgkmcnt(4)
; DI unsigned pk2(float a, float b) { f32x2 v = {a, b}; bf16v2_t r = __builtin_convertvector(v, bf16v2_t); return __builtin_bit_cast(unsigned, r); }
; DI void phase_gla_prep(const Params& p, LAS unsigned char* lds) {
;     ...
;             for (int i = 0; i < 16; ++i) kw[i] = *(const unsigned*)(big + (tokb + tg * 16 + i) * 6400 + 1024 + ch0);
; #pragma unroll
;             for (int i = 15; i >= 0; --i) { const int tok = tg * 16 + i;
;                 float z0 = bs0, z1 = bs1;
; #pragma unroll
;                 for (int r = 0; r < 16; ++r) { const float lv = lrs[tok * 16 + r]; z0 += lv * wg0[r]; z1 += lv * wg1[r]; }
;                 *(unsigned*)(big + (tokb + tok) * 6400 + 1024 + ch0) = pk2(__uint_as_float(kw[i] << 16) * __expf(t0), __uint_as_float(kw[i] & 0xffff0000u) * __expf(t1));
;                 t0 += (fminf(z0, 0.f) - __logf(1.f + __expf(-fabsf(z0)))) * (1.f / 16.f); t1 += (fminf(z1, 0.f) - __logf(1.f + __expf(-fabsf(z1)))) * (1.f / 16.f);
;             }
	v_pk_fma_f32 v[96:97], v[64:65], v[232:233], v[96:97] op_sel_hi:[0,1,1]
	v_cvt_pk_bf16_f32 v108, v102, v103
	v_pk_fma_f32 v[96:97], v[64:65], v[234:235], v[96:97] op_sel:[1,0,0] op_sel_hi:[1,1,1]
	global_store_dword v166, v108, s[46:47]
	s_sub_u32 s46, s46, 0x3200
	s_subb_u32 s47, s47, 0
	global_load_dword v44, v166, s[30:31]
	s_sub_u32 s30, s30, 0x3200
	s_subb_u32 s31, s31, 0
	v_pk_fma_f32 v[96:97], v[66:67], v[236:237], v[96:97] op_sel_hi:[0,1,1]
	v_pk_fma_f32 v[96:97], v[66:67], v[238:239], v[96:97] op_sel:[1,0,0] op_sel_hi:[1,1,1]
	v_pk_fma_f32 v[96:97], v[68:69], v[240:241], v[96:97] op_sel_hi:[0,1,1]
	v_pk_fma_f32 v[96:97], v[68:69], v[242:243], v[96:97] op_sel:[1,0,0] op_sel_hi:[1,1,1]
	v_pk_fma_f32 v[96:97], v[70:71], v[244:245], v[96:97] op_sel_hi:[0,1,1]
	v_pk_fma_f32 v[96:97], v[70:71], v[246:247], v[96:97] op_sel:[1,0,0] op_sel_hi:[1,1,1]
	v_pk_fma_f32 v[96:97], v[72:73], v[248:249], v[96:97] op_sel_hi:[0,1,1]
	v_pk_fma_f32 v[96:97], v[72:73], v[250:251], v[96:97] op_sel:[1,0,0] op_sel_hi:[1,1,1]
	v_pk_fma_f32 v[96:97], v[74:75], v[252:253], v[96:97] op_sel_hi:[0,1,1]
	v_pk_fma_f32 v[96:97], v[74:75], v[254:255], v[96:97] op_sel:[1,0,0] op_sel_hi:[1,1,1]
	v_pk_fma_f32 v[96:97], v[76:77], v[220:221], v[96:97] op_sel_hi:[0,1,1]
	v_pk_fma_f32 v[96:97], v[76:77], v[222:223], v[96:97] op_sel:[1,0,0] op_sel_hi:[1,1,1]
	v_pk_fma_f32 v[96:97], v[78:79], v[224:225], v[96:97] op_sel_hi:[0,1,1]
	v_pk_fma_f32 v[96:97], v[78:79], v[226:227], v[96:97] op_sel:[1,0,0] op_sel_hi:[1,1,1]
	v_mul_f32_e64 v104, |v96|, s34
	v_mul_f32_e64 v105, |v97|, s34
	v_exp_f32_e32 v104, v104
	v_exp_f32_e32 v105, v105
	v_min_f32_e32 v106, 0, v96
	v_min_f32_e32 v107, 0, v97
	v_pk_add_f32 v[104:105], v[104:105], v[190:191]
	v_log_f32_e32 v104, v104
	v_log_f32_e32 v105, v105
	s_nop 0
	v_fma_f32 v106, v104, s35, v106
	v_fma_f32 v107, v105, s35, v107
	v_pk_fma_f32 v[192:193], v[106:107], v[188:189], v[192:193]
	ds_read_b128 v[64:67], v167 offset:3136
	ds_read_b128 v[68:71], v167 offset:3152
	ds_read_b128 v[72:75], v167 offset:3168
	ds_read_b128 v[76:79], v167 offset:3184
	v_pk_mul_f32 v[98:99], v[192:193], v[186:187]
	s_waitcnt vmcnt(44)
	v_lshlrev_b32_e32 v100, 16, v13
	v_exp_f32_e32 v98, v98
	v_exp_f32_e32 v99, v99
	v_and_b32_e32 v101, 0xffff0000, v13
	v_mov_b32_e32 v96, v198
	v_mov_b32_e32 v97, v199
	v_pk_mul_f32 v[102:103], v[100:101], v[98:99]
	s_waitcnt lgkmcnt(4)
	v_pk_fma_f32 v[96:97], v[80:81], v[232:233], v[96:97] op_sel_hi:[0,1,1]
	v_cvt_pk_bf16_f32 v108, v102, v103
	v_pk_fma_f32 v[96:97], v[80:81], v[234:235], v[96:97] op_sel:[1,0,0] op_sel_hi:[1,1,1]
	global_store_dword v166, v108, s[46:47]
	s_sub_u32 s46, s46, 0x3200
	s_subb_u32 s47, s47, 0
	global_load_dword v45, v166, s[30:31]
	s_sub_u32 s30, s30, 0x3200
	s_subb_u32 s31, s31, 0
	v_pk_fma_f32 v[96:97], v[82:83], v[236:237], v[96:97] op_sel_hi:[0,1,1]
	v_pk_fma_f32 v[96:97], v[82:83], v[238:239], v[96:97] op_sel:[1,0,0] op_sel_hi:[1,1,1]
	v_pk_fma_f32 v[96:97], v[84:85], v[240:241], v[96:97] op_sel_hi:[0,1,1]
	v_pk_fma_f32 v[96:97], v[84:85], v[242:243], v[96:97] op_sel:[1,0,0] op_sel_hi:[1,1,1]
	v_pk_fma_f32 v[96:97], v[86:87], v[244:245], v[96:97] op_sel_hi:[0,1,1]
	v_pk_fma_f32 v[96:97], v[86:87], v[246:247], v[96:97] op_sel:[1,0,0] op_sel_hi:[1,1,1]
	v_pk_fma_f32 v[96:97], v[88:89], v[248:249], v[96:97] op_sel_hi:[0,1,1]
	v_pk_fma_f32 v[96:97], v[88:89], v[250:251], v[96:97] op_sel:[1,0,0] op_sel_hi:[1,1,1]
	v_pk_fma_f32 v[96:97], v[90:91], v[252:253], v[96:97] op_sel_hi:[0,1,1]
	v_pk_fma_f32 v[96:97], v[90:91], v[254:255], v[96:97] op_sel:[1,0,0] op_sel_hi:[1,1,1]
	v_pk_fma_f32 v[96:97], v[92:93], v[220:221], v[96:97] op_sel_hi:[0,1,1]
	v_pk_fma_f32 v[96:97], v[92:93], v[222:223], v[96:97] op_sel:[1,0,0] op_sel_hi:[1,1,1]
	v_pk_fma_f32 v[96:97], v[94:95], v[224:225], v[96:97] op_sel_hi:[0,1,1]
	v_pk_fma_f32 v[96:97], v[94:95], v[226:227], v[96:97] op_sel:[1,0,0] op_sel_hi:[1,1,1]
	v_mul_f32_e64 v104, |v96|, s34
	v_mul_f32_e64 v105, |v97|, s34
	v_exp_f32_e32 v104, v104
	v_exp_f32_e32 v105, v105
	v_min_f32_e32 v106, 0, v96
	v_min_f32_e32 v107, 0, v97
	v_pk_add_f32 v[104:105], v[104:105], v[190:191]
	v_log_f32_e32 v104, v104
	v_log_f32_e32 v105, v105
	s_nop 0
	v_fma_f32 v106, v104, s35, v106
	v_fma_f32 v107, v105, s35, v107
	v_pk_fma_f32 v[192:193], v[106:107], v[188:189], v[192:193]
	ds_read_b128 v[80:83], v167 offset:3072
	ds_read_b128 v[84:87], v167 offset:3088
	ds_read_b128 v[88:91], v167 offset:3104
	ds_read_b128 v[92:95], v167 offset:3120
	v_pk_mul_f32 v[98:99], v[192:193], v[186:187]
	s_waitcnt vmcnt(45)
	v_lshlrev_b32_e32 v100, 16, v14
	v_exp_f32_e32 v98, v98
	v_exp_f32_e32 v99, v99
	v_and_b32_e32 v101, 0xffff0000, v14
	v_mov_b32_e32 v96, v198
	v_mov_b32_e32 v97, v199
	v_pk_mul_f32 v[102:103], v[100:101], v[98:99]
	s_waitcnt lgkmcnt(4)
; DI unsigned pk2(float a, float b) { f32x2 v = {a, b}; bf16v2_t r = __builtin_convertvector(v, bf16v2_t); return __builtin_bit_cast(unsigned, r); }
; DI void phase_gla_prep(const Params& p, LAS unsigned char* lds) {
;     ...
;             for (int i = 0; i < 16; ++i) kw[i] = *(const unsigned*)(big + (tokb + tg * 16 + i) * 6400 + 1024 + ch0);
; #pragma unroll
;             for (int i = 15; i >= 0; --i) { const int tok = tg * 16 + i;
;                 float z0 = bs0, z1 = bs1;
; #pragma unroll
;                 for (int r = 0; r < 16; ++r) { const float lv = lrs[tok * 16 + r]; z0 += lv * wg0[r]; z1 += lv * wg1[r]; }
;                 *(unsigned*)(big + (tokb + tok) * 6400 + 1024 + ch0) = pk2(__uint_as_float(kw[i] << 16) * __expf(t0), __uint_as_float(kw[i] & 0xffff0000u) * __expf(t1));
;                 t0 += (fminf(z0, 0.f) - __logf(1.f + __expf(-fabsf(z0)))) * (1.f / 16.f); t1 += (fminf(z1, 0.f) - __logf(1.f + __expf(-fabsf(z1)))) * (1.f / 16.f);
;             }
	v_pk_fma_f32 v[96:97], v[64:65], v[232:233], v[96:97] op_sel_hi:[0,1,1]
	v_cvt_pk_bf16_f32 v108, v102, v103
	v_pk_fma_f32 v[96:97], v[64:65], v[234:235], v[96:97] op_sel:[1,0,0] op_sel_hi:[1,1,1]
	global_store_dword v166, v108, s[46:47]
	s_sub_u32 s46, s46, 0x3200
	s_subb_u32 s47, s47, 0
	global_load_dword v46, v166, s[30:31]
	s_sub_u32 s30, s30, 0x3200
	s_subb_u32 s31, s31, 0
	v_pk_fma_f32 v[96:97], v[66:67], v[236:237], v[96:97] op_sel_hi:[0,1,1]
	v_pk_fma_f32 v[96:97], v[66:67], v[238:239], v[96:97] op_sel:[1,0,0] op_sel_hi:[1,1,1]
	v_pk_fma_f32 v[96:97], v[68:69], v[240:241], v[96:97] op_sel_hi:[0,1,1]
	v_pk_fma_f32 v[96:97], v[68:69], v[242:243], v[96:97] op_sel:[1,0,0] op_sel_hi:[1,1,1]
	v_pk_fma_f32 v[96:97], v[70:71], v[244:245], v[96:97] op_sel_hi:[0,1,1]
	v_pk_fma_f32 v[96:97], v[70:71], v[246:247], v[96:97] op_sel:[1,0,0] op_sel_hi:[1,1,1]
	v_pk_fma_f32 v[96:97], v[72:73], v[248:249], v[96:97] op_sel_hi:[0,1,1]
	v_pk_fma_f32 v[96:97], v[72:73], v[250:251], v[96:97] op_sel:[1,0,0] op_sel_hi:[1,1,1]
	v_pk_fma_f32 v[96:97], v[74:75], v[252:253], v[96:97] op_sel_hi:[0,1,1]
	v_pk_fma_f32 v[96:97], v[74:75], v[254:255], v[96:97] op_sel:[1,0,0] op_sel_hi:[1,1,1]
	v_pk_fma_f32 v[96:97], v[76:77], v[220:221], v[96:97] op_sel_hi:[0,1,1]
	v_pk_fma_f32 v[96:97], v[76:77], v[222:223], v[96:97] op_sel:[1,0,0] op_sel_hi:[1,1,1]
	v_pk_fma_f32 v[96:97], v[78:79], v[224:225], v[96:97] op_sel_hi:[0,1,1]
	v_pk_fma_f32 v[96:97], v[78:79], v[226:227], v[96:97] op_sel:[1,0,0] op_sel_hi:[1,1,1]
	v_mul_f32_e64 v104, |v96|, s34
	v_mul_f32_e64 v105, |v97|, s34
	v_exp_f32_e32 v104, v104
	v_exp_f32_e32 v105, v105
	v_min_f32_e32 v106, 0, v96
	v_min_f32_e32 v107, 0, v97
	v_pk_add_f32 v[104:105], v[104:105], v[190:191]
	v_log_f32_e32 v104, v104
	v_log_f32_e32 v105, v105
	s_nop 0
	v_fma_f32 v106, v104, s35, v106
	v_fma_f32 v107, v105, s35, v107
	v_pk_fma_f32 v[192:193], v[106:107], v[188:189], v[192:193]
	ds_read_b128 v[64:67], v167 offset:3008
	ds_read_b128 v[68:71], v167 offset:3024
	ds_read_b128 v[72:75], v167 offset:3040
	ds_read_b128 v[76:79], v167 offset:3056
	v_pk_mul_f32 v[98:99], v[192:193], v[186:187]
	s_waitcnt vmcnt(46)
	v_lshlrev_b32_e32 v100, 16, v15
	v_exp_f32_e32 v98, v98
	v_exp_f32_e32 v99, v99
	v_and_b32_e32 v101, 0xffff0000, v15
	v_mov_b32_e32 v96, v198
	v_mov_b32_e32 v97, v199
	v_pk_mul_f32 v[102:103], v[100:101], v[98:99]
	s_waitcnt lgkmcnt(4)
	v_pk_fma_f32 v[96:97], v[80:81], v[232:233], v[96:97] op_sel_hi:[0,1,1]
	v_cvt_pk_bf16_f32 v108, v102, v103
	v_pk_fma_f32 v[96:97], v[80:81], v[234:235], v[96:97] op_sel:[1,0,0] op_sel_hi:[1,1,1]
	global_store_dword v166, v108, s[46:47]
	s_sub_u32 s46, s46, 0x3200
	s_subb_u32 s47, s47, 0
	global_load_dword v47, v166, s[30:31]
	s_sub_u32 s30, s30, 0x3200
	s_subb_u32 s31, s31, 0
	v_pk_fma_f32 v[96:97], v[82:83], v[236:237], v[96:97] op_sel_hi:[0,1,1]
	v_pk_fma_f32 v[96:97], v[82:83], v[238:239], v[96:97] op_sel:[1,0,0] op_sel_hi:[1,1,1]
	v_pk_fma_f32 v[96:97], v[84:85], v[240:241], v[96:97] op_sel_hi:[0,1,1]
	v_pk_fma_f32 v[96:97], v[84:85], v[242:243], v[96:97] op_sel:[1,0,0] op_sel_hi:[1,1,1]
	v_pk_fma_f32 v[96:97], v[86:87], v[244:245], v[96:97] op_sel_hi:[0,1,1]
	v_pk_fma_f32 v[96:97], v[86:87], v[246:247], v[96:97] op_sel:[1,0,0] op_sel_hi:[1,1,1]
	v_pk_fma_f32 v[96:97], v[88:89], v[248:249], v[96:97] op_sel_hi:[0,1,1]
	v_pk_fma_f32 v[96:97], v[88:89], v[250:251], v[96:97] op_sel:[1,0,0] op_sel_hi:[1,1,1]
	v_pk_fma_f32 v[96:97], v[90:91], v[252:253], v[96:97] op_sel_hi:[0,1,1]
	v_pk_fma_f32 v[96:97], v[90:91], v[254:255], v[96:97] op_sel:[1,0,0] op_sel_hi:[1,1,1]
	v_pk_fma_f32 v[96:97], v[92:93], v[220:221], v[96:97] op_sel_hi:[0,1,1]
	v_pk_fma_f32 v[96:97], v[92:93], v[222:223], v[96:97] op_sel:[1,0,0] op_sel_hi:[1,1,1]
	v_pk_fma_f32 v[96:97], v[94:95], v[224:225], v[96:97] op_sel_hi:[0,1,1]
	v_pk_fma_f32 v[96:97], v[94:95], v[226:227], v[96:97] op_sel:[1,0,0] op_sel_hi:[1,1,1]
	v_mul_f32_e64 v104, |v96|, s34
	v_mul_f32_e64 v105, |v97|, s34
	v_exp_f32_e32 v104, v104
	v_exp_f32_e32 v105, v105
	v_min_f32_e32 v106, 0, v96
	v_min_f32_e32 v107, 0, v97
	v_pk_add_f32 v[104:105], v[104:105], v[190:191]
	v_log_f32_e32 v104, v104
	v_log_f32_e32 v105, v105
	s_nop 0
	v_fma_f32 v106, v104, s35, v106
	v_fma_f32 v107, v105, s35, v107
	v_pk_fma_f32 v[192:193], v[106:107], v[188:189], v[192:193]
	ds_read_b128 v[80:83], v167 offset:2944
	ds_read_b128 v[84:87], v167 offset:2960
	ds_read_b128 v[88:91], v167 offset:2976
	ds_read_b128 v[92:95], v167 offset:2992
	v_pk_mul_f32 v[98:99], v[192:193], v[186:187]
	s_waitcnt vmcnt(47)
	v_lshlrev_b32_e32 v100, 16, v16
	v_exp_f32_e32 v98, v98
	v_exp_f32_e32 v99, v99
	v_and_b32_e32 v101, 0xffff0000, v16
	v_mov_b32_e32 v96, v198
	v_mov_b32_e32 v97, v199
	v_pk_mul_f32 v[102:103], v[100:101], v[98:99]
	s_waitcnt lgkmcnt(4)
; DI unsigned pk2(float a, float b) { f32x2 v = {a, b}; bf16v2_t r = __builtin_convertvector(v, bf16v2_t); return __builtin_bit_cast(unsigned, r); }
; DI void phase_gla_prep(const Params& p, LAS unsigned char* lds) {
;     ...
;             unsigned kw[16];
; #pragma unroll
;             for (int i = 0; i < 16; ++i) kw[i] = *(const unsigned*)(big + (tokb + tg * 16 + i) * 6400 + 1024 + ch0);
; #pragma unroll
;             for (int i = 15; i >= 0; --i) { const int tok = tg * 16 + i;
;                 float z0 = bs0, z1 = bs1;
; #pragma unroll
;                 for (int r = 0; r < 16; ++r) { const float lv = lrs[tok * 16 + r]; z0 += lv * wg0[r]; z1 += lv * wg1[r]; }
;                 *(unsigned*)(big + (tokb + tok) * 6400 + 1024 + ch0) = pk2(__uint_as_float(kw[i] << 16) * __expf(t0), __uint_as_float(kw[i] & 0xffff0000u) * __expf(t1));
;                 t0 += (fminf(z0, 0.f) - __logf(1.f + __expf(-fabsf(z0)))) * (1.f / 16.f); t1 += (fminf(z1, 0.f) - __logf(1.f + __expf(-fabsf(z1)))) * (1.f / 16.f);
	v_pk_fma_f32 v[96:97], v[64:65], v[232:233], v[96:97] op_sel_hi:[0,1,1]
	v_cvt_pk_bf16_f32 v108, v102, v103
	v_pk_fma_f32 v[96:97], v[64:65], v[234:235], v[96:97] op_sel:[1,0,0] op_sel_hi:[1,1,1]
	global_store_dword v166, v108, s[46:47]
	s_sub_u32 s46, s46, 0x3200
	s_subb_u32 s47, s47, 0
	global_load_dword v48, v166, s[30:31]
	s_sub_u32 s30, s30, 0x3200
	s_subb_u32 s31, s31, 0
	v_pk_fma_f32 v[96:97], v[66:67], v[236:237], v[96:97] op_sel_hi:[0,1,1]
	v_pk_fma_f32 v[96:97], v[66:67], v[238:239], v[96:97] op_sel:[1,0,0] op_sel_hi:[1,1,1]
	v_pk_fma_f32 v[96:97], v[68:69], v[240:241], v[96:97] op_sel_hi:[0,1,1]
	v_pk_fma_f32 v[96:97], v[68:69], v[242:243], v[96:97] op_sel:[1,0,0] op_sel_hi:[1,1,1]
	v_pk_fma_f32 v[96:97], v[70:71], v[244:245], v[96:97] op_sel_hi:[0,1,1]
	v_pk_fma_f32 v[96:97], v[70:71], v[246:247], v[96:97] op_sel:[1,0,0] op_sel_hi:[1,1,1]
	v_pk_fma_f32 v[96:97], v[72:73], v[248:249], v[96:97] op_sel_hi:[0,1,1]
	v_pk_fma_f32 v[96:97], v[72:73], v[250:251], v[96:97] op_sel:[1,0,0] op_sel_hi:[1,1,1]
	v_pk_fma_f32 v[96:97], v[74:75], v[252:253], v[96:97] op_sel_hi:[0,1,1]
	v_pk_fma_f32 v[96:97], v[74:75], v[254:255], v[96:97] op_sel:[1,0,0] op_sel_hi:[1,1,1]
	v_pk_fma_f32 v[96:97], v[76:77], v[220:221], v[96:97] op_sel_hi:[0,1,1]
	v_pk_fma_f32 v[96:97], v[76:77], v[222:223], v[96:97] op_sel:[1,0,0] op_sel_hi:[1,1,1]
	v_pk_fma_f32 v[96:97], v[78:79], v[224:225], v[96:97] op_sel_hi:[0,1,1]
	v_pk_fma_f32 v[96:97], v[78:79], v[226:227], v[96:97] op_sel:[1,0,0] op_sel_hi:[1,1,1]
	v_mul_f32_e64 v104, |v96|, s34
	v_mul_f32_e64 v105, |v97|, s34
	v_exp_f32_e32 v104, v104
	v_exp_f32_e32 v105, v105
	v_min_f32_e32 v106, 0, v96
	v_min_f32_e32 v107, 0, v97
	v_pk_add_f32 v[104:105], v[104:105], v[190:191]
	v_log_f32_e32 v104, v104
	v_log_f32_e32 v105, v105
	s_nop 0
	v_fma_f32 v106, v104, s35, v106
	v_fma_f32 v107, v105, s35, v107
	v_pk_fma_f32 v[192:193], v[106:107], v[188:189], v[192:193]
	ds_read_b128 v[64:67], v167 offset:2880
	ds_read_b128 v[68:71], v167 offset:2896
	ds_read_b128 v[72:75], v167 offset:2912
	ds_read_b128 v[76:79], v167 offset:2928
	v_pk_mul_f32 v[98:99], v[192:193], v[186:187]
	s_waitcnt vmcnt(48)
	v_lshlrev_b32_e32 v100, 16, v17
	v_exp_f32_e32 v98, v98
	v_exp_f32_e32 v99, v99
	v_and_b32_e32 v101, 0xffff0000, v17
	v_mov_b32_e32 v96, v198
	v_mov_b32_e32 v97, v199
	v_pk_mul_f32 v[102:103], v[100:101], v[98:99]
	s_waitcnt lgkmcnt(4)
	v_pk_fma_f32 v[96:97], v[80:81], v[232:233], v[96:97] op_sel_hi:[0,1,1]
	v_cvt_pk_bf16_f32 v108, v102, v103
	v_pk_fma_f32 v[96:97], v[80:81], v[234:235], v[96:97] op_sel:[1,0,0] op_sel_hi:[1,1,1]
	global_store_dword v166, v108, s[46:47]
	s_sub_u32 s46, s46, 0x3200
	s_subb_u32 s47, s47, 0
	global_load_dword v49, v166, s[30:31]
	s_sub_u32 s30, s30, 0x3200
	s_subb_u32 s31, s31, 0
	v_pk_fma_f32 v[96:97], v[82:83], v[236:237], v[96:97] op_sel_hi:[0,1,1]
	v_pk_fma_f32 v[96:97], v[82:83], v[238:239], v[96:97] op_sel:[1,0,0] op_sel_hi:[1,1,1]
	v_pk_fma_f32 v[96:97], v[84:85], v[240:241], v[96:97] op_sel_hi:[0,1,1]
	v_pk_fma_f32 v[96:97], v[84:85], v[242:243], v[96:97] op_sel:[1,0,0] op_sel_hi:[1,1,1]
	v_pk_fma_f32 v[96:97], v[86:87], v[244:245], v[96:97] op_sel_hi:[0,1,1]
	v_pk_fma_f32 v[96:97], v[86:87], v[246:247], v[96:97] op_sel:[1,0,0] op_sel_hi:[1,1,1]
	v_pk_fma_f32 v[96:97], v[88:89], v[248:249], v[96:97] op_sel_hi:[0,1,1]
	v_pk_fma_f32 v[96:97], v[88:89], v[250:251], v[96:97] op_sel:[1,0,0] op_sel_hi:[1,1,1]
	v_pk_fma_f32 v[96:97], v[90:91], v[252:253], v[96:97] op_sel_hi:[0,1,1]
	v_pk_fma_f32 v[96:97], v[90:91], v[254:255], v[96:97] op_sel:[1,0,0] op_sel_hi:[1,1,1]
	v_pk_fma_f32 v[96:97], v[92:93], v[220:221], v[96:97] op_sel_hi:[0,1,1]
	v_pk_fma_f32 v[96:97], v[92:93], v[222:223], v[96:97] op_sel:[1,0,0] op_sel_hi:[1,1,1]
	v_pk_fma_f32 v[96:97], v[94:95], v[224:225], v[96:97] op_sel_hi:[0,1,1]
	v_pk_fma_f32 v[96:97], v[94:95], v[226:227], v[96:97] op_sel:[1,0,0] op_sel_hi:[1,1,1]
	v_mul_f32_e64 v104, |v96|, s34
	v_mul_f32_e64 v105, |v97|, s34
	v_exp_f32_e32 v104, v104
	v_exp_f32_e32 v105, v105
	v_min_f32_e32 v106, 0, v96
	v_min_f32_e32 v107, 0, v97
	v_pk_add_f32 v[104:105], v[104:105], v[190:191]
	v_log_f32_e32 v104, v104
	v_log_f32_e32 v105, v105
	s_nop 0
	v_fma_f32 v106, v104, s35, v106
	v_fma_f32 v107, v105, s35, v107
	v_pk_fma_f32 v[192:193], v[106:107], v[188:189], v[192:193]
	ds_read_b128 v[80:83], v167 offset:2816
	ds_read_b128 v[84:87], v167 offset:2832
	ds_read_b128 v[88:91], v167 offset:2848
	ds_read_b128 v[92:95], v167 offset:2864
	v_pk_mul_f32 v[98:99], v[192:193], v[186:187]
	s_waitcnt vmcnt(49)
	v_lshlrev_b32_e32 v100, 16, v18
	v_exp_f32_e32 v98, v98
	v_exp_f32_e32 v99, v99
	v_and_b32_e32 v101, 0xffff0000, v18
	v_mov_b32_e32 v96, v198
	v_mov_b32_e32 v97, v199
	v_pk_mul_f32 v[102:103], v[100:101], v[98:99]
	s_waitcnt lgkmcnt(4)
; DI unsigned pk2(float a, float b) { f32x2 v = {a, b}; bf16v2_t r = __builtin_convertvector(v, bf16v2_t); return __builtin_bit_cast(unsigned, r); }
; DI void phase_gla_prep(const Params& p, LAS unsigned char* lds) {
;     ...
;             unsigned kw[16];
; #pragma unroll
;             for (int i = 0; i < 16; ++i) kw[i] = *(const unsigned*)(big + (tokb + tg * 16 + i) * 6400 + 1024 + ch0);
; #pragma unroll
;             for (int i = 15; i >= 0; --i) { const int tok = tg * 16 + i;
;                 float z0 = bs0, z1 = bs1;
; #pragma unroll
;                 for (int r = 0; r < 16; ++r) { const float lv = lrs[tok * 16 + r]; z0 += lv * wg0[r]; z1 += lv * wg1[r]; }
;                 *(unsigned*)(big + (tokb + tok) * 6400 + 1024 + ch0) = pk2(__uint_as_float(kw[i] << 16) * __expf(t0), __uint_as_float(kw[i] & 0xffff0000u) * __expf(t1));
;                 t0 += (fminf(z0, 0.f) - __logf(1.f + __expf(-fabsf(z0)))) * (1.f / 16.f); t1 += (fminf(z1, 0.f) - __logf(1.f + __expf(-fabsf(z1)))) * (1.f / 16.f);
	v_pk_fma_f32 v[96:97], v[64:65], v[232:233], v[96:97] op_sel_hi:[0,1,1]
	v_cvt_pk_bf16_f32 v108, v102, v103
	v_pk_fma_f32 v[96:97], v[64:65], v[234:235], v[96:97] op_sel:[1,0,0] op_sel_hi:[1,1,1]
	global_store_dword v166, v108, s[46:47]
	s_sub_u32 s46, s46, 0x3200
	s_subb_u32 s47, s47, 0
	global_load_dword v50, v166, s[30:31]
	s_sub_u32 s30, s30, 0x3200
	s_subb_u32 s31, s31, 0
	v_pk_fma_f32 v[96:97], v[66:67], v[236:237], v[96:97] op_sel_hi:[0,1,1]
	v_pk_fma_f32 v[96:97], v[66:67], v[238:239], v[96:97] op_sel:[1,0,0] op_sel_hi:[1,1,1]
	v_pk_fma_f32 v[96:97], v[68:69], v[240:241], v[96:97] op_sel_hi:[0,1,1]
	v_pk_fma_f32 v[96:97], v[68:69], v[242:243], v[96:97] op_sel:[1,0,0] op_sel_hi:[1,1,1]
	v_pk_fma_f32 v[96:97], v[70:71], v[244:245], v[96:97] op_sel_hi:[0,1,1]
	v_pk_fma_f32 v[96:97], v[70:71], v[246:247], v[96:97] op_sel:[1,0,0] op_sel_hi:[1,1,1]
	v_pk_fma_f32 v[96:97], v[72:73], v[248:249], v[96:97] op_sel_hi:[0,1,1]
	v_pk_fma_f32 v[96:97], v[72:73], v[250:251], v[96:97] op_sel:[1,0,0] op_sel_hi:[1,1,1]
	v_pk_fma_f32 v[96:97], v[74:75], v[252:253], v[96:97] op_sel_hi:[0,1,1]
	v_pk_fma_f32 v[96:97], v[74:75], v[254:255], v[96:97] op_sel:[1,0,0] op_sel_hi:[1,1,1]
	v_pk_fma_f32 v[96:97], v[76:77], v[220:221], v[96:97] op_sel_hi:[0,1,1]
	v_pk_fma_f32 v[96:97], v[76:77], v[222:223], v[96:97] op_sel:[1,0,0] op_sel_hi:[1,1,1]
	v_pk_fma_f32 v[96:97], v[78:79], v[224:225], v[96:97] op_sel_hi:[0,1,1]
	v_pk_fma_f32 v[96:97], v[78:79], v[226:227], v[96:97] op_sel:[1,0,0] op_sel_hi:[1,1,1]
	v_mul_f32_e64 v104, |v96|, s34
	v_mul_f32_e64 v105, |v97|, s34
	v_exp_f32_e32 v104, v104
	v_exp_f32_e32 v105, v105
	v_min_f32_e32 v106, 0, v96
	v_min_f32_e32 v107, 0, v97
	v_pk_add_f32 v[104:105], v[104:105], v[190:191]
	v_log_f32_e32 v104, v104
	v_log_f32_e32 v105, v105
	s_nop 0
	v_fma_f32 v106, v104, s35, v106
	v_fma_f32 v107, v105, s35, v107
	v_pk_fma_f32 v[192:193], v[106:107], v[188:189], v[192:193]
	ds_read_b128 v[64:67], v167 offset:2752
	ds_read_b128 v[68:71], v167 offset:2768
	ds_read_b128 v[72:75], v167 offset:2784
	ds_read_b128 v[76:79], v167 offset:2800
	v_pk_mul_f32 v[98:99], v[192:193], v[186:187]
	s_waitcnt vmcnt(50)
	v_lshlrev_b32_e32 v100, 16, v19
	v_exp_f32_e32 v98, v98
	v_exp_f32_e32 v99, v99
	v_and_b32_e32 v101, 0xffff0000, v19
	v_mov_b32_e32 v96, v198
	v_mov_b32_e32 v97, v199
	v_pk_mul_f32 v[102:103], v[100:101], v[98:99]
	s_waitcnt lgkmcnt(4)
	v_pk_fma_f32 v[96:97], v[80:81], v[232:233], v[96:97] op_sel_hi:[0,1,1]
	v_cvt_pk_bf16_f32 v108, v102, v103
	v_pk_fma_f32 v[96:97], v[80:81], v[234:235], v[96:97] op_sel:[1,0,0] op_sel_hi:[1,1,1]
	global_store_dword v166, v108, s[46:47]
	s_sub_u32 s46, s46, 0x3200
	s_subb_u32 s47, s47, 0
	global_load_dword v51, v166, s[30:31]
	s_sub_u32 s30, s30, 0x3200
	s_subb_u32 s31, s31, 0
	v_pk_fma_f32 v[96:97], v[82:83], v[236:237], v[96:97] op_sel_hi:[0,1,1]
	v_pk_fma_f32 v[96:97], v[82:83], v[238:239], v[96:97] op_sel:[1,0,0] op_sel_hi:[1,1,1]
	v_pk_fma_f32 v[96:97], v[84:85], v[240:241], v[96:97] op_sel_hi:[0,1,1]
	v_pk_fma_f32 v[96:97], v[84:85], v[242:243], v[96:97] op_sel:[1,0,0] op_sel_hi:[1,1,1]
	v_pk_fma_f32 v[96:97], v[86:87], v[244:245], v[96:97] op_sel_hi:[0,1,1]
	v_pk_fma_f32 v[96:97], v[86:87], v[246:247], v[96:97] op_sel:[1,0,0] op_sel_hi:[1,1,1]
	v_pk_fma_f32 v[96:97], v[88:89], v[248:249], v[96:97] op_sel_hi:[0,1,1]
	v_pk_fma_f32 v[96:97], v[88:89], v[250:251], v[96:97] op_sel:[1,0,0] op_sel_hi:[1,1,1]
	v_pk_fma_f32 v[96:97], v[90:91], v[252:253], v[96:97] op_sel_hi:[0,1,1]
	v_pk_fma_f32 v[96:97], v[90:91], v[254:255], v[96:97] op_sel:[1,0,0] op_sel_hi:[1,1,1]
	v_pk_fma_f32 v[96:97], v[92:93], v[220:221], v[96:97] op_sel_hi:[0,1,1]
	v_pk_fma_f32 v[96:97], v[92:93], v[222:223], v[96:97] op_sel:[1,0,0] op_sel_hi:[1,1,1]
	v_pk_fma_f32 v[96:97], v[94:95], v[224:225], v[96:97] op_sel_hi:[0,1,1]
	v_pk_fma_f32 v[96:97], v[94:95], v[226:227], v[96:97] op_sel:[1,0,0] op_sel_hi:[1,1,1]
	v_mul_f32_e64 v104, |v96|, s34
	v_mul_f32_e64 v105, |v97|, s34
	v_exp_f32_e32 v104, v104
	v_exp_f32_e32 v105, v105
	v_min_f32_e32 v106, 0, v96
	v_min_f32_e32 v107, 0, v97
	v_pk_add_f32 v[104:105], v[104:105], v[190:191]
	v_log_f32_e32 v104, v104
	v_log_f32_e32 v105, v105
	s_nop 0
	v_fma_f32 v106, v104, s35, v106
	v_fma_f32 v107, v105, s35, v107
	v_pk_fma_f32 v[192:193], v[106:107], v[188:189], v[192:193]
	ds_read_b128 v[80:83], v167 offset:2688
	ds_read_b128 v[84:87], v167 offset:2704
	ds_read_b128 v[88:91], v167 offset:2720
	ds_read_b128 v[92:95], v167 offset:2736
	v_pk_mul_f32 v[98:99], v[192:193], v[186:187]
	s_waitcnt vmcnt(51)
	v_lshlrev_b32_e32 v100, 16, v20
	v_exp_f32_e32 v98, v98
	v_exp_f32_e32 v99, v99
	v_and_b32_e32 v101, 0xffff0000, v20
	v_mov_b32_e32 v96, v198
	v_mov_b32_e32 v97, v199
	v_pk_mul_f32 v[102:103], v[100:101], v[98:99]
	s_waitcnt lgkmcnt(4)
; DI unsigned pk2(float a, float b) { f32x2 v = {a, b}; bf16v2_t r = __builtin_convertvector(v, bf16v2_t); return __builtin_bit_cast(unsigned, r); }
; DI void phase_gla_prep(const Params& p, LAS unsigned char* lds) {
;     ...
;             unsigned kw[16];
; #pragma unroll
;             for (int i = 0; i < 16; ++i) kw[i] = *(const unsigned*)(big + (tokb + tg * 16 + i) * 6400 + 1024 + ch0);
; #pragma unroll
;             for (int i = 15; i >= 0; --i) { const int tok = tg * 16 + i;
;                 float z0 = bs0, z1 = bs1;
; #pragma unroll
;                 for (int r = 0; r < 16; ++r) { const float lv = lrs[tok * 16 + r]; z0 += lv * wg0[r]; z1 += lv * wg1[r]; }
;                 *(unsigned*)(big + (tokb + tok) * 6400 + 1024 + ch0) = pk2(__uint_as_float(kw[i] << 16) * __expf(t0), __uint_as_float(kw[i] & 0xffff0000u) * __expf(t1));
;                 t0 += (fminf(z0, 0.f) - __logf(1.f + __expf(-fabsf(z0)))) * (1.f / 16.f); t1 += (fminf(z1, 0.f) - __logf(1.f + __expf(-fabsf(z1)))) * (1.f / 16.f);
	v_pk_fma_f32 v[96:97], v[64:65], v[232:233], v[96:97] op_sel_hi:[0,1,1]
	v_cvt_pk_bf16_f32 v108, v102, v103
	v_pk_fma_f32 v[96:97], v[64:65], v[234:235], v[96:97] op_sel:[1,0,0] op_sel_hi:[1,1,1]
	global_store_dword v166, v108, s[46:47]
	s_sub_u32 s46, s46, 0x3200
	s_subb_u32 s47, s47, 0
	global_load_dword v52, v166, s[30:31]
	s_sub_u32 s30, s30, 0x3200
	s_subb_u32 s31, s31, 0
	v_pk_fma_f32 v[96:97], v[66:67], v[236:237], v[96:97] op_sel_hi:[0,1,1]
	v_pk_fma_f32 v[96:97], v[66:67], v[238:239], v[96:97] op_sel:[1,0,0] op_sel_hi:[1,1,1]
	v_pk_fma_f32 v[96:97], v[68:69], v[240:241], v[96:97] op_sel_hi:[0,1,1]
	v_pk_fma_f32 v[96:97], v[68:69], v[242:243], v[96:97] op_sel:[1,0,0] op_sel_hi:[1,1,1]
	v_pk_fma_f32 v[96:97], v[70:71], v[244:245], v[96:97] op_sel_hi:[0,1,1]
	v_pk_fma_f32 v[96:97], v[70:71], v[246:247], v[96:97] op_sel:[1,0,0] op_sel_hi:[1,1,1]
	v_pk_fma_f32 v[96:97], v[72:73], v[248:249], v[96:97] op_sel_hi:[0,1,1]
	v_pk_fma_f32 v[96:97], v[72:73], v[250:251], v[96:97] op_sel:[1,0,0] op_sel_hi:[1,1,1]
	v_pk_fma_f32 v[96:97], v[74:75], v[252:253], v[96:97] op_sel_hi:[0,1,1]
	v_pk_fma_f32 v[96:97], v[74:75], v[254:255], v[96:97] op_sel:[1,0,0] op_sel_hi:[1,1,1]
	v_pk_fma_f32 v[96:97], v[76:77], v[220:221], v[96:97] op_sel_hi:[0,1,1]
	v_pk_fma_f32 v[96:97], v[76:77], v[222:223], v[96:97] op_sel:[1,0,0] op_sel_hi:[1,1,1]
	v_pk_fma_f32 v[96:97], v[78:79], v[224:225], v[96:97] op_sel_hi:[0,1,1]
	v_pk_fma_f32 v[96:97], v[78:79], v[226:227], v[96:97] op_sel:[1,0,0] op_sel_hi:[1,1,1]
	v_mul_f32_e64 v104, |v96|, s34
	v_mul_f32_e64 v105, |v97|, s34
	v_exp_f32_e32 v104, v104
	v_exp_f32_e32 v105, v105
	v_min_f32_e32 v106, 0, v96
	v_min_f32_e32 v107, 0, v97
	v_pk_add_f32 v[104:105], v[104:105], v[190:191]
	v_log_f32_e32 v104, v104
	v_log_f32_e32 v105, v105
	s_nop 0
	v_fma_f32 v106, v104, s35, v106
	v_fma_f32 v107, v105, s35, v107
	v_pk_fma_f32 v[192:193], v[106:107], v[188:189], v[192:193]
	ds_read_b128 v[64:67], v167 offset:2624
	ds_read_b128 v[68:71], v167 offset:2640
	ds_read_b128 v[72:75], v167 offset:2656
	ds_read_b128 v[76:79], v167 offset:2672
	v_pk_mul_f32 v[98:99], v[192:193], v[186:187]
	s_waitcnt vmcnt(52)
	v_lshlrev_b32_e32 v100, 16, v21
	v_exp_f32_e32 v98, v98
	v_exp_f32_e32 v99, v99
	v_and_b32_e32 v101, 0xffff0000, v21
	v_mov_b32_e32 v96, v198
	v_mov_b32_e32 v97, v199
	v_pk_mul_f32 v[102:103], v[100:101], v[98:99]
	s_waitcnt lgkmcnt(4)
	v_pk_fma_f32 v[96:97], v[80:81], v[232:233], v[96:97] op_sel_hi:[0,1,1]
	v_cvt_pk_bf16_f32 v108, v102, v103
	v_pk_fma_f32 v[96:97], v[80:81], v[234:235], v[96:97] op_sel:[1,0,0] op_sel_hi:[1,1,1]
	global_store_dword v166, v108, s[46:47]
	s_sub_u32 s46, s46, 0x3200
	s_subb_u32 s47, s47, 0
	global_load_dword v53, v166, s[30:31]
	s_sub_u32 s30, s30, 0x3200
	s_subb_u32 s31, s31, 0
	v_pk_fma_f32 v[96:97], v[82:83], v[236:237], v[96:97] op_sel_hi:[0,1,1]
	v_pk_fma_f32 v[96:97], v[82:83], v[238:239], v[96:97] op_sel:[1,0,0] op_sel_hi:[1,1,1]
	v_pk_fma_f32 v[96:97], v[84:85], v[240:241], v[96:97] op_sel_hi:[0,1,1]
	v_pk_fma_f32 v[96:97], v[84:85], v[242:243], v[96:97] op_sel:[1,0,0] op_sel_hi:[1,1,1]
	v_pk_fma_f32 v[96:97], v[86:87], v[244:245], v[96:97] op_sel_hi:[0,1,1]
	v_pk_fma_f32 v[96:97], v[86:87], v[246:247], v[96:97] op_sel:[1,0,0] op_sel_hi:[1,1,1]
	v_pk_fma_f32 v[96:97], v[88:89], v[248:249], v[96:97] op_sel_hi:[0,1,1]
	v_pk_fma_f32 v[96:97], v[88:89], v[250:251], v[96:97] op_sel:[1,0,0] op_sel_hi:[1,1,1]
	v_pk_fma_f32 v[96:97], v[90:91], v[252:253], v[96:97] op_sel_hi:[0,1,1]
	v_pk_fma_f32 v[96:97], v[90:91], v[254:255], v[96:97] op_sel:[1,0,0] op_sel_hi:[1,1,1]
	v_pk_fma_f32 v[96:97], v[92:93], v[220:221], v[96:97] op_sel_hi:[0,1,1]
	v_pk_fma_f32 v[96:97], v[92:93], v[222:223], v[96:97] op_sel:[1,0,0] op_sel_hi:[1,1,1]
	v_pk_fma_f32 v[96:97], v[94:95], v[224:225], v[96:97] op_sel_hi:[0,1,1]
	v_pk_fma_f32 v[96:97], v[94:95], v[226:227], v[96:97] op_sel:[1,0,0] op_sel_hi:[1,1,1]
	v_mul_f32_e64 v104, |v96|, s34
	v_mul_f32_e64 v105, |v97|, s34
	v_exp_f32_e32 v104, v104
	v_exp_f32_e32 v105, v105
	v_min_f32_e32 v106, 0, v96
	v_min_f32_e32 v107, 0, v97
	v_pk_add_f32 v[104:105], v[104:105], v[190:191]
	v_log_f32_e32 v104, v104
	v_log_f32_e32 v105, v105
	s_nop 0
	v_fma_f32 v106, v104, s35, v106
	v_fma_f32 v107, v105, s35, v107
	v_pk_fma_f32 v[192:193], v[106:107], v[188:189], v[192:193]
	ds_read_b128 v[80:83], v167 offset:2560
	ds_read_b128 v[84:87], v167 offset:2576
	ds_read_b128 v[88:91], v167 offset:2592
	ds_read_b128 v[92:95], v167 offset:2608
	v_pk_mul_f32 v[98:99], v[192:193], v[186:187]
	s_waitcnt vmcnt(53)
	v_lshlrev_b32_e32 v100, 16, v22
	v_exp_f32_e32 v98, v98
	v_exp_f32_e32 v99, v99
	v_and_b32_e32 v101, 0xffff0000, v22
	v_mov_b32_e32 v96, v198
	v_mov_b32_e32 v97, v199
	v_pk_mul_f32 v[102:103], v[100:101], v[98:99]
	s_waitcnt lgkmcnt(4)
; DI unsigned pk2(float a, float b) { f32x2 v = {a, b}; bf16v2_t r = __builtin_convertvector(v, bf16v2_t); return __builtin_bit_cast(unsigned, r); }
; DI void phase_gla_prep(const Params& p, LAS unsigned char* lds) {
;     ...
;             unsigned kw[16];
; #pragma unroll
;             for (int i = 0; i < 16; ++i) kw[i] = *(const unsigned*)(big + (tokb + tg * 16 + i) * 6400 + 1024 + ch0);
; #pragma unroll
;             for (int i = 15; i >= 0; --i) { const int tok = tg * 16 + i;
;                 float z0 = bs0, z1 = bs1;
; #pragma unroll
;                 for (int r = 0; r < 16; ++r) { const float lv = lrs[tok * 16 + r]; z0 += lv * wg0[r]; z1 += lv * wg1[r]; }
;                 *(unsigned*)(big + (tokb + tok) * 6400 + 1024 + ch0) = pk2(__uint_as_float(kw[i] << 16) * __expf(t0), __uint_as_float(kw[i] & 0xffff0000u) * __expf(t1));
;                 t0 += (fminf(z0, 0.f) - __logf(1.f + __expf(-fabsf(z0)))) * (1.f / 16.f); t1 += (fminf(z1, 0.f) - __logf(1.f + __expf(-fabsf(z1)))) * (1.f / 16.f);
	v_pk_fma_f32 v[96:97], v[64:65], v[232:233], v[96:97] op_sel_hi:[0,1,1]
	v_cvt_pk_bf16_f32 v108, v102, v103
	v_pk_fma_f32 v[96:97], v[64:65], v[234:235], v[96:97] op_sel:[1,0,0] op_sel_hi:[1,1,1]
	global_store_dword v166, v108, s[46:47]
	s_sub_u32 s46, s46, 0x3200
	s_subb_u32 s47, s47, 0
	global_load_dword v54, v166, s[30:31]
	s_sub_u32 s30, s30, 0x3200
	s_subb_u32 s31, s31, 0
	v_pk_fma_f32 v[96:97], v[66:67], v[236:237], v[96:97] op_sel_hi:[0,1,1]
	v_pk_fma_f32 v[96:97], v[66:67], v[238:239], v[96:97] op_sel:[1,0,0] op_sel_hi:[1,1,1]
	v_pk_fma_f32 v[96:97], v[68:69], v[240:241], v[96:97] op_sel_hi:[0,1,1]
	v_pk_fma_f32 v[96:97], v[68:69], v[242:243], v[96:97] op_sel:[1,0,0] op_sel_hi:[1,1,1]
	v_pk_fma_f32 v[96:97], v[70:71], v[244:245], v[96:97] op_sel_hi:[0,1,1]
	v_pk_fma_f32 v[96:97], v[70:71], v[246:247], v[96:97] op_sel:[1,0,0] op_sel_hi:[1,1,1]
	v_pk_fma_f32 v[96:97], v[72:73], v[248:249], v[96:97] op_sel_hi:[0,1,1]
	v_pk_fma_f32 v[96:97], v[72:73], v[250:251], v[96:97] op_sel:[1,0,0] op_sel_hi:[1,1,1]
	v_pk_fma_f32 v[96:97], v[74:75], v[252:253], v[96:97] op_sel_hi:[0,1,1]
	v_pk_fma_f32 v[96:97], v[74:75], v[254:255], v[96:97] op_sel:[1,0,0] op_sel_hi:[1,1,1]
	v_pk_fma_f32 v[96:97], v[76:77], v[220:221], v[96:97] op_sel_hi:[0,1,1]
	v_pk_fma_f32 v[96:97], v[76:77], v[222:223], v[96:97] op_sel:[1,0,0] op_sel_hi:[1,1,1]
	v_pk_fma_f32 v[96:97], v[78:79], v[224:225], v[96:97] op_sel_hi:[0,1,1]
	v_pk_fma_f32 v[96:97], v[78:79], v[226:227], v[96:97] op_sel:[1,0,0] op_sel_hi:[1,1,1]
	v_mul_f32_e64 v104, |v96|, s34
	v_mul_f32_e64 v105, |v97|, s34
	v_exp_f32_e32 v104, v104
	v_exp_f32_e32 v105, v105
	v_min_f32_e32 v106, 0, v96
	v_min_f32_e32 v107, 0, v97
	v_pk_add_f32 v[104:105], v[104:105], v[190:191]
	v_log_f32_e32 v104, v104
	v_log_f32_e32 v105, v105
	s_nop 0
	v_fma_f32 v106, v104, s35, v106
	v_fma_f32 v107, v105, s35, v107
	v_pk_fma_f32 v[192:193], v[106:107], v[188:189], v[192:193]
	ds_read_b128 v[64:67], v167 offset:2496
	ds_read_b128 v[68:71], v167 offset:2512
	ds_read_b128 v[72:75], v167 offset:2528
	ds_read_b128 v[76:79], v167 offset:2544
	v_pk_mul_f32 v[98:99], v[192:193], v[186:187]
	s_waitcnt vmcnt(54)
	v_lshlrev_b32_e32 v100, 16, v23
	v_exp_f32_e32 v98, v98
	v_exp_f32_e32 v99, v99
	v_and_b32_e32 v101, 0xffff0000, v23
	v_mov_b32_e32 v96, v198
	v_mov_b32_e32 v97, v199
	v_pk_mul_f32 v[102:103], v[100:101], v[98:99]
	s_waitcnt lgkmcnt(4)
	v_pk_fma_f32 v[96:97], v[80:81], v[232:233], v[96:97] op_sel_hi:[0,1,1]
	v_cvt_pk_bf16_f32 v108, v102, v103
	v_pk_fma_f32 v[96:97], v[80:81], v[234:235], v[96:97] op_sel:[1,0,0] op_sel_hi:[1,1,1]
	global_store_dword v166, v108, s[46:47]
	s_sub_u32 s46, s46, 0x3200
	s_subb_u32 s47, s47, 0
	global_load_dword v55, v166, s[30:31]
	s_sub_u32 s30, s30, 0x3200
	s_subb_u32 s31, s31, 0
	v_pk_fma_f32 v[96:97], v[82:83], v[236:237], v[96:97] op_sel_hi:[0,1,1]
	v_pk_fma_f32 v[96:97], v[82:83], v[238:239], v[96:97] op_sel:[1,0,0] op_sel_hi:[1,1,1]
	v_pk_fma_f32 v[96:97], v[84:85], v[240:241], v[96:97] op_sel_hi:[0,1,1]
	v_pk_fma_f32 v[96:97], v[84:85], v[242:243], v[96:97] op_sel:[1,0,0] op_sel_hi:[1,1,1]
	v_pk_fma_f32 v[96:97], v[86:87], v[244:245], v[96:97] op_sel_hi:[0,1,1]
	v_pk_fma_f32 v[96:97], v[86:87], v[246:247], v[96:97] op_sel:[1,0,0] op_sel_hi:[1,1,1]
	v_pk_fma_f32 v[96:97], v[88:89], v[248:249], v[96:97] op_sel_hi:[0,1,1]
	v_pk_fma_f32 v[96:97], v[88:89], v[250:251], v[96:97] op_sel:[1,0,0] op_sel_hi:[1,1,1]
	v_pk_fma_f32 v[96:97], v[90:91], v[252:253], v[96:97] op_sel_hi:[0,1,1]
	v_pk_fma_f32 v[96:97], v[90:91], v[254:255], v[96:97] op_sel:[1,0,0] op_sel_hi:[1,1,1]
	v_pk_fma_f32 v[96:97], v[92:93], v[220:221], v[96:97] op_sel_hi:[0,1,1]
	v_pk_fma_f32 v[96:97], v[92:93], v[222:223], v[96:97] op_sel:[1,0,0] op_sel_hi:[1,1,1]
	v_pk_fma_f32 v[96:97], v[94:95], v[224:225], v[96:97] op_sel_hi:[0,1,1]
	v_pk_fma_f32 v[96:97], v[94:95], v[226:227], v[96:97] op_sel:[1,0,0] op_sel_hi:[1,1,1]
	v_mul_f32_e64 v104, |v96|, s34
	v_mul_f32_e64 v105, |v97|, s34
	v_exp_f32_e32 v104, v104
	v_exp_f32_e32 v105, v105
	v_min_f32_e32 v106, 0, v96
	v_min_f32_e32 v107, 0, v97
	v_pk_add_f32 v[104:105], v[104:105], v[190:191]
	v_log_f32_e32 v104, v104
	v_log_f32_e32 v105, v105
	s_nop 0
	v_fma_f32 v106, v104, s35, v106
	v_fma_f32 v107, v105, s35, v107
	v_pk_fma_f32 v[192:193], v[106:107], v[188:189], v[192:193]
	ds_read_b128 v[80:83], v167 offset:2432
	ds_read_b128 v[84:87], v167 offset:2448
	ds_read_b128 v[88:91], v167 offset:2464
	ds_read_b128 v[92:95], v167 offset:2480
	v_pk_mul_f32 v[98:99], v[192:193], v[186:187]
	s_waitcnt vmcnt(55)
	v_lshlrev_b32_e32 v100, 16, v24
	v_exp_f32_e32 v98, v98
	v_exp_f32_e32 v99, v99
	v_and_b32_e32 v101, 0xffff0000, v24
	v_mov_b32_e32 v96, v198
	v_mov_b32_e32 v97, v199
	v_pk_mul_f32 v[102:103], v[100:101], v[98:99]
	s_waitcnt lgkmcnt(4)
; DI unsigned pk2(float a, float b) { f32x2 v = {a, b}; bf16v2_t r = __builtin_convertvector(v, bf16v2_t); return __builtin_bit_cast(unsigned, r); }
; DI void phase_gla_prep(const Params& p, LAS unsigned char* lds) {
;     ...
;             unsigned kw[16];
; #pragma unroll
;             for (int i = 0; i < 16; ++i) kw[i] = *(const unsigned*)(big + (tokb + tg * 16 + i) * 6400 + 1024 + ch0);
; #pragma unroll
;             for (int i = 15; i >= 0; --i) { const int tok = tg * 16 + i;
;                 float z0 = bs0, z1 = bs1;
; #pragma unroll
;                 for (int r = 0; r < 16; ++r) { const float lv = lrs[tok * 16 + r]; z0 += lv * wg0[r]; z1 += lv * wg1[r]; }
;                 *(unsigned*)(big + (tokb + tok) * 6400 + 1024 + ch0) = pk2(__uint_as_float(kw[i] << 16) * __expf(t0), __uint_as_float(kw[i] & 0xffff0000u) * __expf(t1));
;                 t0 += (fminf(z0, 0.f) - __logf(1.f + __expf(-fabsf(z0)))) * (1.f / 16.f); t1 += (fminf(z1, 0.f) - __logf(1.f + __expf(-fabsf(z1)))) * (1.f / 16.f);
	v_pk_fma_f32 v[96:97], v[64:65], v[232:233], v[96:97] op_sel_hi:[0,1,1]
	v_cvt_pk_bf16_f32 v108, v102, v103
	v_pk_fma_f32 v[96:97], v[64:65], v[234:235], v[96:97] op_sel:[1,0,0] op_sel_hi:[1,1,1]
	global_store_dword v166, v108, s[46:47]
	s_sub_u32 s46, s46, 0x3200
	s_subb_u32 s47, s47, 0
	global_load_dword v56, v166, s[30:31]
	s_sub_u32 s30, s30, 0x3200
	s_subb_u32 s31, s31, 0
	v_pk_fma_f32 v[96:97], v[66:67], v[236:237], v[96:97] op_sel_hi:[0,1,1]
	v_pk_fma_f32 v[96:97], v[66:67], v[238:239], v[96:97] op_sel:[1,0,0] op_sel_hi:[1,1,1]
	v_pk_fma_f32 v[96:97], v[68:69], v[240:241], v[96:97] op_sel_hi:[0,1,1]
	v_pk_fma_f32 v[96:97], v[68:69], v[242:243], v[96:97] op_sel:[1,0,0] op_sel_hi:[1,1,1]
	v_pk_fma_f32 v[96:97], v[70:71], v[244:245], v[96:97] op_sel_hi:[0,1,1]
	v_pk_fma_f32 v[96:97], v[70:71], v[246:247], v[96:97] op_sel:[1,0,0] op_sel_hi:[1,1,1]
	v_pk_fma_f32 v[96:97], v[72:73], v[248:249], v[96:97] op_sel_hi:[0,1,1]
	v_pk_fma_f32 v[96:97], v[72:73], v[250:251], v[96:97] op_sel:[1,0,0] op_sel_hi:[1,1,1]
	v_pk_fma_f32 v[96:97], v[74:75], v[252:253], v[96:97] op_sel_hi:[0,1,1]
	v_pk_fma_f32 v[96:97], v[74:75], v[254:255], v[96:97] op_sel:[1,0,0] op_sel_hi:[1,1,1]
	v_pk_fma_f32 v[96:97], v[76:77], v[220:221], v[96:97] op_sel_hi:[0,1,1]
	v_pk_fma_f32 v[96:97], v[76:77], v[222:223], v[96:97] op_sel:[1,0,0] op_sel_hi:[1,1,1]
	v_pk_fma_f32 v[96:97], v[78:79], v[224:225], v[96:97] op_sel_hi:[0,1,1]
	v_pk_fma_f32 v[96:97], v[78:79], v[226:227], v[96:97] op_sel:[1,0,0] op_sel_hi:[1,1,1]
	v_mul_f32_e64 v104, |v96|, s34
	v_mul_f32_e64 v105, |v97|, s34
	v_exp_f32_e32 v104, v104
	v_exp_f32_e32 v105, v105
	v_min_f32_e32 v106, 0, v96
	v_min_f32_e32 v107, 0, v97
	v_pk_add_f32 v[104:105], v[104:105], v[190:191]
	v_log_f32_e32 v104, v104
	v_log_f32_e32 v105, v105
	s_nop 0
	v_fma_f32 v106, v104, s35, v106
	v_fma_f32 v107, v105, s35, v107
	v_pk_fma_f32 v[192:193], v[106:107], v[188:189], v[192:193]
	ds_read_b128 v[64:67], v167 offset:2368
	ds_read_b128 v[68:71], v167 offset:2384
	ds_read_b128 v[72:75], v167 offset:2400
	ds_read_b128 v[76:79], v167 offset:2416
	v_pk_mul_f32 v[98:99], v[192:193], v[186:187]
	s_waitcnt vmcnt(56)
	v_lshlrev_b32_e32 v100, 16, v25
	v_exp_f32_e32 v98, v98
	v_exp_f32_e32 v99, v99
	v_and_b32_e32 v101, 0xffff0000, v25
	v_mov_b32_e32 v96, v198
	v_mov_b32_e32 v97, v199
	v_pk_mul_f32 v[102:103], v[100:101], v[98:99]
	s_waitcnt lgkmcnt(4)
	v_pk_fma_f32 v[96:97], v[80:81], v[232:233], v[96:97] op_sel_hi:[0,1,1]
	v_cvt_pk_bf16_f32 v108, v102, v103
	v_pk_fma_f32 v[96:97], v[80:81], v[234:235], v[96:97] op_sel:[1,0,0] op_sel_hi:[1,1,1]
	global_store_dword v166, v108, s[46:47]
	s_sub_u32 s46, s46, 0x3200
	s_subb_u32 s47, s47, 0
	global_load_dword v57, v166, s[30:31]
	s_sub_u32 s30, s30, 0x3200
	s_subb_u32 s31, s31, 0
	v_pk_fma_f32 v[96:97], v[82:83], v[236:237], v[96:97] op_sel_hi:[0,1,1]
	v_pk_fma_f32 v[96:97], v[82:83], v[238:239], v[96:97] op_sel:[1,0,0] op_sel_hi:[1,1,1]
	v_pk_fma_f32 v[96:97], v[84:85], v[240:241], v[96:97] op_sel_hi:[0,1,1]
	v_pk_fma_f32 v[96:97], v[84:85], v[242:243], v[96:97] op_sel:[1,0,0] op_sel_hi:[1,1,1]
	v_pk_fma_f32 v[96:97], v[86:87], v[244:245], v[96:97] op_sel_hi:[0,1,1]
	v_pk_fma_f32 v[96:97], v[86:87], v[246:247], v[96:97] op_sel:[1,0,0] op_sel_hi:[1,1,1]
	v_pk_fma_f32 v[96:97], v[88:89], v[248:249], v[96:97] op_sel_hi:[0,1,1]
	v_pk_fma_f32 v[96:97], v[88:89], v[250:251], v[96:97] op_sel:[1,0,0] op_sel_hi:[1,1,1]
	v_pk_fma_f32 v[96:97], v[90:91], v[252:253], v[96:97] op_sel_hi:[0,1,1]
	v_pk_fma_f32 v[96:97], v[90:91], v[254:255], v[96:97] op_sel:[1,0,0] op_sel_hi:[1,1,1]
	v_pk_fma_f32 v[96:97], v[92:93], v[220:221], v[96:97] op_sel_hi:[0,1,1]
	v_pk_fma_f32 v[96:97], v[92:93], v[222:223], v[96:97] op_sel:[1,0,0] op_sel_hi:[1,1,1]
	v_pk_fma_f32 v[96:97], v[94:95], v[224:225], v[96:97] op_sel_hi:[0,1,1]
	v_pk_fma_f32 v[96:97], v[94:95], v[226:227], v[96:97] op_sel:[1,0,0] op_sel_hi:[1,1,1]
	v_mul_f32_e64 v104, |v96|, s34
	v_mul_f32_e64 v105, |v97|, s34
	v_exp_f32_e32 v104, v104
	v_exp_f32_e32 v105, v105
	v_min_f32_e32 v106, 0, v96
	v_min_f32_e32 v107, 0, v97
	v_pk_add_f32 v[104:105], v[104:105], v[190:191]
	v_log_f32_e32 v104, v104
	v_log_f32_e32 v105, v105
	s_nop 0
	v_fma_f32 v106, v104, s35, v106
	v_fma_f32 v107, v105, s35, v107
	v_pk_fma_f32 v[192:193], v[106:107], v[188:189], v[192:193]
	ds_read_b128 v[80:83], v167 offset:2304
	ds_read_b128 v[84:87], v167 offset:2320
	ds_read_b128 v[88:91], v167 offset:2336
	ds_read_b128 v[92:95], v167 offset:2352
	v_pk_mul_f32 v[98:99], v[192:193], v[186:187]
	s_waitcnt vmcnt(57)
	v_lshlrev_b32_e32 v100, 16, v26
	v_exp_f32_e32 v98, v98
	v_exp_f32_e32 v99, v99
	v_and_b32_e32 v101, 0xffff0000, v26
	v_mov_b32_e32 v96, v198
	v_mov_b32_e32 v97, v199
	v_pk_mul_f32 v[102:103], v[100:101], v[98:99]
	s_waitcnt lgkmcnt(4)
; DI unsigned pk2(float a, float b) { f32x2 v = {a, b}; bf16v2_t r = __builtin_convertvector(v, bf16v2_t); return __builtin_bit_cast(unsigned, r); }
; DI void phase_gla_prep(const Params& p, LAS unsigned char* lds) {
;     ...
;             unsigned kw[16];
; #pragma unroll
;             for (int i = 0; i < 16; ++i) kw[i] = *(const unsigned*)(big + (tokb + tg * 16 + i) * 6400 + 1024 + ch0);
; #pragma unroll
;             for (int i = 15; i >= 0; --i) { const int tok = tg * 16 + i;
;                 float z0 = bs0, z1 = bs1;
; #pragma unroll
;                 for (int r = 0; r < 16; ++r) { const float lv = lrs[tok * 16 + r]; z0 += lv * wg0[r]; z1 += lv * wg1[r]; }
;                 *(unsigned*)(big + (tokb + tok) * 6400 + 1024 + ch0) = pk2(__uint_as_float(kw[i] << 16) * __expf(t0), __uint_as_float(kw[i] & 0xffff0000u) * __expf(t1));
;                 t0 += (fminf(z0, 0.f) - __logf(1.f + __expf(-fabsf(z0)))) * (1.f / 16.f); t1 += (fminf(z1, 0.f) - __logf(1.f + __expf(-fabsf(z1)))) * (1.f / 16.f);
	v_pk_fma_f32 v[96:97], v[64:65], v[232:233], v[96:97] op_sel_hi:[0,1,1]
	v_cvt_pk_bf16_f32 v108, v102, v103
	v_pk_fma_f32 v[96:97], v[64:65], v[234:235], v[96:97] op_sel:[1,0,0] op_sel_hi:[1,1,1]
	global_store_dword v166, v108, s[46:47]
	s_sub_u32 s46, s46, 0x3200
	s_subb_u32 s47, s47, 0
	global_load_dword v58, v166, s[30:31]
	s_sub_u32 s30, s30, 0x3200
	s_subb_u32 s31, s31, 0
	v_pk_fma_f32 v[96:97], v[66:67], v[236:237], v[96:97] op_sel_hi:[0,1,1]
	v_pk_fma_f32 v[96:97], v[66:67], v[238:239], v[96:97] op_sel:[1,0,0] op_sel_hi:[1,1,1]
	v_pk_fma_f32 v[96:97], v[68:69], v[240:241], v[96:97] op_sel_hi:[0,1,1]
	v_pk_fma_f32 v[96:97], v[68:69], v[242:243], v[96:97] op_sel:[1,0,0] op_sel_hi:[1,1,1]
	v_pk_fma_f32 v[96:97], v[70:71], v[244:245], v[96:97] op_sel_hi:[0,1,1]
	v_pk_fma_f32 v[96:97], v[70:71], v[246:247], v[96:97] op_sel:[1,0,0] op_sel_hi:[1,1,1]
	v_pk_fma_f32 v[96:97], v[72:73], v[248:249], v[96:97] op_sel_hi:[0,1,1]
	v_pk_fma_f32 v[96:97], v[72:73], v[250:251], v[96:97] op_sel:[1,0,0] op_sel_hi:[1,1,1]
	v_pk_fma_f32 v[96:97], v[74:75], v[252:253], v[96:97] op_sel_hi:[0,1,1]
	v_pk_fma_f32 v[96:97], v[74:75], v[254:255], v[96:97] op_sel:[1,0,0] op_sel_hi:[1,1,1]
	v_pk_fma_f32 v[96:97], v[76:77], v[220:221], v[96:97] op_sel_hi:[0,1,1]
	v_pk_fma_f32 v[96:97], v[76:77], v[222:223], v[96:97] op_sel:[1,0,0] op_sel_hi:[1,1,1]
	v_pk_fma_f32 v[96:97], v[78:79], v[224:225], v[96:97] op_sel_hi:[0,1,1]
	v_pk_fma_f32 v[96:97], v[78:79], v[226:227], v[96:97] op_sel:[1,0,0] op_sel_hi:[1,1,1]
	v_mul_f32_e64 v104, |v96|, s34
	v_mul_f32_e64 v105, |v97|, s34
	v_exp_f32_e32 v104, v104
	v_exp_f32_e32 v105, v105
	v_min_f32_e32 v106, 0, v96
	v_min_f32_e32 v107, 0, v97
	v_pk_add_f32 v[104:105], v[104:105], v[190:191]
	v_log_f32_e32 v104, v104
	v_log_f32_e32 v105, v105
	s_nop 0
	v_fma_f32 v106, v104, s35, v106
	v_fma_f32 v107, v105, s35, v107
	v_pk_fma_f32 v[192:193], v[106:107], v[188:189], v[192:193]
	ds_read_b128 v[64:67], v167 offset:2240
	ds_read_b128 v[68:71], v167 offset:2256
	ds_read_b128 v[72:75], v167 offset:2272
	ds_read_b128 v[76:79], v167 offset:2288
	v_pk_mul_f32 v[98:99], v[192:193], v[186:187]
	s_waitcnt vmcnt(58)
	v_lshlrev_b32_e32 v100, 16, v27
	v_exp_f32_e32 v98, v98
	v_exp_f32_e32 v99, v99
	v_and_b32_e32 v101, 0xffff0000, v27
	v_mov_b32_e32 v96, v198
	v_mov_b32_e32 v97, v199
	v_pk_mul_f32 v[102:103], v[100:101], v[98:99]
	s_waitcnt lgkmcnt(4)
	v_pk_fma_f32 v[96:97], v[80:81], v[232:233], v[96:97] op_sel_hi:[0,1,1]
	v_cvt_pk_bf16_f32 v108, v102, v103
	v_pk_fma_f32 v[96:97], v[80:81], v[234:235], v[96:97] op_sel:[1,0,0] op_sel_hi:[1,1,1]
	global_store_dword v166, v108, s[46:47]
	s_sub_u32 s46, s46, 0x3200
	s_subb_u32 s47, s47, 0
	global_load_dword v59, v166, s[30:31]
	s_sub_u32 s30, s30, 0x3200
	s_subb_u32 s31, s31, 0
	v_pk_fma_f32 v[96:97], v[82:83], v[236:237], v[96:97] op_sel_hi:[0,1,1]
	v_pk_fma_f32 v[96:97], v[82:83], v[238:239], v[96:97] op_sel:[1,0,0] op_sel_hi:[1,1,1]
	v_pk_fma_f32 v[96:97], v[84:85], v[240:241], v[96:97] op_sel_hi:[0,1,1]
	v_pk_fma_f32 v[96:97], v[84:85], v[242:243], v[96:97] op_sel:[1,0,0] op_sel_hi:[1,1,1]
	v_pk_fma_f32 v[96:97], v[86:87], v[244:245], v[96:97] op_sel_hi:[0,1,1]
	v_pk_fma_f32 v[96:97], v[86:87], v[246:247], v[96:97] op_sel:[1,0,0] op_sel_hi:[1,1,1]
	v_pk_fma_f32 v[96:97], v[88:89], v[248:249], v[96:97] op_sel_hi:[0,1,1]
	v_pk_fma_f32 v[96:97], v[88:89], v[250:251], v[96:97] op_sel:[1,0,0] op_sel_hi:[1,1,1]
	v_pk_fma_f32 v[96:97], v[90:91], v[252:253], v[96:97] op_sel_hi:[0,1,1]
	v_pk_fma_f32 v[96:97], v[90:91], v[254:255], v[96:97] op_sel:[1,0,0] op_sel_hi:[1,1,1]
	v_pk_fma_f32 v[96:97], v[92:93], v[220:221], v[96:97] op_sel_hi:[0,1,1]
	v_pk_fma_f32 v[96:97], v[92:93], v[222:223], v[96:97] op_sel:[1,0,0] op_sel_hi:[1,1,1]
	v_pk_fma_f32 v[96:97], v[94:95], v[224:225], v[96:97] op_sel_hi:[0,1,1]
	v_pk_fma_f32 v[96:97], v[94:95], v[226:227], v[96:97] op_sel:[1,0,0] op_sel_hi:[1,1,1]
	v_mul_f32_e64 v104, |v96|, s34
	v_mul_f32_e64 v105, |v97|, s34
	v_exp_f32_e32 v104, v104
	v_exp_f32_e32 v105, v105
	v_min_f32_e32 v106, 0, v96
	v_min_f32_e32 v107, 0, v97
	v_pk_add_f32 v[104:105], v[104:105], v[190:191]
	v_log_f32_e32 v104, v104
	v_log_f32_e32 v105, v105
	s_nop 0
	v_fma_f32 v106, v104, s35, v106
	v_fma_f32 v107, v105, s35, v107
	v_pk_fma_f32 v[192:193], v[106:107], v[188:189], v[192:193]
	ds_read_b128 v[80:83], v167 offset:2176
	ds_read_b128 v[84:87], v167 offset:2192
	ds_read_b128 v[88:91], v167 offset:2208
	ds_read_b128 v[92:95], v167 offset:2224
	v_pk_mul_f32 v[98:99], v[192:193], v[186:187]
	s_waitcnt vmcnt(59)
	v_lshlrev_b32_e32 v100, 16, v28
	v_exp_f32_e32 v98, v98
	v_exp_f32_e32 v99, v99
	v_and_b32_e32 v101, 0xffff0000, v28
	v_mov_b32_e32 v96, v198
	v_mov_b32_e32 v97, v199
	v_pk_mul_f32 v[102:103], v[100:101], v[98:99]
	s_waitcnt lgkmcnt(4)
; DI unsigned pk2(float a, float b) { f32x2 v = {a, b}; bf16v2_t r = __builtin_convertvector(v, bf16v2_t); return __builtin_bit_cast(unsigned, r); }
; DI void phase_gla_prep(const Params& p, LAS unsigned char* lds) {
;     ...
;             unsigned kw[16];
; #pragma unroll
;             for (int i = 0; i < 16; ++i) kw[i] = *(const unsigned*)(big + (tokb + tg * 16 + i) * 6400 + 1024 + ch0);
; #pragma unroll
;             for (int i = 15; i >= 0; --i) { const int tok = tg * 16 + i;
;                 float z0 = bs0, z1 = bs1;
; #pragma unroll
;                 for (int r = 0; r < 16; ++r) { const float lv = lrs[tok * 16 + r]; z0 += lv * wg0[r]; z1 += lv * wg1[r]; }
;                 *(unsigned*)(big + (tokb + tok) * 6400 + 1024 + ch0) = pk2(__uint_as_float(kw[i] << 16) * __expf(t0), __uint_as_float(kw[i] & 0xffff0000u) * __expf(t1));
;                 t0 += (fminf(z0, 0.f) - __logf(1.f + __expf(-fabsf(z0)))) * (1.f / 16.f); t1 += (fminf(z1, 0.f) - __logf(1.f + __expf(-fabsf(z1)))) * (1.f / 16.f);
	v_pk_fma_f32 v[96:97], v[64:65], v[232:233], v[96:97] op_sel_hi:[0,1,1]
	v_cvt_pk_bf16_f32 v108, v102, v103
	v_pk_fma_f32 v[96:97], v[64:65], v[234:235], v[96:97] op_sel:[1,0,0] op_sel_hi:[1,1,1]
	global_store_dword v166, v108, s[46:47]
	s_sub_u32 s46, s46, 0x3200
	s_subb_u32 s47, s47, 0
	global_load_dword v60, v166, s[30:31]
	s_sub_u32 s30, s30, 0x3200
	s_subb_u32 s31, s31, 0
	v_pk_fma_f32 v[96:97], v[66:67], v[236:237], v[96:97] op_sel_hi:[0,1,1]
	v_pk_fma_f32 v[96:97], v[66:67], v[238:239], v[96:97] op_sel:[1,0,0] op_sel_hi:[1,1,1]
	v_pk_fma_f32 v[96:97], v[68:69], v[240:241], v[96:97] op_sel_hi:[0,1,1]
	v_pk_fma_f32 v[96:97], v[68:69], v[242:243], v[96:97] op_sel:[1,0,0] op_sel_hi:[1,1,1]
	v_pk_fma_f32 v[96:97], v[70:71], v[244:245], v[96:97] op_sel_hi:[0,1,1]
	v_pk_fma_f32 v[96:97], v[70:71], v[246:247], v[96:97] op_sel:[1,0,0] op_sel_hi:[1,1,1]
	v_pk_fma_f32 v[96:97], v[72:73], v[248:249], v[96:97] op_sel_hi:[0,1,1]
	v_pk_fma_f32 v[96:97], v[72:73], v[250:251], v[96:97] op_sel:[1,0,0] op_sel_hi:[1,1,1]
	v_pk_fma_f32 v[96:97], v[74:75], v[252:253], v[96:97] op_sel_hi:[0,1,1]
	v_pk_fma_f32 v[96:97], v[74:75], v[254:255], v[96:97] op_sel:[1,0,0] op_sel_hi:[1,1,1]
	v_pk_fma_f32 v[96:97], v[76:77], v[220:221], v[96:97] op_sel_hi:[0,1,1]
	v_pk_fma_f32 v[96:97], v[76:77], v[222:223], v[96:97] op_sel:[1,0,0] op_sel_hi:[1,1,1]
	v_pk_fma_f32 v[96:97], v[78:79], v[224:225], v[96:97] op_sel_hi:[0,1,1]
	v_pk_fma_f32 v[96:97], v[78:79], v[226:227], v[96:97] op_sel:[1,0,0] op_sel_hi:[1,1,1]
	v_mul_f32_e64 v104, |v96|, s34
	v_mul_f32_e64 v105, |v97|, s34
	v_exp_f32_e32 v104, v104
	v_exp_f32_e32 v105, v105
	v_min_f32_e32 v106, 0, v96
	v_min_f32_e32 v107, 0, v97
	v_pk_add_f32 v[104:105], v[104:105], v[190:191]
	v_log_f32_e32 v104, v104
	v_log_f32_e32 v105, v105
	s_nop 0
	v_fma_f32 v106, v104, s35, v106
	v_fma_f32 v107, v105, s35, v107
	v_pk_fma_f32 v[192:193], v[106:107], v[188:189], v[192:193]
	ds_read_b128 v[64:67], v167 offset:2112
	ds_read_b128 v[68:71], v167 offset:2128
	ds_read_b128 v[72:75], v167 offset:2144
	ds_read_b128 v[76:79], v167 offset:2160
	v_pk_mul_f32 v[98:99], v[192:193], v[186:187]
	s_waitcnt vmcnt(60)
	v_lshlrev_b32_e32 v100, 16, v29
	v_exp_f32_e32 v98, v98
	v_exp_f32_e32 v99, v99
	v_and_b32_e32 v101, 0xffff0000, v29
	v_mov_b32_e32 v96, v198
	v_mov_b32_e32 v97, v199
	v_pk_mul_f32 v[102:103], v[100:101], v[98:99]
	s_waitcnt lgkmcnt(4)
	v_pk_fma_f32 v[96:97], v[80:81], v[232:233], v[96:97] op_sel_hi:[0,1,1]
	v_cvt_pk_bf16_f32 v108, v102, v103
	v_pk_fma_f32 v[96:97], v[80:81], v[234:235], v[96:97] op_sel:[1,0,0] op_sel_hi:[1,1,1]
	global_store_dword v166, v108, s[46:47]
	s_sub_u32 s46, s46, 0x3200
	s_subb_u32 s47, s47, 0
	global_load_dword v61, v166, s[30:31]
	s_sub_u32 s30, s30, 0x3200
	s_subb_u32 s31, s31, 0
	v_pk_fma_f32 v[96:97], v[82:83], v[236:237], v[96:97] op_sel_hi:[0,1,1]
	v_pk_fma_f32 v[96:97], v[82:83], v[238:239], v[96:97] op_sel:[1,0,0] op_sel_hi:[1,1,1]
	v_pk_fma_f32 v[96:97], v[84:85], v[240:241], v[96:97] op_sel_hi:[0,1,1]
	v_pk_fma_f32 v[96:97], v[84:85], v[242:243], v[96:97] op_sel:[1,0,0] op_sel_hi:[1,1,1]
	v_pk_fma_f32 v[96:97], v[86:87], v[244:245], v[96:97] op_sel_hi:[0,1,1]
	v_pk_fma_f32 v[96:97], v[86:87], v[246:247], v[96:97] op_sel:[1,0,0] op_sel_hi:[1,1,1]
	v_pk_fma_f32 v[96:97], v[88:89], v[248:249], v[96:97] op_sel_hi:[0,1,1]
	v_pk_fma_f32 v[96:97], v[88:89], v[250:251], v[96:97] op_sel:[1,0,0] op_sel_hi:[1,1,1]
	v_pk_fma_f32 v[96:97], v[90:91], v[252:253], v[96:97] op_sel_hi:[0,1,1]
	v_pk_fma_f32 v[96:97], v[90:91], v[254:255], v[96:97] op_sel:[1,0,0] op_sel_hi:[1,1,1]
	v_pk_fma_f32 v[96:97], v[92:93], v[220:221], v[96:97] op_sel_hi:[0,1,1]
	v_pk_fma_f32 v[96:97], v[92:93], v[222:223], v[96:97] op_sel:[1,0,0] op_sel_hi:[1,1,1]
	v_pk_fma_f32 v[96:97], v[94:95], v[224:225], v[96:97] op_sel_hi:[0,1,1]
	v_pk_fma_f32 v[96:97], v[94:95], v[226:227], v[96:97] op_sel:[1,0,0] op_sel_hi:[1,1,1]
	v_mul_f32_e64 v104, |v96|, s34
	v_mul_f32_e64 v105, |v97|, s34
	v_exp_f32_e32 v104, v104
	v_exp_f32_e32 v105, v105
	v_min_f32_e32 v106, 0, v96
	v_min_f32_e32 v107, 0, v97
	v_pk_add_f32 v[104:105], v[104:105], v[190:191]
	v_log_f32_e32 v104, v104
	v_log_f32_e32 v105, v105
	s_nop 0
	v_fma_f32 v106, v104, s35, v106
	v_fma_f32 v107, v105, s35, v107
	v_pk_fma_f32 v[192:193], v[106:107], v[188:189], v[192:193]
	ds_read_b128 v[80:83], v167 offset:2048
	ds_read_b128 v[84:87], v167 offset:2064
	ds_read_b128 v[88:91], v167 offset:2080
	ds_read_b128 v[92:95], v167 offset:2096
	v_pk_mul_f32 v[98:99], v[192:193], v[186:187]
	s_waitcnt vmcnt(61)
	v_lshlrev_b32_e32 v100, 16, v30
	v_exp_f32_e32 v98, v98
	v_exp_f32_e32 v99, v99
	v_and_b32_e32 v101, 0xffff0000, v30
	v_mov_b32_e32 v96, v198
	v_mov_b32_e32 v97, v199
	v_pk_mul_f32 v[102:103], v[100:101], v[98:99]
	s_waitcnt lgkmcnt(4)
; DI unsigned pk2(float a, float b) { f32x2 v = {a, b}; bf16v2_t r = __builtin_convertvector(v, bf16v2_t); return __builtin_bit_cast(unsigned, r); }
; DI void phase_gla_prep(const Params& p, LAS unsigned char* lds) {
;     ...
;             unsigned kw[16];
; #pragma unroll
;             for (int i = 0; i < 16; ++i) kw[i] = *(const unsigned*)(big + (tokb + tg * 16 + i) * 6400 + 1024 + ch0);
; #pragma unroll
;             for (int i = 15; i >= 0; --i) { const int tok = tg * 16 + i;
;                 float z0 = bs0, z1 = bs1;
; #pragma unroll
;                 for (int r = 0; r < 16; ++r) { const float lv = lrs[tok * 16 + r]; z0 += lv * wg0[r]; z1 += lv * wg1[r]; }
;                 *(unsigned*)(big + (tokb + tok) * 6400 + 1024 + ch0) = pk2(__uint_as_float(kw[i] << 16) * __expf(t0), __uint_as_float(kw[i] & 0xffff0000u) * __expf(t1));
;                 t0 += (fminf(z0, 0.f) - __logf(1.f + __expf(-fabsf(z0)))) * (1.f / 16.f); t1 += (fminf(z1, 0.f) - __logf(1.f + __expf(-fabsf(z1)))) * (1.f / 16.f);
	v_pk_fma_f32 v[96:97], v[64:65], v[232:233], v[96:97] op_sel_hi:[0,1,1]
	v_cvt_pk_bf16_f32 v108, v102, v103
	v_pk_fma_f32 v[96:97], v[64:65], v[234:235], v[96:97] op_sel:[1,0,0] op_sel_hi:[1,1,1]
	global_store_dword v166, v108, s[46:47]
	s_sub_u32 s46, s46, 0x3200
	s_subb_u32 s47, s47, 0
	global_load_dword v62, v166, s[30:31]
	s_sub_u32 s30, s30, 0x3200
	s_subb_u32 s31, s31, 0
	v_pk_fma_f32 v[96:97], v[66:67], v[236:237], v[96:97] op_sel_hi:[0,1,1]
	v_pk_fma_f32 v[96:97], v[66:67], v[238:239], v[96:97] op_sel:[1,0,0] op_sel_hi:[1,1,1]
	v_pk_fma_f32 v[96:97], v[68:69], v[240:241], v[96:97] op_sel_hi:[0,1,1]
	v_pk_fma_f32 v[96:97], v[68:69], v[242:243], v[96:97] op_sel:[1,0,0] op_sel_hi:[1,1,1]
	v_pk_fma_f32 v[96:97], v[70:71], v[244:245], v[96:97] op_sel_hi:[0,1,1]
	v_pk_fma_f32 v[96:97], v[70:71], v[246:247], v[96:97] op_sel:[1,0,0] op_sel_hi:[1,1,1]
	v_pk_fma_f32 v[96:97], v[72:73], v[248:249], v[96:97] op_sel_hi:[0,1,1]
	v_pk_fma_f32 v[96:97], v[72:73], v[250:251], v[96:97] op_sel:[1,0,0] op_sel_hi:[1,1,1]
	v_pk_fma_f32 v[96:97], v[74:75], v[252:253], v[96:97] op_sel_hi:[0,1,1]
	v_pk_fma_f32 v[96:97], v[74:75], v[254:255], v[96:97] op_sel:[1,0,0] op_sel_hi:[1,1,1]
	v_pk_fma_f32 v[96:97], v[76:77], v[220:221], v[96:97] op_sel_hi:[0,1,1]
	v_pk_fma_f32 v[96:97], v[76:77], v[222:223], v[96:97] op_sel:[1,0,0] op_sel_hi:[1,1,1]
	v_pk_fma_f32 v[96:97], v[78:79], v[224:225], v[96:97] op_sel_hi:[0,1,1]
	v_pk_fma_f32 v[96:97], v[78:79], v[226:227], v[96:97] op_sel:[1,0,0] op_sel_hi:[1,1,1]
	v_mul_f32_e64 v104, |v96|, s34
	v_mul_f32_e64 v105, |v97|, s34
	v_exp_f32_e32 v104, v104
	v_exp_f32_e32 v105, v105
	v_min_f32_e32 v106, 0, v96
	v_min_f32_e32 v107, 0, v97
	v_pk_add_f32 v[104:105], v[104:105], v[190:191]
	v_log_f32_e32 v104, v104
	v_log_f32_e32 v105, v105
	s_nop 0
	v_fma_f32 v106, v104, s35, v106
	v_fma_f32 v107, v105, s35, v107
	v_pk_fma_f32 v[192:193], v[106:107], v[188:189], v[192:193]
	ds_read_b128 v[64:67], v167 offset:1984
	ds_read_b128 v[68:71], v167 offset:2000
	ds_read_b128 v[72:75], v167 offset:2016
	ds_read_b128 v[76:79], v167 offset:2032
	v_pk_mul_f32 v[98:99], v[192:193], v[186:187]
	s_waitcnt vmcnt(61)
	v_lshlrev_b32_e32 v100, 16, v31
	v_exp_f32_e32 v98, v98
	v_exp_f32_e32 v99, v99
	v_and_b32_e32 v101, 0xffff0000, v31
	v_mov_b32_e32 v96, v198
	v_mov_b32_e32 v97, v199
	v_pk_mul_f32 v[102:103], v[100:101], v[98:99]
	s_waitcnt lgkmcnt(4)
	v_pk_fma_f32 v[96:97], v[80:81], v[232:233], v[96:97] op_sel_hi:[0,1,1]
	v_cvt_pk_bf16_f32 v108, v102, v103
	v_pk_fma_f32 v[96:97], v[80:81], v[234:235], v[96:97] op_sel:[1,0,0] op_sel_hi:[1,1,1]
	global_store_dword v166, v108, s[46:47]
	s_sub_u32 s46, s46, 0x3200
	s_subb_u32 s47, s47, 0
	global_load_dword v63, v166, s[30:31]
	s_sub_u32 s30, s30, 0x3200
	s_subb_u32 s31, s31, 0
	v_pk_fma_f32 v[96:97], v[82:83], v[236:237], v[96:97] op_sel_hi:[0,1,1]
	v_pk_fma_f32 v[96:97], v[82:83], v[238:239], v[96:97] op_sel:[1,0,0] op_sel_hi:[1,1,1]
	v_pk_fma_f32 v[96:97], v[84:85], v[240:241], v[96:97] op_sel_hi:[0,1,1]
	v_pk_fma_f32 v[96:97], v[84:85], v[242:243], v[96:97] op_sel:[1,0,0] op_sel_hi:[1,1,1]
	v_pk_fma_f32 v[96:97], v[86:87], v[244:245], v[96:97] op_sel_hi:[0,1,1]
	v_pk_fma_f32 v[96:97], v[86:87], v[246:247], v[96:97] op_sel:[1,0,0] op_sel_hi:[1,1,1]
	v_pk_fma_f32 v[96:97], v[88:89], v[248:249], v[96:97] op_sel_hi:[0,1,1]
	v_pk_fma_f32 v[96:97], v[88:89], v[250:251], v[96:97] op_sel:[1,0,0] op_sel_hi:[1,1,1]
	v_pk_fma_f32 v[96:97], v[90:91], v[252:253], v[96:97] op_sel_hi:[0,1,1]
	v_pk_fma_f32 v[96:97], v[90:91], v[254:255], v[96:97] op_sel:[1,0,0] op_sel_hi:[1,1,1]
	v_pk_fma_f32 v[96:97], v[92:93], v[220:221], v[96:97] op_sel_hi:[0,1,1]
	v_pk_fma_f32 v[96:97], v[92:93], v[222:223], v[96:97] op_sel:[1,0,0] op_sel_hi:[1,1,1]
	v_pk_fma_f32 v[96:97], v[94:95], v[224:225], v[96:97] op_sel_hi:[0,1,1]
	v_pk_fma_f32 v[96:97], v[94:95], v[226:227], v[96:97] op_sel:[1,0,0] op_sel_hi:[1,1,1]
	v_mul_f32_e64 v104, |v96|, s34
	v_mul_f32_e64 v105, |v97|, s34
	v_exp_f32_e32 v104, v104
	v_exp_f32_e32 v105, v105
	v_min_f32_e32 v106, 0, v96
	v_min_f32_e32 v107, 0, v97
	v_pk_add_f32 v[104:105], v[104:105], v[190:191]
	v_log_f32_e32 v104, v104
	v_log_f32_e32 v105, v105
	s_nop 0
	v_fma_f32 v106, v104, s35, v106
	v_fma_f32 v107, v105, s35, v107
	v_pk_fma_f32 v[192:193], v[106:107], v[188:189], v[192:193]
	ds_read_b128 v[80:83], v167 offset:1920
	ds_read_b128 v[84:87], v167 offset:1936
	ds_read_b128 v[88:91], v167 offset:1952
	ds_read_b128 v[92:95], v167 offset:1968
	v_pk_mul_f32 v[98:99], v[192:193], v[186:187]
	s_waitcnt vmcnt(61)
	v_lshlrev_b32_e32 v100, 16, v32
	v_exp_f32_e32 v98, v98
	v_exp_f32_e32 v99, v99
	v_and_b32_e32 v101, 0xffff0000, v32
	v_mov_b32_e32 v96, v198
	v_mov_b32_e32 v97, v199
	v_pk_mul_f32 v[102:103], v[100:101], v[98:99]
	s_waitcnt lgkmcnt(4)
; DI unsigned pk2(float a, float b) { f32x2 v = {a, b}; bf16v2_t r = __builtin_convertvector(v, bf16v2_t); return __builtin_bit_cast(unsigned, r); }
; DI void phase_gla_prep(const Params& p, LAS unsigned char* lds) {
;     ...
;             unsigned kw[16];
; #pragma unroll
;             for (int i = 0; i < 16; ++i) kw[i] = *(const unsigned*)(big + (tokb + tg * 16 + i) * 6400 + 1024 + ch0);
; #pragma unroll
;             for (int i = 15; i >= 0; --i) { const int tok = tg * 16 + i;
;                 float z0 = bs0, z1 = bs1;
; #pragma unroll
;                 for (int r = 0; r < 16; ++r) { const float lv = lrs[tok * 16 + r]; z0 += lv * wg0[r]; z1 += lv * wg1[r]; }
;                 *(unsigned*)(big + (tokb + tok) * 6400 + 1024 + ch0) = pk2(__uint_as_float(kw[i] << 16) * __expf(t0), __uint_as_float(kw[i] & 0xffff0000u) * __expf(t1));
;                 t0 += (fminf(z0, 0.f) - __logf(1.f + __expf(-fabsf(z0)))) * (1.f / 16.f); t1 += (fminf(z1, 0.f) - __logf(1.f + __expf(-fabsf(z1)))) * (1.f / 16.f);
	v_pk_fma_f32 v[96:97], v[64:65], v[232:233], v[96:97] op_sel_hi:[0,1,1]
	v_cvt_pk_bf16_f32 v108, v102, v103
	v_pk_fma_f32 v[96:97], v[64:65], v[234:235], v[96:97] op_sel:[1,0,0] op_sel_hi:[1,1,1]
	global_store_dword v166, v108, s[46:47]
	s_sub_u32 s46, s46, 0x3200
	s_subb_u32 s47, s47, 0
	v_pk_fma_f32 v[96:97], v[66:67], v[236:237], v[96:97] op_sel_hi:[0,1,1]
	v_pk_fma_f32 v[96:97], v[66:67], v[238:239], v[96:97] op_sel:[1,0,0] op_sel_hi:[1,1,1]
	v_pk_fma_f32 v[96:97], v[68:69], v[240:241], v[96:97] op_sel_hi:[0,1,1]
	v_pk_fma_f32 v[96:97], v[68:69], v[242:243], v[96:97] op_sel:[1,0,0] op_sel_hi:[1,1,1]
	v_pk_fma_f32 v[96:97], v[70:71], v[244:245], v[96:97] op_sel_hi:[0,1,1]
	v_pk_fma_f32 v[96:97], v[70:71], v[246:247], v[96:97] op_sel:[1,0,0] op_sel_hi:[1,1,1]
	v_pk_fma_f32 v[96:97], v[72:73], v[248:249], v[96:97] op_sel_hi:[0,1,1]
	v_pk_fma_f32 v[96:97], v[72:73], v[250:251], v[96:97] op_sel:[1,0,0] op_sel_hi:[1,1,1]
	v_pk_fma_f32 v[96:97], v[74:75], v[252:253], v[96:97] op_sel_hi:[0,1,1]
	v_pk_fma_f32 v[96:97], v[74:75], v[254:255], v[96:97] op_sel:[1,0,0] op_sel_hi:[1,1,1]
	v_pk_fma_f32 v[96:97], v[76:77], v[220:221], v[96:97] op_sel_hi:[0,1,1]
	v_pk_fma_f32 v[96:97], v[76:77], v[222:223], v[96:97] op_sel:[1,0,0] op_sel_hi:[1,1,1]
	v_pk_fma_f32 v[96:97], v[78:79], v[224:225], v[96:97] op_sel_hi:[0,1,1]
	v_pk_fma_f32 v[96:97], v[78:79], v[226:227], v[96:97] op_sel:[1,0,0] op_sel_hi:[1,1,1]
	v_mul_f32_e64 v104, |v96|, s34
	v_mul_f32_e64 v105, |v97|, s34
	v_exp_f32_e32 v104, v104
	v_exp_f32_e32 v105, v105
	v_min_f32_e32 v106, 0, v96
	v_min_f32_e32 v107, 0, v97
	v_pk_add_f32 v[104:105], v[104:105], v[190:191]
	v_log_f32_e32 v104, v104
	v_log_f32_e32 v105, v105
	s_nop 0
	v_fma_f32 v106, v104, s35, v106
	v_fma_f32 v107, v105, s35, v107
	v_pk_fma_f32 v[192:193], v[106:107], v[188:189], v[192:193]
	ds_read_b128 v[64:67], v167 offset:1856
	ds_read_b128 v[68:71], v167 offset:1872
	ds_read_b128 v[72:75], v167 offset:1888
	ds_read_b128 v[76:79], v167 offset:1904
	v_pk_mul_f32 v[98:99], v[192:193], v[186:187]
	s_waitcnt vmcnt(61)
	v_lshlrev_b32_e32 v100, 16, v33
	v_exp_f32_e32 v98, v98
	v_exp_f32_e32 v99, v99
	v_and_b32_e32 v101, 0xffff0000, v33
	v_mov_b32_e32 v96, v198
	v_mov_b32_e32 v97, v199
	v_pk_mul_f32 v[102:103], v[100:101], v[98:99]
	s_waitcnt lgkmcnt(4)
	v_pk_fma_f32 v[96:97], v[80:81], v[232:233], v[96:97] op_sel_hi:[0,1,1]
	v_cvt_pk_bf16_f32 v108, v102, v103
	v_pk_fma_f32 v[96:97], v[80:81], v[234:235], v[96:97] op_sel:[1,0,0] op_sel_hi:[1,1,1]
	global_store_dword v166, v108, s[46:47]
	s_sub_u32 s46, s46, 0x3200
	s_subb_u32 s47, s47, 0
	v_pk_fma_f32 v[96:97], v[82:83], v[236:237], v[96:97] op_sel_hi:[0,1,1]
	v_pk_fma_f32 v[96:97], v[82:83], v[238:239], v[96:97] op_sel:[1,0,0] op_sel_hi:[1,1,1]
	v_pk_fma_f32 v[96:97], v[84:85], v[240:241], v[96:97] op_sel_hi:[0,1,1]
	v_pk_fma_f32 v[96:97], v[84:85], v[242:243], v[96:97] op_sel:[1,0,0] op_sel_hi:[1,1,1]
	v_pk_fma_f32 v[96:97], v[86:87], v[244:245], v[96:97] op_sel_hi:[0,1,1]
	v_pk_fma_f32 v[96:97], v[86:87], v[246:247], v[96:97] op_sel:[1,0,0] op_sel_hi:[1,1,1]
	v_pk_fma_f32 v[96:97], v[88:89], v[248:249], v[96:97] op_sel_hi:[0,1,1]
	v_pk_fma_f32 v[96:97], v[88:89], v[250:251], v[96:97] op_sel:[1,0,0] op_sel_hi:[1,1,1]
	v_pk_fma_f32 v[96:97], v[90:91], v[252:253], v[96:97] op_sel_hi:[0,1,1]
	v_pk_fma_f32 v[96:97], v[90:91], v[254:255], v[96:97] op_sel:[1,0,0] op_sel_hi:[1,1,1]
	v_pk_fma_f32 v[96:97], v[92:93], v[220:221], v[96:97] op_sel_hi:[0,1,1]
	v_pk_fma_f32 v[96:97], v[92:93], v[222:223], v[96:97] op_sel:[1,0,0] op_sel_hi:[1,1,1]
	v_pk_fma_f32 v[96:97], v[94:95], v[224:225], v[96:97] op_sel_hi:[0,1,1]
	v_pk_fma_f32 v[96:97], v[94:95], v[226:227], v[96:97] op_sel:[1,0,0] op_sel_hi:[1,1,1]
	v_mul_f32_e64 v104, |v96|, s34
	v_mul_f32_e64 v105, |v97|, s34
	v_exp_f32_e32 v104, v104
	v_exp_f32_e32 v105, v105
	v_min_f32_e32 v106, 0, v96
	v_min_f32_e32 v107, 0, v97
	v_pk_add_f32 v[104:105], v[104:105], v[190:191]
	v_log_f32_e32 v104, v104
	v_log_f32_e32 v105, v105
	s_nop 0
	v_fma_f32 v106, v104, s35, v106
	v_fma_f32 v107, v105, s35, v107
	v_pk_fma_f32 v[192:193], v[106:107], v[188:189], v[192:193]
	ds_read_b128 v[80:83], v167 offset:1792
	ds_read_b128 v[84:87], v167 offset:1808
	ds_read_b128 v[88:91], v167 offset:1824
	ds_read_b128 v[92:95], v167 offset:1840
	v_pk_mul_f32 v[98:99], v[192:193], v[186:187]
	s_waitcnt vmcnt(60)
	v_lshlrev_b32_e32 v100, 16, v34
	v_exp_f32_e32 v98, v98
	v_exp_f32_e32 v99, v99
	v_and_b32_e32 v101, 0xffff0000, v34
	v_mov_b32_e32 v96, v198
	v_mov_b32_e32 v97, v199
	v_pk_mul_f32 v[102:103], v[100:101], v[98:99]
	s_waitcnt lgkmcnt(4)
	v_pk_fma_f32 v[96:97], v[64:65], v[232:233], v[96:97] op_sel_hi:[0,1,1]
	v_cvt_pk_bf16_f32 v108, v102, v103
	v_pk_fma_f32 v[96:97], v[64:65], v[234:235], v[96:97] op_sel:[1,0,0] op_sel_hi:[1,1,1]
	global_store_dword v166, v108, s[46:47]
	s_sub_u32 s46, s46, 0x3200
	s_subb_u32 s47, s47, 0
	v_pk_fma_f32 v[96:97], v[66:67], v[236:237], v[96:97] op_sel_hi:[0,1,1]
	v_pk_fma_f32 v[96:97], v[66:67], v[238:239], v[96:97] op_sel:[1,0,0] op_sel_hi:[1,1,1]
	v_pk_fma_f32 v[96:97], v[68:69], v[240:241], v[96:97] op_sel_hi:[0,1,1]
	v_pk_fma_f32 v[96:97], v[68:69], v[242:243], v[96:97] op_sel:[1,0,0] op_sel_hi:[1,1,1]
	v_pk_fma_f32 v[96:97], v[70:71], v[244:245], v[96:97] op_sel_hi:[0,1,1]
	v_pk_fma_f32 v[96:97], v[70:71], v[246:247], v[96:97] op_sel:[1,0,0] op_sel_hi:[1,1,1]
	v_pk_fma_f32 v[96:97], v[72:73], v[248:249], v[96:97] op_sel_hi:[0,1,1]
	v_pk_fma_f32 v[96:97], v[72:73], v[250:251], v[96:97] op_sel:[1,0,0] op_sel_hi:[1,1,1]
	v_pk_fma_f32 v[96:97], v[74:75], v[252:253], v[96:97] op_sel_hi:[0,1,1]
	v_pk_fma_f32 v[96:97], v[74:75], v[254:255], v[96:97] op_sel:[1,0,0] op_sel_hi:[1,1,1]
	v_pk_fma_f32 v[96:97], v[76:77], v[220:221], v[96:97] op_sel_hi:[0,1,1]
	v_pk_fma_f32 v[96:97], v[76:77], v[222:223], v[96:97] op_sel:[1,0,0] op_sel_hi:[1,1,1]
	v_pk_fma_f32 v[96:97], v[78:79], v[224:225], v[96:97] op_sel_hi:[0,1,1]
	v_pk_fma_f32 v[96:97], v[78:79], v[226:227], v[96:97] op_sel:[1,0,0] op_sel_hi:[1,1,1]
	v_mul_f32_e64 v104, |v96|, s34
	v_mul_f32_e64 v105, |v97|, s34
	v_exp_f32_e32 v104, v104
	v_exp_f32_e32 v105, v105
	v_min_f32_e32 v106, 0, v96
	v_min_f32_e32 v107, 0, v97
	v_pk_add_f32 v[104:105], v[104:105], v[190:191]
	v_log_f32_e32 v104, v104
	v_log_f32_e32 v105, v105
	s_nop 0
	v_fma_f32 v106, v104, s35, v106
	v_fma_f32 v107, v105, s35, v107
	v_pk_fma_f32 v[192:193], v[106:107], v[188:189], v[192:193]
	ds_read_b128 v[64:67], v167 offset:1728
	ds_read_b128 v[68:71], v167 offset:1744
	ds_read_b128 v[72:75], v167 offset:1760
	ds_read_b128 v[76:79], v167 offset:1776
	v_pk_mul_f32 v[98:99], v[192:193], v[186:187]
	s_waitcnt vmcnt(59)
; DI unsigned pk2(float a, float b) { f32x2 v = {a, b}; bf16v2_t r = __builtin_convertvector(v, bf16v2_t); return __builtin_bit_cast(unsigned, r); }
; DI void phase_gla_prep(const Params& p, LAS unsigned char* lds) {
;     ...
;             unsigned kw[16];
; #pragma unroll
;             for (int i = 0; i < 16; ++i) kw[i] = *(const unsigned*)(big + (tokb + tg * 16 + i) * 6400 + 1024 + ch0);
; #pragma unroll
;             for (int i = 15; i >= 0; --i) { const int tok = tg * 16 + i;
;                 float z0 = bs0, z1 = bs1;
; #pragma unroll
;                 for (int r = 0; r < 16; ++r) { const float lv = lrs[tok * 16 + r]; z0 += lv * wg0[r]; z1 += lv * wg1[r]; }
;                 *(unsigned*)(big + (tokb + tok) * 6400 + 1024 + ch0) = pk2(__uint_as_float(kw[i] << 16) * __expf(t0), __uint_as_float(kw[i] & 0xffff0000u) * __expf(t1));
;                 t0 += (fminf(z0, 0.f) - __logf(1.f + __expf(-fabsf(z0)))) * (1.f / 16.f); t1 += (fminf(z1, 0.f) - __logf(1.f + __expf(-fabsf(z1)))) * (1.f / 16.f);
	v_lshlrev_b32_e32 v100, 16, v35
	v_exp_f32_e32 v98, v98
	v_exp_f32_e32 v99, v99
	v_and_b32_e32 v101, 0xffff0000, v35
	v_mov_b32_e32 v96, v198
	v_mov_b32_e32 v97, v199
	v_pk_mul_f32 v[102:103], v[100:101], v[98:99]
	s_waitcnt lgkmcnt(4)
	v_pk_fma_f32 v[96:97], v[80:81], v[232:233], v[96:97] op_sel_hi:[0,1,1]
	v_cvt_pk_bf16_f32 v108, v102, v103
	v_pk_fma_f32 v[96:97], v[80:81], v[234:235], v[96:97] op_sel:[1,0,0] op_sel_hi:[1,1,1]
	global_store_dword v166, v108, s[46:47]
	s_sub_u32 s46, s46, 0x3200
	s_subb_u32 s47, s47, 0
	v_pk_fma_f32 v[96:97], v[82:83], v[236:237], v[96:97] op_sel_hi:[0,1,1]
	v_pk_fma_f32 v[96:97], v[82:83], v[238:239], v[96:97] op_sel:[1,0,0] op_sel_hi:[1,1,1]
	v_pk_fma_f32 v[96:97], v[84:85], v[240:241], v[96:97] op_sel_hi:[0,1,1]
	v_pk_fma_f32 v[96:97], v[84:85], v[242:243], v[96:97] op_sel:[1,0,0] op_sel_hi:[1,1,1]
	v_pk_fma_f32 v[96:97], v[86:87], v[244:245], v[96:97] op_sel_hi:[0,1,1]
	v_pk_fma_f32 v[96:97], v[86:87], v[246:247], v[96:97] op_sel:[1,0,0] op_sel_hi:[1,1,1]
	v_pk_fma_f32 v[96:97], v[88:89], v[248:249], v[96:97] op_sel_hi:[0,1,1]
	v_pk_fma_f32 v[96:97], v[88:89], v[250:251], v[96:97] op_sel:[1,0,0] op_sel_hi:[1,1,1]
	v_pk_fma_f32 v[96:97], v[90:91], v[252:253], v[96:97] op_sel_hi:[0,1,1]
	v_pk_fma_f32 v[96:97], v[90:91], v[254:255], v[96:97] op_sel:[1,0,0] op_sel_hi:[1,1,1]
	v_pk_fma_f32 v[96:97], v[92:93], v[220:221], v[96:97] op_sel_hi:[0,1,1]
	v_pk_fma_f32 v[96:97], v[92:93], v[222:223], v[96:97] op_sel:[1,0,0] op_sel_hi:[1,1,1]
	v_pk_fma_f32 v[96:97], v[94:95], v[224:225], v[96:97] op_sel_hi:[0,1,1]
	v_pk_fma_f32 v[96:97], v[94:95], v[226:227], v[96:97] op_sel:[1,0,0] op_sel_hi:[1,1,1]
	v_mul_f32_e64 v104, |v96|, s34
	v_mul_f32_e64 v105, |v97|, s34
	v_exp_f32_e32 v104, v104
	v_exp_f32_e32 v105, v105
	v_min_f32_e32 v106, 0, v96
	v_min_f32_e32 v107, 0, v97
	v_pk_add_f32 v[104:105], v[104:105], v[190:191]
	v_log_f32_e32 v104, v104
	v_log_f32_e32 v105, v105
	s_nop 0
	v_fma_f32 v106, v104, s35, v106
	v_fma_f32 v107, v105, s35, v107
	v_pk_fma_f32 v[192:193], v[106:107], v[188:189], v[192:193]
	ds_read_b128 v[80:83], v167 offset:1664
	ds_read_b128 v[84:87], v167 offset:1680
	ds_read_b128 v[88:91], v167 offset:1696
	ds_read_b128 v[92:95], v167 offset:1712
	v_pk_mul_f32 v[98:99], v[192:193], v[186:187]
	s_waitcnt vmcnt(58)
	v_lshlrev_b32_e32 v100, 16, v36
	v_exp_f32_e32 v98, v98
	v_exp_f32_e32 v99, v99
	v_and_b32_e32 v101, 0xffff0000, v36
	v_mov_b32_e32 v96, v198
	v_mov_b32_e32 v97, v199
	v_pk_mul_f32 v[102:103], v[100:101], v[98:99]
	s_waitcnt lgkmcnt(4)
	v_pk_fma_f32 v[96:97], v[64:65], v[232:233], v[96:97] op_sel_hi:[0,1,1]
	v_cvt_pk_bf16_f32 v108, v102, v103
	v_pk_fma_f32 v[96:97], v[64:65], v[234:235], v[96:97] op_sel:[1,0,0] op_sel_hi:[1,1,1]
	global_store_dword v166, v108, s[46:47]
	s_sub_u32 s46, s46, 0x3200
	s_subb_u32 s47, s47, 0
	v_pk_fma_f32 v[96:97], v[66:67], v[236:237], v[96:97] op_sel_hi:[0,1,1]
	v_pk_fma_f32 v[96:97], v[66:67], v[238:239], v[96:97] op_sel:[1,0,0] op_sel_hi:[1,1,1]
	v_pk_fma_f32 v[96:97], v[68:69], v[240:241], v[96:97] op_sel_hi:[0,1,1]
	v_pk_fma_f32 v[96:97], v[68:69], v[242:243], v[96:97] op_sel:[1,0,0] op_sel_hi:[1,1,1]
	v_pk_fma_f32 v[96:97], v[70:71], v[244:245], v[96:97] op_sel_hi:[0,1,1]
	v_pk_fma_f32 v[96:97], v[70:71], v[246:247], v[96:97] op_sel:[1,0,0] op_sel_hi:[1,1,1]
	v_pk_fma_f32 v[96:97], v[72:73], v[248:249], v[96:97] op_sel_hi:[0,1,1]
	v_pk_fma_f32 v[96:97], v[72:73], v[250:251], v[96:97] op_sel:[1,0,0] op_sel_hi:[1,1,1]
	v_pk_fma_f32 v[96:97], v[74:75], v[252:253], v[96:97] op_sel_hi:[0,1,1]
	v_pk_fma_f32 v[96:97], v[74:75], v[254:255], v[96:97] op_sel:[1,0,0] op_sel_hi:[1,1,1]
	v_pk_fma_f32 v[96:97], v[76:77], v[220:221], v[96:97] op_sel_hi:[0,1,1]
	v_pk_fma_f32 v[96:97], v[76:77], v[222:223], v[96:97] op_sel:[1,0,0] op_sel_hi:[1,1,1]
	v_pk_fma_f32 v[96:97], v[78:79], v[224:225], v[96:97] op_sel_hi:[0,1,1]
	v_pk_fma_f32 v[96:97], v[78:79], v[226:227], v[96:97] op_sel:[1,0,0] op_sel_hi:[1,1,1]
	v_mul_f32_e64 v104, |v96|, s34
	v_mul_f32_e64 v105, |v97|, s34
	v_exp_f32_e32 v104, v104
	v_exp_f32_e32 v105, v105
	v_min_f32_e32 v106, 0, v96
	v_min_f32_e32 v107, 0, v97
	v_pk_add_f32 v[104:105], v[104:105], v[190:191]
	v_log_f32_e32 v104, v104
	v_log_f32_e32 v105, v105
	s_nop 0
	v_fma_f32 v106, v104, s35, v106
	v_fma_f32 v107, v105, s35, v107
	v_pk_fma_f32 v[192:193], v[106:107], v[188:189], v[192:193]
	ds_read_b128 v[64:67], v167 offset:1600
	ds_read_b128 v[68:71], v167 offset:1616
	ds_read_b128 v[72:75], v167 offset:1632
	ds_read_b128 v[76:79], v167 offset:1648
	v_pk_mul_f32 v[98:99], v[192:193], v[186:187]
	s_waitcnt vmcnt(57)
	v_lshlrev_b32_e32 v100, 16, v37
	v_exp_f32_e32 v98, v98
	v_exp_f32_e32 v99, v99
	v_and_b32_e32 v101, 0xffff0000, v37
	v_mov_b32_e32 v96, v198
	v_mov_b32_e32 v97, v199
	v_pk_mul_f32 v[102:103], v[100:101], v[98:99]
	s_waitcnt lgkmcnt(4)
; DI unsigned pk2(float a, float b) { f32x2 v = {a, b}; bf16v2_t r = __builtin_convertvector(v, bf16v2_t); return __builtin_bit_cast(unsigned, r); }
; DI void phase_gla_prep(const Params& p, LAS unsigned char* lds) {
;     ...
;             unsigned kw[16];
; #pragma unroll
;             for (int i = 0; i < 16; ++i) kw[i] = *(const unsigned*)(big + (tokb + tg * 16 + i) * 6400 + 1024 + ch0);
; #pragma unroll
;             for (int i = 15; i >= 0; --i) { const int tok = tg * 16 + i;
;                 float z0 = bs0, z1 = bs1;
; #pragma unroll
;                 for (int r = 0; r < 16; ++r) { const float lv = lrs[tok * 16 + r]; z0 += lv * wg0[r]; z1 += lv * wg1[r]; }
;                 *(unsigned*)(big + (tokb + tok) * 6400 + 1024 + ch0) = pk2(__uint_as_float(kw[i] << 16) * __expf(t0), __uint_as_float(kw[i] & 0xffff0000u) * __expf(t1));
;                 t0 += (fminf(z0, 0.f) - __logf(1.f + __expf(-fabsf(z0)))) * (1.f / 16.f); t1 += (fminf(z1, 0.f) - __logf(1.f + __expf(-fabsf(z1)))) * (1.f / 16.f);
	v_pk_fma_f32 v[96:97], v[80:81], v[232:233], v[96:97] op_sel_hi:[0,1,1]
	v_cvt_pk_bf16_f32 v108, v102, v103
	v_pk_fma_f32 v[96:97], v[80:81], v[234:235], v[96:97] op_sel:[1,0,0] op_sel_hi:[1,1,1]
	global_store_dword v166, v108, s[46:47]
	s_sub_u32 s46, s46, 0x3200
	s_subb_u32 s47, s47, 0
	v_pk_fma_f32 v[96:97], v[82:83], v[236:237], v[96:97] op_sel_hi:[0,1,1]
	v_pk_fma_f32 v[96:97], v[82:83], v[238:239], v[96:97] op_sel:[1,0,0] op_sel_hi:[1,1,1]
	v_pk_fma_f32 v[96:97], v[84:85], v[240:241], v[96:97] op_sel_hi:[0,1,1]
	v_pk_fma_f32 v[96:97], v[84:85], v[242:243], v[96:97] op_sel:[1,0,0] op_sel_hi:[1,1,1]
	v_pk_fma_f32 v[96:97], v[86:87], v[244:245], v[96:97] op_sel_hi:[0,1,1]
	v_pk_fma_f32 v[96:97], v[86:87], v[246:247], v[96:97] op_sel:[1,0,0] op_sel_hi:[1,1,1]
	v_pk_fma_f32 v[96:97], v[88:89], v[248:249], v[96:97] op_sel_hi:[0,1,1]
	v_pk_fma_f32 v[96:97], v[88:89], v[250:251], v[96:97] op_sel:[1,0,0] op_sel_hi:[1,1,1]
	v_pk_fma_f32 v[96:97], v[90:91], v[252:253], v[96:97] op_sel_hi:[0,1,1]
	v_pk_fma_f32 v[96:97], v[90:91], v[254:255], v[96:97] op_sel:[1,0,0] op_sel_hi:[1,1,1]
	v_pk_fma_f32 v[96:97], v[92:93], v[220:221], v[96:97] op_sel_hi:[0,1,1]
	v_pk_fma_f32 v[96:97], v[92:93], v[222:223], v[96:97] op_sel:[1,0,0] op_sel_hi:[1,1,1]
	v_pk_fma_f32 v[96:97], v[94:95], v[224:225], v[96:97] op_sel_hi:[0,1,1]
	v_pk_fma_f32 v[96:97], v[94:95], v[226:227], v[96:97] op_sel:[1,0,0] op_sel_hi:[1,1,1]
	v_mul_f32_e64 v104, |v96|, s34
	v_mul_f32_e64 v105, |v97|, s34
	v_exp_f32_e32 v104, v104
	v_exp_f32_e32 v105, v105
	v_min_f32_e32 v106, 0, v96
	v_min_f32_e32 v107, 0, v97
	v_pk_add_f32 v[104:105], v[104:105], v[190:191]
	v_log_f32_e32 v104, v104
	v_log_f32_e32 v105, v105
	s_nop 0
	v_fma_f32 v106, v104, s35, v106
	v_fma_f32 v107, v105, s35, v107
	v_pk_fma_f32 v[192:193], v[106:107], v[188:189], v[192:193]
	ds_read_b128 v[80:83], v167 offset:1536
	ds_read_b128 v[84:87], v167 offset:1552
	ds_read_b128 v[88:91], v167 offset:1568
	ds_read_b128 v[92:95], v167 offset:1584
	v_pk_mul_f32 v[98:99], v[192:193], v[186:187]
	s_waitcnt vmcnt(56)
	v_lshlrev_b32_e32 v100, 16, v38
	v_exp_f32_e32 v98, v98
	v_exp_f32_e32 v99, v99
	v_and_b32_e32 v101, 0xffff0000, v38
	v_mov_b32_e32 v96, v198
	v_mov_b32_e32 v97, v199
	v_pk_mul_f32 v[102:103], v[100:101], v[98:99]
	s_waitcnt lgkmcnt(4)
	v_pk_fma_f32 v[96:97], v[64:65], v[232:233], v[96:97] op_sel_hi:[0,1,1]
	v_cvt_pk_bf16_f32 v108, v102, v103
	v_pk_fma_f32 v[96:97], v[64:65], v[234:235], v[96:97] op_sel:[1,0,0] op_sel_hi:[1,1,1]
	global_store_dword v166, v108, s[46:47]
	s_sub_u32 s46, s46, 0x3200
	s_subb_u32 s47, s47, 0
	v_pk_fma_f32 v[96:97], v[66:67], v[236:237], v[96:97] op_sel_hi:[0,1,1]
	v_pk_fma_f32 v[96:97], v[66:67], v[238:239], v[96:97] op_sel:[1,0,0] op_sel_hi:[1,1,1]
	v_pk_fma_f32 v[96:97], v[68:69], v[240:241], v[96:97] op_sel_hi:[0,1,1]
	v_pk_fma_f32 v[96:97], v[68:69], v[242:243], v[96:97] op_sel:[1,0,0] op_sel_hi:[1,1,1]
	v_pk_fma_f32 v[96:97], v[70:71], v[244:245], v[96:97] op_sel_hi:[0,1,1]
	v_pk_fma_f32 v[96:97], v[70:71], v[246:247], v[96:97] op_sel:[1,0,0] op_sel_hi:[1,1,1]
	v_pk_fma_f32 v[96:97], v[72:73], v[248:249], v[96:97] op_sel_hi:[0,1,1]
	v_pk_fma_f32 v[96:97], v[72:73], v[250:251], v[96:97] op_sel:[1,0,0] op_sel_hi:[1,1,1]
	v_pk_fma_f32 v[96:97], v[74:75], v[252:253], v[96:97] op_sel_hi:[0,1,1]
	v_pk_fma_f32 v[96:97], v[74:75], v[254:255], v[96:97] op_sel:[1,0,0] op_sel_hi:[1,1,1]
	v_pk_fma_f32 v[96:97], v[76:77], v[220:221], v[96:97] op_sel_hi:[0,1,1]
	v_pk_fma_f32 v[96:97], v[76:77], v[222:223], v[96:97] op_sel:[1,0,0] op_sel_hi:[1,1,1]
	v_pk_fma_f32 v[96:97], v[78:79], v[224:225], v[96:97] op_sel_hi:[0,1,1]
	v_pk_fma_f32 v[96:97], v[78:79], v[226:227], v[96:97] op_sel:[1,0,0] op_sel_hi:[1,1,1]
	v_mul_f32_e64 v104, |v96|, s34
	v_mul_f32_e64 v105, |v97|, s34
	v_exp_f32_e32 v104, v104
	v_exp_f32_e32 v105, v105
	v_min_f32_e32 v106, 0, v96
	v_min_f32_e32 v107, 0, v97
	v_pk_add_f32 v[104:105], v[104:105], v[190:191]
	v_log_f32_e32 v104, v104
	v_log_f32_e32 v105, v105
	s_nop 0
	v_fma_f32 v106, v104, s35, v106
	v_fma_f32 v107, v105, s35, v107
	v_pk_fma_f32 v[192:193], v[106:107], v[188:189], v[192:193]
	ds_read_b128 v[64:67], v167 offset:1472
	ds_read_b128 v[68:71], v167 offset:1488
	ds_read_b128 v[72:75], v167 offset:1504
	ds_read_b128 v[76:79], v167 offset:1520
	v_pk_mul_f32 v[98:99], v[192:193], v[186:187]
	s_waitcnt vmcnt(55)
	v_lshlrev_b32_e32 v100, 16, v39
	v_exp_f32_e32 v98, v98
	v_exp_f32_e32 v99, v99
	v_and_b32_e32 v101, 0xffff0000, v39
	v_mov_b32_e32 v96, v198
	v_mov_b32_e32 v97, v199
	v_pk_mul_f32 v[102:103], v[100:101], v[98:99]
	s_waitcnt lgkmcnt(4)
	v_pk_fma_f32 v[96:97], v[80:81], v[232:233], v[96:97] op_sel_hi:[0,1,1]
	v_cvt_pk_bf16_f32 v108, v102, v103
	v_pk_fma_f32 v[96:97], v[80:81], v[234:235], v[96:97] op_sel:[1,0,0] op_sel_hi:[1,1,1]
	global_store_dword v166, v108, s[46:47]
	s_sub_u32 s46, s46, 0x3200
	s_subb_u32 s47, s47, 0
	v_pk_fma_f32 v[96:97], v[82:83], v[236:237], v[96:97] op_sel_hi:[0,1,1]
	v_pk_fma_f32 v[96:97], v[82:83], v[238:239], v[96:97] op_sel:[1,0,0] op_sel_hi:[1,1,1]
	v_pk_fma_f32 v[96:97], v[84:85], v[240:241], v[96:97] op_sel_hi:[0,1,1]
	v_pk_fma_f32 v[96:97], v[84:85], v[242:243], v[96:97] op_sel:[1,0,0] op_sel_hi:[1,1,1]
	v_pk_fma_f32 v[96:97], v[86:87], v[244:245], v[96:97] op_sel_hi:[0,1,1]
	v_pk_fma_f32 v[96:97], v[86:87], v[246:247], v[96:97] op_sel:[1,0,0] op_sel_hi:[1,1,1]
	v_pk_fma_f32 v[96:97], v[88:89], v[248:249], v[96:97] op_sel_hi:[0,1,1]
	v_pk_fma_f32 v[96:97], v[88:89], v[250:251], v[96:97] op_sel:[1,0,0] op_sel_hi:[1,1,1]
	v_pk_fma_f32 v[96:97], v[90:91], v[252:253], v[96:97] op_sel_hi:[0,1,1]
	v_pk_fma_f32 v[96:97], v[90:91], v[254:255], v[96:97] op_sel:[1,0,0] op_sel_hi:[1,1,1]
	v_pk_fma_f32 v[96:97], v[92:93], v[220:221], v[96:97] op_sel_hi:[0,1,1]
	v_pk_fma_f32 v[96:97], v[92:93], v[222:223], v[96:97] op_sel:[1,0,0] op_sel_hi:[1,1,1]
	v_pk_fma_f32 v[96:97], v[94:95], v[224:225], v[96:97] op_sel_hi:[0,1,1]
	v_pk_fma_f32 v[96:97], v[94:95], v[226:227], v[96:97] op_sel:[1,0,0] op_sel_hi:[1,1,1]
	v_mul_f32_e64 v104, |v96|, s34
	v_mul_f32_e64 v105, |v97|, s34
	v_exp_f32_e32 v104, v104
	v_exp_f32_e32 v105, v105
	v_min_f32_e32 v106, 0, v96
	v_min_f32_e32 v107, 0, v97
	v_pk_add_f32 v[104:105], v[104:105], v[190:191]
	v_log_f32_e32 v104, v104
	v_log_f32_e32 v105, v105
	s_nop 0
	v_fma_f32 v106, v104, s35, v106
	v_fma_f32 v107, v105, s35, v107
	v_pk_fma_f32 v[192:193], v[106:107], v[188:189], v[192:193]
	ds_read_b128 v[80:83], v167 offset:1408
	ds_read_b128 v[84:87], v167 offset:1424
	ds_read_b128 v[88:91], v167 offset:1440
	ds_read_b128 v[92:95], v167 offset:1456
	v_pk_mul_f32 v[98:99], v[192:193], v[186:187]
	s_waitcnt vmcnt(54)
; DI unsigned pk2(float a, float b) { f32x2 v = {a, b}; bf16v2_t r = __builtin_convertvector(v, bf16v2_t); return __builtin_bit_cast(unsigned, r); }
; DI void phase_gla_prep(const Params& p, LAS unsigned char* lds) {
;     ...
;             unsigned kw[16];
; #pragma unroll
;             for (int i = 0; i < 16; ++i) kw[i] = *(const unsigned*)(big + (tokb + tg * 16 + i) * 6400 + 1024 + ch0);
; #pragma unroll
;             for (int i = 15; i >= 0; --i) { const int tok = tg * 16 + i;
;                 float z0 = bs0, z1 = bs1;
; #pragma unroll
;                 for (int r = 0; r < 16; ++r) { const float lv = lrs[tok * 16 + r]; z0 += lv * wg0[r]; z1 += lv * wg1[r]; }
;                 *(unsigned*)(big + (tokb + tok) * 6400 + 1024 + ch0) = pk2(__uint_as_float(kw[i] << 16) * __expf(t0), __uint_as_float(kw[i] & 0xffff0000u) * __expf(t1));
;                 t0 += (fminf(z0, 0.f) - __logf(1.f + __expf(-fabsf(z0)))) * (1.f / 16.f); t1 += (fminf(z1, 0.f) - __logf(1.f + __expf(-fabsf(z1)))) * (1.f / 16.f);
	v_lshlrev_b32_e32 v100, 16, v40
	v_exp_f32_e32 v98, v98
	v_exp_f32_e32 v99, v99
	v_and_b32_e32 v101, 0xffff0000, v40
	v_mov_b32_e32 v96, v198
	v_mov_b32_e32 v97, v199
	v_pk_mul_f32 v[102:103], v[100:101], v[98:99]
	s_waitcnt lgkmcnt(4)
	v_pk_fma_f32 v[96:97], v[64:65], v[232:233], v[96:97] op_sel_hi:[0,1,1]
	v_cvt_pk_bf16_f32 v108, v102, v103
	v_pk_fma_f32 v[96:97], v[64:65], v[234:235], v[96:97] op_sel:[1,0,0] op_sel_hi:[1,1,1]
	global_store_dword v166, v108, s[46:47]
	s_sub_u32 s46, s46, 0x3200
	s_subb_u32 s47, s47, 0
	v_pk_fma_f32 v[96:97], v[66:67], v[236:237], v[96:97] op_sel_hi:[0,1,1]
	v_pk_fma_f32 v[96:97], v[66:67], v[238:239], v[96:97] op_sel:[1,0,0] op_sel_hi:[1,1,1]
	v_pk_fma_f32 v[96:97], v[68:69], v[240:241], v[96:97] op_sel_hi:[0,1,1]
	v_pk_fma_f32 v[96:97], v[68:69], v[242:243], v[96:97] op_sel:[1,0,0] op_sel_hi:[1,1,1]
	v_pk_fma_f32 v[96:97], v[70:71], v[244:245], v[96:97] op_sel_hi:[0,1,1]
	v_pk_fma_f32 v[96:97], v[70:71], v[246:247], v[96:97] op_sel:[1,0,0] op_sel_hi:[1,1,1]
	v_pk_fma_f32 v[96:97], v[72:73], v[248:249], v[96:97] op_sel_hi:[0,1,1]
	v_pk_fma_f32 v[96:97], v[72:73], v[250:251], v[96:97] op_sel:[1,0,0] op_sel_hi:[1,1,1]
	v_pk_fma_f32 v[96:97], v[74:75], v[252:253], v[96:97] op_sel_hi:[0,1,1]
	v_pk_fma_f32 v[96:97], v[74:75], v[254:255], v[96:97] op_sel:[1,0,0] op_sel_hi:[1,1,1]
	v_pk_fma_f32 v[96:97], v[76:77], v[220:221], v[96:97] op_sel_hi:[0,1,1]
	v_pk_fma_f32 v[96:97], v[76:77], v[222:223], v[96:97] op_sel:[1,0,0] op_sel_hi:[1,1,1]
	v_pk_fma_f32 v[96:97], v[78:79], v[224:225], v[96:97] op_sel_hi:[0,1,1]
	v_pk_fma_f32 v[96:97], v[78:79], v[226:227], v[96:97] op_sel:[1,0,0] op_sel_hi:[1,1,1]
	v_mul_f32_e64 v104, |v96|, s34
	v_mul_f32_e64 v105, |v97|, s34
	v_exp_f32_e32 v104, v104
	v_exp_f32_e32 v105, v105
	v_min_f32_e32 v106, 0, v96
	v_min_f32_e32 v107, 0, v97
	v_pk_add_f32 v[104:105], v[104:105], v[190:191]
	v_log_f32_e32 v104, v104
	v_log_f32_e32 v105, v105
	s_nop 0
	v_fma_f32 v106, v104, s35, v106
	v_fma_f32 v107, v105, s35, v107
	v_pk_fma_f32 v[192:193], v[106:107], v[188:189], v[192:193]
	ds_read_b128 v[64:67], v167 offset:1344
	ds_read_b128 v[68:71], v167 offset:1360
	ds_read_b128 v[72:75], v167 offset:1376
	ds_read_b128 v[76:79], v167 offset:1392
	v_pk_mul_f32 v[98:99], v[192:193], v[186:187]
	s_waitcnt vmcnt(53)
	v_lshlrev_b32_e32 v100, 16, v41
	v_exp_f32_e32 v98, v98
	v_exp_f32_e32 v99, v99
	v_and_b32_e32 v101, 0xffff0000, v41
	v_mov_b32_e32 v96, v198
	v_mov_b32_e32 v97, v199
	v_pk_mul_f32 v[102:103], v[100:101], v[98:99]
	s_waitcnt lgkmcnt(4)
	v_pk_fma_f32 v[96:97], v[80:81], v[232:233], v[96:97] op_sel_hi:[0,1,1]
	v_cvt_pk_bf16_f32 v108, v102, v103
	v_pk_fma_f32 v[96:97], v[80:81], v[234:235], v[96:97] op_sel:[1,0,0] op_sel_hi:[1,1,1]
	global_store_dword v166, v108, s[46:47]
	s_sub_u32 s46, s46, 0x3200
	s_subb_u32 s47, s47, 0
	v_pk_fma_f32 v[96:97], v[82:83], v[236:237], v[96:97] op_sel_hi:[0,1,1]
	v_pk_fma_f32 v[96:97], v[82:83], v[238:239], v[96:97] op_sel:[1,0,0] op_sel_hi:[1,1,1]
	v_pk_fma_f32 v[96:97], v[84:85], v[240:241], v[96:97] op_sel_hi:[0,1,1]
	v_pk_fma_f32 v[96:97], v[84:85], v[242:243], v[96:97] op_sel:[1,0,0] op_sel_hi:[1,1,1]
	v_pk_fma_f32 v[96:97], v[86:87], v[244:245], v[96:97] op_sel_hi:[0,1,1]
	v_pk_fma_f32 v[96:97], v[86:87], v[246:247], v[96:97] op_sel:[1,0,0] op_sel_hi:[1,1,1]
	v_pk_fma_f32 v[96:97], v[88:89], v[248:249], v[96:97] op_sel_hi:[0,1,1]
	v_pk_fma_f32 v[96:97], v[88:89], v[250:251], v[96:97] op_sel:[1,0,0] op_sel_hi:[1,1,1]
	v_pk_fma_f32 v[96:97], v[90:91], v[252:253], v[96:97] op_sel_hi:[0,1,1]
	v_pk_fma_f32 v[96:97], v[90:91], v[254:255], v[96:97] op_sel:[1,0,0] op_sel_hi:[1,1,1]
	v_pk_fma_f32 v[96:97], v[92:93], v[220:221], v[96:97] op_sel_hi:[0,1,1]
	v_pk_fma_f32 v[96:97], v[92:93], v[222:223], v[96:97] op_sel:[1,0,0] op_sel_hi:[1,1,1]
	v_pk_fma_f32 v[96:97], v[94:95], v[224:225], v[96:97] op_sel_hi:[0,1,1]
	v_pk_fma_f32 v[96:97], v[94:95], v[226:227], v[96:97] op_sel:[1,0,0] op_sel_hi:[1,1,1]
	v_mul_f32_e64 v104, |v96|, s34
	v_mul_f32_e64 v105, |v97|, s34
	v_exp_f32_e32 v104, v104
	v_exp_f32_e32 v105, v105
	v_min_f32_e32 v106, 0, v96
	v_min_f32_e32 v107, 0, v97
	v_pk_add_f32 v[104:105], v[104:105], v[190:191]
	v_log_f32_e32 v104, v104
	v_log_f32_e32 v105, v105
	s_nop 0
	v_fma_f32 v106, v104, s35, v106
	v_fma_f32 v107, v105, s35, v107
	v_pk_fma_f32 v[192:193], v[106:107], v[188:189], v[192:193]
	ds_read_b128 v[80:83], v167 offset:1280
	ds_read_b128 v[84:87], v167 offset:1296
	ds_read_b128 v[88:91], v167 offset:1312
	ds_read_b128 v[92:95], v167 offset:1328
	v_pk_mul_f32 v[98:99], v[192:193], v[186:187]
	s_waitcnt vmcnt(52)
	v_lshlrev_b32_e32 v100, 16, v42
	v_exp_f32_e32 v98, v98
	v_exp_f32_e32 v99, v99
	v_and_b32_e32 v101, 0xffff0000, v42
	v_mov_b32_e32 v96, v198
	v_mov_b32_e32 v97, v199
	v_pk_mul_f32 v[102:103], v[100:101], v[98:99]
	s_waitcnt lgkmcnt(4)
; DI unsigned pk2(float a, float b) { f32x2 v = {a, b}; bf16v2_t r = __builtin_convertvector(v, bf16v2_t); return __builtin_bit_cast(unsigned, r); }
; DI void phase_gla_prep(const Params& p, LAS unsigned char* lds) {
;     ...
;             unsigned kw[16];
; #pragma unroll
;             for (int i = 0; i < 16; ++i) kw[i] = *(const unsigned*)(big + (tokb + tg * 16 + i) * 6400 + 1024 + ch0);
; #pragma unroll
;             for (int i = 15; i >= 0; --i) { const int tok = tg * 16 + i;
;                 float z0 = bs0, z1 = bs1;
; #pragma unroll
;                 for (int r = 0; r < 16; ++r) { const float lv = lrs[tok * 16 + r]; z0 += lv * wg0[r]; z1 += lv * wg1[r]; }
;                 *(unsigned*)(big + (tokb + tok) * 6400 + 1024 + ch0) = pk2(__uint_as_float(kw[i] << 16) * __expf(t0), __uint_as_float(kw[i] & 0xffff0000u) * __expf(t1));
;                 t0 += (fminf(z0, 0.f) - __logf(1.f + __expf(-fabsf(z0)))) * (1.f / 16.f); t1 += (fminf(z1, 0.f) - __logf(1.f + __expf(-fabsf(z1)))) * (1.f / 16.f);
	v_pk_fma_f32 v[96:97], v[64:65], v[232:233], v[96:97] op_sel_hi:[0,1,1]
	v_cvt_pk_bf16_f32 v108, v102, v103
	v_pk_fma_f32 v[96:97], v[64:65], v[234:235], v[96:97] op_sel:[1,0,0] op_sel_hi:[1,1,1]
	global_store_dword v166, v108, s[46:47]
	s_sub_u32 s46, s46, 0x3200
	s_subb_u32 s47, s47, 0
	v_pk_fma_f32 v[96:97], v[66:67], v[236:237], v[96:97] op_sel_hi:[0,1,1]
	v_pk_fma_f32 v[96:97], v[66:67], v[238:239], v[96:97] op_sel:[1,0,0] op_sel_hi:[1,1,1]
	v_pk_fma_f32 v[96:97], v[68:69], v[240:241], v[96:97] op_sel_hi:[0,1,1]
	v_pk_fma_f32 v[96:97], v[68:69], v[242:243], v[96:97] op_sel:[1,0,0] op_sel_hi:[1,1,1]
	v_pk_fma_f32 v[96:97], v[70:71], v[244:245], v[96:97] op_sel_hi:[0,1,1]
	v_pk_fma_f32 v[96:97], v[70:71], v[246:247], v[96:97] op_sel:[1,0,0] op_sel_hi:[1,1,1]
	v_pk_fma_f32 v[96:97], v[72:73], v[248:249], v[96:97] op_sel_hi:[0,1,1]
	v_pk_fma_f32 v[96:97], v[72:73], v[250:251], v[96:97] op_sel:[1,0,0] op_sel_hi:[1,1,1]
	v_pk_fma_f32 v[96:97], v[74:75], v[252:253], v[96:97] op_sel_hi:[0,1,1]
	v_pk_fma_f32 v[96:97], v[74:75], v[254:255], v[96:97] op_sel:[1,0,0] op_sel_hi:[1,1,1]
	v_pk_fma_f32 v[96:97], v[76:77], v[220:221], v[96:97] op_sel_hi:[0,1,1]
	v_pk_fma_f32 v[96:97], v[76:77], v[222:223], v[96:97] op_sel:[1,0,0] op_sel_hi:[1,1,1]
	v_pk_fma_f32 v[96:97], v[78:79], v[224:225], v[96:97] op_sel_hi:[0,1,1]
	v_pk_fma_f32 v[96:97], v[78:79], v[226:227], v[96:97] op_sel:[1,0,0] op_sel_hi:[1,1,1]
	v_mul_f32_e64 v104, |v96|, s34
	v_mul_f32_e64 v105, |v97|, s34
	v_exp_f32_e32 v104, v104
	v_exp_f32_e32 v105, v105
	v_min_f32_e32 v106, 0, v96
	v_min_f32_e32 v107, 0, v97
	v_pk_add_f32 v[104:105], v[104:105], v[190:191]
	v_log_f32_e32 v104, v104
	v_log_f32_e32 v105, v105
	s_nop 0
	v_fma_f32 v106, v104, s35, v106
	v_fma_f32 v107, v105, s35, v107
	v_pk_fma_f32 v[192:193], v[106:107], v[188:189], v[192:193]
	ds_read_b128 v[64:67], v167 offset:1216
	ds_read_b128 v[68:71], v167 offset:1232
	ds_read_b128 v[72:75], v167 offset:1248
	ds_read_b128 v[76:79], v167 offset:1264
	v_pk_mul_f32 v[98:99], v[192:193], v[186:187]
	s_waitcnt vmcnt(51)
	v_lshlrev_b32_e32 v100, 16, v43
	v_exp_f32_e32 v98, v98
	v_exp_f32_e32 v99, v99
	v_and_b32_e32 v101, 0xffff0000, v43
	v_mov_b32_e32 v96, v198
	v_mov_b32_e32 v97, v199
	v_pk_mul_f32 v[102:103], v[100:101], v[98:99]
	s_waitcnt lgkmcnt(4)
	v_pk_fma_f32 v[96:97], v[80:81], v[232:233], v[96:97] op_sel_hi:[0,1,1]
	v_cvt_pk_bf16_f32 v108, v102, v103
	v_pk_fma_f32 v[96:97], v[80:81], v[234:235], v[96:97] op_sel:[1,0,0] op_sel_hi:[1,1,1]
	global_store_dword v166, v108, s[46:47]
	s_sub_u32 s46, s46, 0x3200
	s_subb_u32 s47, s47, 0
	v_pk_fma_f32 v[96:97], v[82:83], v[236:237], v[96:97] op_sel_hi:[0,1,1]
	v_pk_fma_f32 v[96:97], v[82:83], v[238:239], v[96:97] op_sel:[1,0,0] op_sel_hi:[1,1,1]
	v_pk_fma_f32 v[96:97], v[84:85], v[240:241], v[96:97] op_sel_hi:[0,1,1]
	v_pk_fma_f32 v[96:97], v[84:85], v[242:243], v[96:97] op_sel:[1,0,0] op_sel_hi:[1,1,1]
	v_pk_fma_f32 v[96:97], v[86:87], v[244:245], v[96:97] op_sel_hi:[0,1,1]
	v_pk_fma_f32 v[96:97], v[86:87], v[246:247], v[96:97] op_sel:[1,0,0] op_sel_hi:[1,1,1]
	v_pk_fma_f32 v[96:97], v[88:89], v[248:249], v[96:97] op_sel_hi:[0,1,1]
	v_pk_fma_f32 v[96:97], v[88:89], v[250:251], v[96:97] op_sel:[1,0,0] op_sel_hi:[1,1,1]
	v_pk_fma_f32 v[96:97], v[90:91], v[252:253], v[96:97] op_sel_hi:[0,1,1]
	v_pk_fma_f32 v[96:97], v[90:91], v[254:255], v[96:97] op_sel:[1,0,0] op_sel_hi:[1,1,1]
	v_pk_fma_f32 v[96:97], v[92:93], v[220:221], v[96:97] op_sel_hi:[0,1,1]
	v_pk_fma_f32 v[96:97], v[92:93], v[222:223], v[96:97] op_sel:[1,0,0] op_sel_hi:[1,1,1]
	v_pk_fma_f32 v[96:97], v[94:95], v[224:225], v[96:97] op_sel_hi:[0,1,1]
	v_pk_fma_f32 v[96:97], v[94:95], v[226:227], v[96:97] op_sel:[1,0,0] op_sel_hi:[1,1,1]
	v_mul_f32_e64 v104, |v96|, s34
	v_mul_f32_e64 v105, |v97|, s34
	v_exp_f32_e32 v104, v104
	v_exp_f32_e32 v105, v105
	v_min_f32_e32 v106, 0, v96
	v_min_f32_e32 v107, 0, v97
	v_pk_add_f32 v[104:105], v[104:105], v[190:191]
	v_log_f32_e32 v104, v104
	v_log_f32_e32 v105, v105
	s_nop 0
	v_fma_f32 v106, v104, s35, v106
	v_fma_f32 v107, v105, s35, v107
	v_pk_fma_f32 v[192:193], v[106:107], v[188:189], v[192:193]
	ds_read_b128 v[80:83], v167 offset:1152
	ds_read_b128 v[84:87], v167 offset:1168
	ds_read_b128 v[88:91], v167 offset:1184
	ds_read_b128 v[92:95], v167 offset:1200
	v_pk_mul_f32 v[98:99], v[192:193], v[186:187]
	s_waitcnt vmcnt(50)
	v_lshlrev_b32_e32 v100, 16, v44
	v_exp_f32_e32 v98, v98
	v_exp_f32_e32 v99, v99
	v_and_b32_e32 v101, 0xffff0000, v44
	v_mov_b32_e32 v96, v198
	v_mov_b32_e32 v97, v199
	v_pk_mul_f32 v[102:103], v[100:101], v[98:99]
	s_waitcnt lgkmcnt(4)
	v_pk_fma_f32 v[96:97], v[64:65], v[232:233], v[96:97] op_sel_hi:[0,1,1]
	v_cvt_pk_bf16_f32 v108, v102, v103
	v_pk_fma_f32 v[96:97], v[64:65], v[234:235], v[96:97] op_sel:[1,0,0] op_sel_hi:[1,1,1]
	global_store_dword v166, v108, s[46:47]
	s_sub_u32 s46, s46, 0x3200
	s_subb_u32 s47, s47, 0
	v_pk_fma_f32 v[96:97], v[66:67], v[236:237], v[96:97] op_sel_hi:[0,1,1]
	v_pk_fma_f32 v[96:97], v[66:67], v[238:239], v[96:97] op_sel:[1,0,0] op_sel_hi:[1,1,1]
	v_pk_fma_f32 v[96:97], v[68:69], v[240:241], v[96:97] op_sel_hi:[0,1,1]
	v_pk_fma_f32 v[96:97], v[68:69], v[242:243], v[96:97] op_sel:[1,0,0] op_sel_hi:[1,1,1]
	v_pk_fma_f32 v[96:97], v[70:71], v[244:245], v[96:97] op_sel_hi:[0,1,1]
	v_pk_fma_f32 v[96:97], v[70:71], v[246:247], v[96:97] op_sel:[1,0,0] op_sel_hi:[1,1,1]
	v_pk_fma_f32 v[96:97], v[72:73], v[248:249], v[96:97] op_sel_hi:[0,1,1]
	v_pk_fma_f32 v[96:97], v[72:73], v[250:251], v[96:97] op_sel:[1,0,0] op_sel_hi:[1,1,1]
	v_pk_fma_f32 v[96:97], v[74:75], v[252:253], v[96:97] op_sel_hi:[0,1,1]
	v_pk_fma_f32 v[96:97], v[74:75], v[254:255], v[96:97] op_sel:[1,0,0] op_sel_hi:[1,1,1]
	v_pk_fma_f32 v[96:97], v[76:77], v[220:221], v[96:97] op_sel_hi:[0,1,1]
	v_pk_fma_f32 v[96:97], v[76:77], v[222:223], v[96:97] op_sel:[1,0,0] op_sel_hi:[1,1,1]
	v_pk_fma_f32 v[96:97], v[78:79], v[224:225], v[96:97] op_sel_hi:[0,1,1]
	v_pk_fma_f32 v[96:97], v[78:79], v[226:227], v[96:97] op_sel:[1,0,0] op_sel_hi:[1,1,1]
	v_mul_f32_e64 v104, |v96|, s34
	v_mul_f32_e64 v105, |v97|, s34
	v_exp_f32_e32 v104, v104
	v_exp_f32_e32 v105, v105
	v_min_f32_e32 v106, 0, v96
	v_min_f32_e32 v107, 0, v97
	v_pk_add_f32 v[104:105], v[104:105], v[190:191]
	v_log_f32_e32 v104, v104
	v_log_f32_e32 v105, v105
	s_nop 0
	v_fma_f32 v106, v104, s35, v106
	v_fma_f32 v107, v105, s35, v107
	v_pk_fma_f32 v[192:193], v[106:107], v[188:189], v[192:193]
	ds_read_b128 v[64:67], v167 offset:1088
	ds_read_b128 v[68:71], v167 offset:1104
	ds_read_b128 v[72:75], v167 offset:1120
	ds_read_b128 v[76:79], v167 offset:1136
	v_pk_mul_f32 v[98:99], v[192:193], v[186:187]
	s_waitcnt vmcnt(49)
; DI unsigned pk2(float a, float b) { f32x2 v = {a, b}; bf16v2_t r = __builtin_convertvector(v, bf16v2_t); return __builtin_bit_cast(unsigned, r); }
; DI void phase_gla_prep(const Params& p, LAS unsigned char* lds) {
;     ...
;             unsigned kw[16];
; #pragma unroll
;             for (int i = 0; i < 16; ++i) kw[i] = *(const unsigned*)(big + (tokb + tg * 16 + i) * 6400 + 1024 + ch0);
; #pragma unroll
;             for (int i = 15; i >= 0; --i) { const int tok = tg * 16 + i;
;                 float z0 = bs0, z1 = bs1;
; #pragma unroll
;                 for (int r = 0; r < 16; ++r) { const float lv = lrs[tok * 16 + r]; z0 += lv * wg0[r]; z1 += lv * wg1[r]; }
;                 *(unsigned*)(big + (tokb + tok) * 6400 + 1024 + ch0) = pk2(__uint_as_float(kw[i] << 16) * __expf(t0), __uint_as_float(kw[i] & 0xffff0000u) * __expf(t1));
;                 t0 += (fminf(z0, 0.f) - __logf(1.f + __expf(-fabsf(z0)))) * (1.f / 16.f); t1 += (fminf(z1, 0.f) - __logf(1.f + __expf(-fabsf(z1)))) * (1.f / 16.f);
	v_lshlrev_b32_e32 v100, 16, v45
	v_exp_f32_e32 v98, v98
	v_exp_f32_e32 v99, v99
	v_and_b32_e32 v101, 0xffff0000, v45
	v_mov_b32_e32 v96, v198
	v_mov_b32_e32 v97, v199
	v_pk_mul_f32 v[102:103], v[100:101], v[98:99]
	s_waitcnt lgkmcnt(4)
	v_pk_fma_f32 v[96:97], v[80:81], v[232:233], v[96:97] op_sel_hi:[0,1,1]
	v_cvt_pk_bf16_f32 v108, v102, v103
	v_pk_fma_f32 v[96:97], v[80:81], v[234:235], v[96:97] op_sel:[1,0,0] op_sel_hi:[1,1,1]
	global_store_dword v166, v108, s[46:47]
	s_sub_u32 s46, s46, 0x3200
	s_subb_u32 s47, s47, 0
	v_pk_fma_f32 v[96:97], v[82:83], v[236:237], v[96:97] op_sel_hi:[0,1,1]
	v_pk_fma_f32 v[96:97], v[82:83], v[238:239], v[96:97] op_sel:[1,0,0] op_sel_hi:[1,1,1]
	v_pk_fma_f32 v[96:97], v[84:85], v[240:241], v[96:97] op_sel_hi:[0,1,1]
	v_pk_fma_f32 v[96:97], v[84:85], v[242:243], v[96:97] op_sel:[1,0,0] op_sel_hi:[1,1,1]
	v_pk_fma_f32 v[96:97], v[86:87], v[244:245], v[96:97] op_sel_hi:[0,1,1]
	v_pk_fma_f32 v[96:97], v[86:87], v[246:247], v[96:97] op_sel:[1,0,0] op_sel_hi:[1,1,1]
	v_pk_fma_f32 v[96:97], v[88:89], v[248:249], v[96:97] op_sel_hi:[0,1,1]
	v_pk_fma_f32 v[96:97], v[88:89], v[250:251], v[96:97] op_sel:[1,0,0] op_sel_hi:[1,1,1]
	v_pk_fma_f32 v[96:97], v[90:91], v[252:253], v[96:97] op_sel_hi:[0,1,1]
	v_pk_fma_f32 v[96:97], v[90:91], v[254:255], v[96:97] op_sel:[1,0,0] op_sel_hi:[1,1,1]
	v_pk_fma_f32 v[96:97], v[92:93], v[220:221], v[96:97] op_sel_hi:[0,1,1]
	v_pk_fma_f32 v[96:97], v[92:93], v[222:223], v[96:97] op_sel:[1,0,0] op_sel_hi:[1,1,1]
	v_pk_fma_f32 v[96:97], v[94:95], v[224:225], v[96:97] op_sel_hi:[0,1,1]
	v_pk_fma_f32 v[96:97], v[94:95], v[226:227], v[96:97] op_sel:[1,0,0] op_sel_hi:[1,1,1]
	v_mul_f32_e64 v104, |v96|, s34
	v_mul_f32_e64 v105, |v97|, s34
	v_exp_f32_e32 v104, v104
	v_exp_f32_e32 v105, v105
	v_min_f32_e32 v106, 0, v96
	v_min_f32_e32 v107, 0, v97
	v_pk_add_f32 v[104:105], v[104:105], v[190:191]
	v_log_f32_e32 v104, v104
	v_log_f32_e32 v105, v105
	s_nop 0
	v_fma_f32 v106, v104, s35, v106
	v_fma_f32 v107, v105, s35, v107
	v_pk_fma_f32 v[192:193], v[106:107], v[188:189], v[192:193]
	ds_read_b128 v[80:83], v167 offset:1024
	ds_read_b128 v[84:87], v167 offset:1040
	ds_read_b128 v[88:91], v167 offset:1056
	ds_read_b128 v[92:95], v167 offset:1072
	v_pk_mul_f32 v[98:99], v[192:193], v[186:187]
	s_waitcnt vmcnt(48)
	v_lshlrev_b32_e32 v100, 16, v46
	v_exp_f32_e32 v98, v98
	v_exp_f32_e32 v99, v99
	v_and_b32_e32 v101, 0xffff0000, v46
	v_mov_b32_e32 v96, v198
	v_mov_b32_e32 v97, v199
	v_pk_mul_f32 v[102:103], v[100:101], v[98:99]
	s_waitcnt lgkmcnt(4)
	v_pk_fma_f32 v[96:97], v[64:65], v[232:233], v[96:97] op_sel_hi:[0,1,1]
	v_cvt_pk_bf16_f32 v108, v102, v103
	v_pk_fma_f32 v[96:97], v[64:65], v[234:235], v[96:97] op_sel:[1,0,0] op_sel_hi:[1,1,1]
	global_store_dword v166, v108, s[46:47]
	s_sub_u32 s46, s46, 0x3200
	s_subb_u32 s47, s47, 0
	v_pk_fma_f32 v[96:97], v[66:67], v[236:237], v[96:97] op_sel_hi:[0,1,1]
	v_pk_fma_f32 v[96:97], v[66:67], v[238:239], v[96:97] op_sel:[1,0,0] op_sel_hi:[1,1,1]
	v_pk_fma_f32 v[96:97], v[68:69], v[240:241], v[96:97] op_sel_hi:[0,1,1]
	v_pk_fma_f32 v[96:97], v[68:69], v[242:243], v[96:97] op_sel:[1,0,0] op_sel_hi:[1,1,1]
	v_pk_fma_f32 v[96:97], v[70:71], v[244:245], v[96:97] op_sel_hi:[0,1,1]
	v_pk_fma_f32 v[96:97], v[70:71], v[246:247], v[96:97] op_sel:[1,0,0] op_sel_hi:[1,1,1]
	v_pk_fma_f32 v[96:97], v[72:73], v[248:249], v[96:97] op_sel_hi:[0,1,1]
	v_pk_fma_f32 v[96:97], v[72:73], v[250:251], v[96:97] op_sel:[1,0,0] op_sel_hi:[1,1,1]
	v_pk_fma_f32 v[96:97], v[74:75], v[252:253], v[96:97] op_sel_hi:[0,1,1]
	v_pk_fma_f32 v[96:97], v[74:75], v[254:255], v[96:97] op_sel:[1,0,0] op_sel_hi:[1,1,1]
	v_pk_fma_f32 v[96:97], v[76:77], v[220:221], v[96:97] op_sel_hi:[0,1,1]
	v_pk_fma_f32 v[96:97], v[76:77], v[222:223], v[96:97] op_sel:[1,0,0] op_sel_hi:[1,1,1]
	v_pk_fma_f32 v[96:97], v[78:79], v[224:225], v[96:97] op_sel_hi:[0,1,1]
	v_pk_fma_f32 v[96:97], v[78:79], v[226:227], v[96:97] op_sel:[1,0,0] op_sel_hi:[1,1,1]
	v_mul_f32_e64 v104, |v96|, s34
	v_mul_f32_e64 v105, |v97|, s34
	v_exp_f32_e32 v104, v104
	v_exp_f32_e32 v105, v105
	v_min_f32_e32 v106, 0, v96
	v_min_f32_e32 v107, 0, v97
	v_pk_add_f32 v[104:105], v[104:105], v[190:191]
	v_log_f32_e32 v104, v104
	v_log_f32_e32 v105, v105
	s_nop 0
	v_fma_f32 v106, v104, s35, v106
	v_fma_f32 v107, v105, s35, v107
	v_pk_fma_f32 v[192:193], v[106:107], v[188:189], v[192:193]
	ds_read_b128 v[64:67], v167 offset:960
	ds_read_b128 v[68:71], v167 offset:976
	ds_read_b128 v[72:75], v167 offset:992
	ds_read_b128 v[76:79], v167 offset:1008
	v_pk_mul_f32 v[98:99], v[192:193], v[186:187]
	s_waitcnt vmcnt(47)
	v_lshlrev_b32_e32 v100, 16, v47
	v_exp_f32_e32 v98, v98
	v_exp_f32_e32 v99, v99
	v_and_b32_e32 v101, 0xffff0000, v47
	v_mov_b32_e32 v96, v198
	v_mov_b32_e32 v97, v199
	v_pk_mul_f32 v[102:103], v[100:101], v[98:99]
	s_waitcnt lgkmcnt(4)
; DI unsigned pk2(float a, float b) { f32x2 v = {a, b}; bf16v2_t r = __builtin_convertvector(v, bf16v2_t); return __builtin_bit_cast(unsigned, r); }
; DI void phase_gla_prep(const Params& p, LAS unsigned char* lds) {
;     ...
;             unsigned kw[16];
; #pragma unroll
;             for (int i = 0; i < 16; ++i) kw[i] = *(const unsigned*)(big + (tokb + tg * 16 + i) * 6400 + 1024 + ch0);
; #pragma unroll
;             for (int i = 15; i >= 0; --i) { const int tok = tg * 16 + i;
;                 float z0 = bs0, z1 = bs1;
; #pragma unroll
;                 for (int r = 0; r < 16; ++r) { const float lv = lrs[tok * 16 + r]; z0 += lv * wg0[r]; z1 += lv * wg1[r]; }
;                 *(unsigned*)(big + (tokb + tok) * 6400 + 1024 + ch0) = pk2(__uint_as_float(kw[i] << 16) * __expf(t0), __uint_as_float(kw[i] & 0xffff0000u) * __expf(t1));
;                 t0 += (fminf(z0, 0.f) - __logf(1.f + __expf(-fabsf(z0)))) * (1.f / 16.f); t1 += (fminf(z1, 0.f) - __logf(1.f + __expf(-fabsf(z1)))) * (1.f / 16.f);
	v_pk_fma_f32 v[96:97], v[80:81], v[232:233], v[96:97] op_sel_hi:[0,1,1]
	v_cvt_pk_bf16_f32 v108, v102, v103
	v_pk_fma_f32 v[96:97], v[80:81], v[234:235], v[96:97] op_sel:[1,0,0] op_sel_hi:[1,1,1]
	global_store_dword v166, v108, s[46:47]
	s_sub_u32 s46, s46, 0x3200
	s_subb_u32 s47, s47, 0
	v_pk_fma_f32 v[96:97], v[82:83], v[236:237], v[96:97] op_sel_hi:[0,1,1]
	v_pk_fma_f32 v[96:97], v[82:83], v[238:239], v[96:97] op_sel:[1,0,0] op_sel_hi:[1,1,1]
	v_pk_fma_f32 v[96:97], v[84:85], v[240:241], v[96:97] op_sel_hi:[0,1,1]
	v_pk_fma_f32 v[96:97], v[84:85], v[242:243], v[96:97] op_sel:[1,0,0] op_sel_hi:[1,1,1]
	v_pk_fma_f32 v[96:97], v[86:87], v[244:245], v[96:97] op_sel_hi:[0,1,1]
	v_pk_fma_f32 v[96:97], v[86:87], v[246:247], v[96:97] op_sel:[1,0,0] op_sel_hi:[1,1,1]
	v_pk_fma_f32 v[96:97], v[88:89], v[248:249], v[96:97] op_sel_hi:[0,1,1]
	v_pk_fma_f32 v[96:97], v[88:89], v[250:251], v[96:97] op_sel:[1,0,0] op_sel_hi:[1,1,1]
	v_pk_fma_f32 v[96:97], v[90:91], v[252:253], v[96:97] op_sel_hi:[0,1,1]
	v_pk_fma_f32 v[96:97], v[90:91], v[254:255], v[96:97] op_sel:[1,0,0] op_sel_hi:[1,1,1]
	v_pk_fma_f32 v[96:97], v[92:93], v[220:221], v[96:97] op_sel_hi:[0,1,1]
	v_pk_fma_f32 v[96:97], v[92:93], v[222:223], v[96:97] op_sel:[1,0,0] op_sel_hi:[1,1,1]
	v_pk_fma_f32 v[96:97], v[94:95], v[224:225], v[96:97] op_sel_hi:[0,1,1]
	v_pk_fma_f32 v[96:97], v[94:95], v[226:227], v[96:97] op_sel:[1,0,0] op_sel_hi:[1,1,1]
	v_mul_f32_e64 v104, |v96|, s34
	v_mul_f32_e64 v105, |v97|, s34
	v_exp_f32_e32 v104, v104
	v_exp_f32_e32 v105, v105
	v_min_f32_e32 v106, 0, v96
	v_min_f32_e32 v107, 0, v97
	v_pk_add_f32 v[104:105], v[104:105], v[190:191]
	v_log_f32_e32 v104, v104
	v_log_f32_e32 v105, v105
	s_nop 0
	v_fma_f32 v106, v104, s35, v106
	v_fma_f32 v107, v105, s35, v107
	v_pk_fma_f32 v[192:193], v[106:107], v[188:189], v[192:193]
	ds_read_b128 v[80:83], v167 offset:896
	ds_read_b128 v[84:87], v167 offset:912
	ds_read_b128 v[88:91], v167 offset:928
	ds_read_b128 v[92:95], v167 offset:944
	v_pk_mul_f32 v[98:99], v[192:193], v[186:187]
	s_waitcnt vmcnt(46)
	v_lshlrev_b32_e32 v100, 16, v48
	v_exp_f32_e32 v98, v98
	v_exp_f32_e32 v99, v99
	v_and_b32_e32 v101, 0xffff0000, v48
	v_mov_b32_e32 v96, v198
	v_mov_b32_e32 v97, v199
	v_pk_mul_f32 v[102:103], v[100:101], v[98:99]
	s_waitcnt lgkmcnt(4)
	v_pk_fma_f32 v[96:97], v[64:65], v[232:233], v[96:97] op_sel_hi:[0,1,1]
	v_cvt_pk_bf16_f32 v108, v102, v103
	v_pk_fma_f32 v[96:97], v[64:65], v[234:235], v[96:97] op_sel:[1,0,0] op_sel_hi:[1,1,1]
	global_store_dword v166, v108, s[46:47]
	s_sub_u32 s46, s46, 0x3200
	s_subb_u32 s47, s47, 0
	v_pk_fma_f32 v[96:97], v[66:67], v[236:237], v[96:97] op_sel_hi:[0,1,1]
	v_pk_fma_f32 v[96:97], v[66:67], v[238:239], v[96:97] op_sel:[1,0,0] op_sel_hi:[1,1,1]
	v_pk_fma_f32 v[96:97], v[68:69], v[240:241], v[96:97] op_sel_hi:[0,1,1]
	v_pk_fma_f32 v[96:97], v[68:69], v[242:243], v[96:97] op_sel:[1,0,0] op_sel_hi:[1,1,1]
	v_pk_fma_f32 v[96:97], v[70:71], v[244:245], v[96:97] op_sel_hi:[0,1,1]
	v_pk_fma_f32 v[96:97], v[70:71], v[246:247], v[96:97] op_sel:[1,0,0] op_sel_hi:[1,1,1]
	v_pk_fma_f32 v[96:97], v[72:73], v[248:249], v[96:97] op_sel_hi:[0,1,1]
	v_pk_fma_f32 v[96:97], v[72:73], v[250:251], v[96:97] op_sel:[1,0,0] op_sel_hi:[1,1,1]
	v_pk_fma_f32 v[96:97], v[74:75], v[252:253], v[96:97] op_sel_hi:[0,1,1]
	v_pk_fma_f32 v[96:97], v[74:75], v[254:255], v[96:97] op_sel:[1,0,0] op_sel_hi:[1,1,1]
	v_pk_fma_f32 v[96:97], v[76:77], v[220:221], v[96:97] op_sel_hi:[0,1,1]
	v_pk_fma_f32 v[96:97], v[76:77], v[222:223], v[96:97] op_sel:[1,0,0] op_sel_hi:[1,1,1]
	v_pk_fma_f32 v[96:97], v[78:79], v[224:225], v[96:97] op_sel_hi:[0,1,1]
	v_pk_fma_f32 v[96:97], v[78:79], v[226:227], v[96:97] op_sel:[1,0,0] op_sel_hi:[1,1,1]
	v_mul_f32_e64 v104, |v96|, s34
	v_mul_f32_e64 v105, |v97|, s34
	v_exp_f32_e32 v104, v104
	v_exp_f32_e32 v105, v105
	v_min_f32_e32 v106, 0, v96
	v_min_f32_e32 v107, 0, v97
	v_pk_add_f32 v[104:105], v[104:105], v[190:191]
	v_log_f32_e32 v104, v104
	v_log_f32_e32 v105, v105
	s_nop 0
	v_fma_f32 v106, v104, s35, v106
	v_fma_f32 v107, v105, s35, v107
	v_pk_fma_f32 v[192:193], v[106:107], v[188:189], v[192:193]
	ds_read_b128 v[64:67], v167 offset:832
	ds_read_b128 v[68:71], v167 offset:848
	ds_read_b128 v[72:75], v167 offset:864
	ds_read_b128 v[76:79], v167 offset:880
	v_pk_mul_f32 v[98:99], v[192:193], v[186:187]
	s_waitcnt vmcnt(45)
	v_lshlrev_b32_e32 v100, 16, v49
	v_exp_f32_e32 v98, v98
	v_exp_f32_e32 v99, v99
	v_and_b32_e32 v101, 0xffff0000, v49
	v_mov_b32_e32 v96, v198
	v_mov_b32_e32 v97, v199
	v_pk_mul_f32 v[102:103], v[100:101], v[98:99]
	s_waitcnt lgkmcnt(4)
	v_pk_fma_f32 v[96:97], v[80:81], v[232:233], v[96:97] op_sel_hi:[0,1,1]
	v_cvt_pk_bf16_f32 v108, v102, v103
	v_pk_fma_f32 v[96:97], v[80:81], v[234:235], v[96:97] op_sel:[1,0,0] op_sel_hi:[1,1,1]
	global_store_dword v166, v108, s[46:47]
	s_sub_u32 s46, s46, 0x3200
	s_subb_u32 s47, s47, 0
	v_pk_fma_f32 v[96:97], v[82:83], v[236:237], v[96:97] op_sel_hi:[0,1,1]
	v_pk_fma_f32 v[96:97], v[82:83], v[238:239], v[96:97] op_sel:[1,0,0] op_sel_hi:[1,1,1]
	v_pk_fma_f32 v[96:97], v[84:85], v[240:241], v[96:97] op_sel_hi:[0,1,1]
	v_pk_fma_f32 v[96:97], v[84:85], v[242:243], v[96:97] op_sel:[1,0,0] op_sel_hi:[1,1,1]
	v_pk_fma_f32 v[96:97], v[86:87], v[244:245], v[96:97] op_sel_hi:[0,1,1]
	v_pk_fma_f32 v[96:97], v[86:87], v[246:247], v[96:97] op_sel:[1,0,0] op_sel_hi:[1,1,1]
	v_pk_fma_f32 v[96:97], v[88:89], v[248:249], v[96:97] op_sel_hi:[0,1,1]
	v_pk_fma_f32 v[96:97], v[88:89], v[250:251], v[96:97] op_sel:[1,0,0] op_sel_hi:[1,1,1]
	v_pk_fma_f32 v[96:97], v[90:91], v[252:253], v[96:97] op_sel_hi:[0,1,1]
	v_pk_fma_f32 v[96:97], v[90:91], v[254:255], v[96:97] op_sel:[1,0,0] op_sel_hi:[1,1,1]
	v_pk_fma_f32 v[96:97], v[92:93], v[220:221], v[96:97] op_sel_hi:[0,1,1]
	v_pk_fma_f32 v[96:97], v[92:93], v[222:223], v[96:97] op_sel:[1,0,0] op_sel_hi:[1,1,1]
	v_pk_fma_f32 v[96:97], v[94:95], v[224:225], v[96:97] op_sel_hi:[0,1,1]
	v_pk_fma_f32 v[96:97], v[94:95], v[226:227], v[96:97] op_sel:[1,0,0] op_sel_hi:[1,1,1]
	v_mul_f32_e64 v104, |v96|, s34
	v_mul_f32_e64 v105, |v97|, s34
	v_exp_f32_e32 v104, v104
	v_exp_f32_e32 v105, v105
	v_min_f32_e32 v106, 0, v96
	v_min_f32_e32 v107, 0, v97
	v_pk_add_f32 v[104:105], v[104:105], v[190:191]
	v_log_f32_e32 v104, v104
	v_log_f32_e32 v105, v105
	s_nop 0
	v_fma_f32 v106, v104, s35, v106
	v_fma_f32 v107, v105, s35, v107
	v_pk_fma_f32 v[192:193], v[106:107], v[188:189], v[192:193]
	ds_read_b128 v[80:83], v167 offset:768
	ds_read_b128 v[84:87], v167 offset:784
	ds_read_b128 v[88:91], v167 offset:800
	ds_read_b128 v[92:95], v167 offset:816
	v_pk_mul_f32 v[98:99], v[192:193], v[186:187]
	s_waitcnt vmcnt(44)
; DI unsigned pk2(float a, float b) { f32x2 v = {a, b}; bf16v2_t r = __builtin_convertvector(v, bf16v2_t); return __builtin_bit_cast(unsigned, r); }
; DI void phase_gla_prep(const Params& p, LAS unsigned char* lds) {
;     ...
;             unsigned kw[16];
; #pragma unroll
;             for (int i = 0; i < 16; ++i) kw[i] = *(const unsigned*)(big + (tokb + tg * 16 + i) * 6400 + 1024 + ch0);
; #pragma unroll
;             for (int i = 15; i >= 0; --i) { const int tok = tg * 16 + i;
;                 float z0 = bs0, z1 = bs1;
; #pragma unroll
;                 for (int r = 0; r < 16; ++r) { const float lv = lrs[tok * 16 + r]; z0 += lv * wg0[r]; z1 += lv * wg1[r]; }
;                 *(unsigned*)(big + (tokb + tok) * 6400 + 1024 + ch0) = pk2(__uint_as_float(kw[i] << 16) * __expf(t0), __uint_as_float(kw[i] & 0xffff0000u) * __expf(t1));
;                 t0 += (fminf(z0, 0.f) - __logf(1.f + __expf(-fabsf(z0)))) * (1.f / 16.f); t1 += (fminf(z1, 0.f) - __logf(1.f + __expf(-fabsf(z1)))) * (1.f / 16.f);
	v_lshlrev_b32_e32 v100, 16, v50
	v_exp_f32_e32 v98, v98
	v_exp_f32_e32 v99, v99
	v_and_b32_e32 v101, 0xffff0000, v50
	v_mov_b32_e32 v96, v198
	v_mov_b32_e32 v97, v199
	v_pk_mul_f32 v[102:103], v[100:101], v[98:99]
	s_waitcnt lgkmcnt(4)
	v_pk_fma_f32 v[96:97], v[64:65], v[232:233], v[96:97] op_sel_hi:[0,1,1]
	v_cvt_pk_bf16_f32 v108, v102, v103
	v_pk_fma_f32 v[96:97], v[64:65], v[234:235], v[96:97] op_sel:[1,0,0] op_sel_hi:[1,1,1]
	global_store_dword v166, v108, s[46:47]
	s_sub_u32 s46, s46, 0x3200
	s_subb_u32 s47, s47, 0
	v_pk_fma_f32 v[96:97], v[66:67], v[236:237], v[96:97] op_sel_hi:[0,1,1]
	v_pk_fma_f32 v[96:97], v[66:67], v[238:239], v[96:97] op_sel:[1,0,0] op_sel_hi:[1,1,1]
	v_pk_fma_f32 v[96:97], v[68:69], v[240:241], v[96:97] op_sel_hi:[0,1,1]
	v_pk_fma_f32 v[96:97], v[68:69], v[242:243], v[96:97] op_sel:[1,0,0] op_sel_hi:[1,1,1]
	v_pk_fma_f32 v[96:97], v[70:71], v[244:245], v[96:97] op_sel_hi:[0,1,1]
	v_pk_fma_f32 v[96:97], v[70:71], v[246:247], v[96:97] op_sel:[1,0,0] op_sel_hi:[1,1,1]
	v_pk_fma_f32 v[96:97], v[72:73], v[248:249], v[96:97] op_sel_hi:[0,1,1]
	v_pk_fma_f32 v[96:97], v[72:73], v[250:251], v[96:97] op_sel:[1,0,0] op_sel_hi:[1,1,1]
	v_pk_fma_f32 v[96:97], v[74:75], v[252:253], v[96:97] op_sel_hi:[0,1,1]
	v_pk_fma_f32 v[96:97], v[74:75], v[254:255], v[96:97] op_sel:[1,0,0] op_sel_hi:[1,1,1]
	v_pk_fma_f32 v[96:97], v[76:77], v[220:221], v[96:97] op_sel_hi:[0,1,1]
	v_pk_fma_f32 v[96:97], v[76:77], v[222:223], v[96:97] op_sel:[1,0,0] op_sel_hi:[1,1,1]
	v_pk_fma_f32 v[96:97], v[78:79], v[224:225], v[96:97] op_sel_hi:[0,1,1]
	v_pk_fma_f32 v[96:97], v[78:79], v[226:227], v[96:97] op_sel:[1,0,0] op_sel_hi:[1,1,1]
	v_mul_f32_e64 v104, |v96|, s34
	v_mul_f32_e64 v105, |v97|, s34
	v_exp_f32_e32 v104, v104
	v_exp_f32_e32 v105, v105
	v_min_f32_e32 v106, 0, v96
	v_min_f32_e32 v107, 0, v97
	v_pk_add_f32 v[104:105], v[104:105], v[190:191]
	v_log_f32_e32 v104, v104
	v_log_f32_e32 v105, v105
	s_nop 0
	v_fma_f32 v106, v104, s35, v106
	v_fma_f32 v107, v105, s35, v107
	v_pk_fma_f32 v[192:193], v[106:107], v[188:189], v[192:193]
	ds_read_b128 v[64:67], v167 offset:704
	ds_read_b128 v[68:71], v167 offset:720
	ds_read_b128 v[72:75], v167 offset:736
	ds_read_b128 v[76:79], v167 offset:752
	v_pk_mul_f32 v[98:99], v[192:193], v[186:187]
	s_waitcnt vmcnt(43)
	v_lshlrev_b32_e32 v100, 16, v51
	v_exp_f32_e32 v98, v98
	v_exp_f32_e32 v99, v99
	v_and_b32_e32 v101, 0xffff0000, v51
	v_mov_b32_e32 v96, v198
	v_mov_b32_e32 v97, v199
	v_pk_mul_f32 v[102:103], v[100:101], v[98:99]
	s_waitcnt lgkmcnt(4)
	v_pk_fma_f32 v[96:97], v[80:81], v[232:233], v[96:97] op_sel_hi:[0,1,1]
	v_cvt_pk_bf16_f32 v108, v102, v103
	v_pk_fma_f32 v[96:97], v[80:81], v[234:235], v[96:97] op_sel:[1,0,0] op_sel_hi:[1,1,1]
	global_store_dword v166, v108, s[46:47]
	s_sub_u32 s46, s46, 0x3200
	s_subb_u32 s47, s47, 0
	v_pk_fma_f32 v[96:97], v[82:83], v[236:237], v[96:97] op_sel_hi:[0,1,1]
	v_pk_fma_f32 v[96:97], v[82:83], v[238:239], v[96:97] op_sel:[1,0,0] op_sel_hi:[1,1,1]
	v_pk_fma_f32 v[96:97], v[84:85], v[240:241], v[96:97] op_sel_hi:[0,1,1]
	v_pk_fma_f32 v[96:97], v[84:85], v[242:243], v[96:97] op_sel:[1,0,0] op_sel_hi:[1,1,1]
	v_pk_fma_f32 v[96:97], v[86:87], v[244:245], v[96:97] op_sel_hi:[0,1,1]
	v_pk_fma_f32 v[96:97], v[86:87], v[246:247], v[96:97] op_sel:[1,0,0] op_sel_hi:[1,1,1]
	v_pk_fma_f32 v[96:97], v[88:89], v[248:249], v[96:97] op_sel_hi:[0,1,1]
	v_pk_fma_f32 v[96:97], v[88:89], v[250:251], v[96:97] op_sel:[1,0,0] op_sel_hi:[1,1,1]
	v_pk_fma_f32 v[96:97], v[90:91], v[252:253], v[96:97] op_sel_hi:[0,1,1]
	v_pk_fma_f32 v[96:97], v[90:91], v[254:255], v[96:97] op_sel:[1,0,0] op_sel_hi:[1,1,1]
	v_pk_fma_f32 v[96:97], v[92:93], v[220:221], v[96:97] op_sel_hi:[0,1,1]
	v_pk_fma_f32 v[96:97], v[92:93], v[222:223], v[96:97] op_sel:[1,0,0] op_sel_hi:[1,1,1]
	v_pk_fma_f32 v[96:97], v[94:95], v[224:225], v[96:97] op_sel_hi:[0,1,1]
	v_pk_fma_f32 v[96:97], v[94:95], v[226:227], v[96:97] op_sel:[1,0,0] op_sel_hi:[1,1,1]
	v_mul_f32_e64 v104, |v96|, s34
	v_mul_f32_e64 v105, |v97|, s34
	v_exp_f32_e32 v104, v104
	v_exp_f32_e32 v105, v105
	v_min_f32_e32 v106, 0, v96
	v_min_f32_e32 v107, 0, v97
	v_pk_add_f32 v[104:105], v[104:105], v[190:191]
	v_log_f32_e32 v104, v104
	v_log_f32_e32 v105, v105
	s_nop 0
	v_fma_f32 v106, v104, s35, v106
	v_fma_f32 v107, v105, s35, v107
	v_pk_fma_f32 v[192:193], v[106:107], v[188:189], v[192:193]
	ds_read_b128 v[80:83], v167 offset:640
	ds_read_b128 v[84:87], v167 offset:656
	ds_read_b128 v[88:91], v167 offset:672
	ds_read_b128 v[92:95], v167 offset:688
	v_pk_mul_f32 v[98:99], v[192:193], v[186:187]
	s_waitcnt vmcnt(42)
	v_lshlrev_b32_e32 v100, 16, v52
	v_exp_f32_e32 v98, v98
	v_exp_f32_e32 v99, v99
	v_and_b32_e32 v101, 0xffff0000, v52
	v_mov_b32_e32 v96, v198
	v_mov_b32_e32 v97, v199
	v_pk_mul_f32 v[102:103], v[100:101], v[98:99]
	s_waitcnt lgkmcnt(4)
; DI unsigned pk2(float a, float b) { f32x2 v = {a, b}; bf16v2_t r = __builtin_convertvector(v, bf16v2_t); return __builtin_bit_cast(unsigned, r); }
; DI void phase_gla_prep(const Params& p, LAS unsigned char* lds) {
;     ...
;             unsigned kw[16];
; #pragma unroll
;             for (int i = 0; i < 16; ++i) kw[i] = *(const unsigned*)(big + (tokb + tg * 16 + i) * 6400 + 1024 + ch0);
; #pragma unroll
;             for (int i = 15; i >= 0; --i) { const int tok = tg * 16 + i;
;                 float z0 = bs0, z1 = bs1;
; #pragma unroll
;                 for (int r = 0; r < 16; ++r) { const float lv = lrs[tok * 16 + r]; z0 += lv * wg0[r]; z1 += lv * wg1[r]; }
;                 *(unsigned*)(big + (tokb + tok) * 6400 + 1024 + ch0) = pk2(__uint_as_float(kw[i] << 16) * __expf(t0), __uint_as_float(kw[i] & 0xffff0000u) * __expf(t1));
;                 t0 += (fminf(z0, 0.f) - __logf(1.f + __expf(-fabsf(z0)))) * (1.f / 16.f); t1 += (fminf(z1, 0.f) - __logf(1.f + __expf(-fabsf(z1)))) * (1.f / 16.f);
	v_pk_fma_f32 v[96:97], v[64:65], v[232:233], v[96:97] op_sel_hi:[0,1,1]
	v_cvt_pk_bf16_f32 v108, v102, v103
	v_pk_fma_f32 v[96:97], v[64:65], v[234:235], v[96:97] op_sel:[1,0,0] op_sel_hi:[1,1,1]
	global_store_dword v166, v108, s[46:47]
	s_sub_u32 s46, s46, 0x3200
	s_subb_u32 s47, s47, 0
	v_pk_fma_f32 v[96:97], v[66:67], v[236:237], v[96:97] op_sel_hi:[0,1,1]
	v_pk_fma_f32 v[96:97], v[66:67], v[238:239], v[96:97] op_sel:[1,0,0] op_sel_hi:[1,1,1]
	v_pk_fma_f32 v[96:97], v[68:69], v[240:241], v[96:97] op_sel_hi:[0,1,1]
	v_pk_fma_f32 v[96:97], v[68:69], v[242:243], v[96:97] op_sel:[1,0,0] op_sel_hi:[1,1,1]
	v_pk_fma_f32 v[96:97], v[70:71], v[244:245], v[96:97] op_sel_hi:[0,1,1]
	v_pk_fma_f32 v[96:97], v[70:71], v[246:247], v[96:97] op_sel:[1,0,0] op_sel_hi:[1,1,1]
	v_pk_fma_f32 v[96:97], v[72:73], v[248:249], v[96:97] op_sel_hi:[0,1,1]
	v_pk_fma_f32 v[96:97], v[72:73], v[250:251], v[96:97] op_sel:[1,0,0] op_sel_hi:[1,1,1]
	v_pk_fma_f32 v[96:97], v[74:75], v[252:253], v[96:97] op_sel_hi:[0,1,1]
	v_pk_fma_f32 v[96:97], v[74:75], v[254:255], v[96:97] op_sel:[1,0,0] op_sel_hi:[1,1,1]
	v_pk_fma_f32 v[96:97], v[76:77], v[220:221], v[96:97] op_sel_hi:[0,1,1]
	v_pk_fma_f32 v[96:97], v[76:77], v[222:223], v[96:97] op_sel:[1,0,0] op_sel_hi:[1,1,1]
	v_pk_fma_f32 v[96:97], v[78:79], v[224:225], v[96:97] op_sel_hi:[0,1,1]
	v_pk_fma_f32 v[96:97], v[78:79], v[226:227], v[96:97] op_sel:[1,0,0] op_sel_hi:[1,1,1]
	v_mul_f32_e64 v104, |v96|, s34
	v_mul_f32_e64 v105, |v97|, s34
	v_exp_f32_e32 v104, v104
	v_exp_f32_e32 v105, v105
	v_min_f32_e32 v106, 0, v96
	v_min_f32_e32 v107, 0, v97
	v_pk_add_f32 v[104:105], v[104:105], v[190:191]
	v_log_f32_e32 v104, v104
	v_log_f32_e32 v105, v105
	s_nop 0
	v_fma_f32 v106, v104, s35, v106
	v_fma_f32 v107, v105, s35, v107
	v_pk_fma_f32 v[192:193], v[106:107], v[188:189], v[192:193]
	ds_read_b128 v[64:67], v167 offset:576
	ds_read_b128 v[68:71], v167 offset:592
	ds_read_b128 v[72:75], v167 offset:608
	ds_read_b128 v[76:79], v167 offset:624
	v_pk_mul_f32 v[98:99], v[192:193], v[186:187]
	s_waitcnt vmcnt(41)
	v_lshlrev_b32_e32 v100, 16, v53
	v_exp_f32_e32 v98, v98
	v_exp_f32_e32 v99, v99
	v_and_b32_e32 v101, 0xffff0000, v53
	v_mov_b32_e32 v96, v198
	v_mov_b32_e32 v97, v199
	v_pk_mul_f32 v[102:103], v[100:101], v[98:99]
	s_waitcnt lgkmcnt(4)
	v_pk_fma_f32 v[96:97], v[80:81], v[232:233], v[96:97] op_sel_hi:[0,1,1]
	v_cvt_pk_bf16_f32 v108, v102, v103
	v_pk_fma_f32 v[96:97], v[80:81], v[234:235], v[96:97] op_sel:[1,0,0] op_sel_hi:[1,1,1]
	global_store_dword v166, v108, s[46:47]
	s_sub_u32 s46, s46, 0x3200
	s_subb_u32 s47, s47, 0
	v_pk_fma_f32 v[96:97], v[82:83], v[236:237], v[96:97] op_sel_hi:[0,1,1]
	v_pk_fma_f32 v[96:97], v[82:83], v[238:239], v[96:97] op_sel:[1,0,0] op_sel_hi:[1,1,1]
	v_pk_fma_f32 v[96:97], v[84:85], v[240:241], v[96:97] op_sel_hi:[0,1,1]
	v_pk_fma_f32 v[96:97], v[84:85], v[242:243], v[96:97] op_sel:[1,0,0] op_sel_hi:[1,1,1]
	v_pk_fma_f32 v[96:97], v[86:87], v[244:245], v[96:97] op_sel_hi:[0,1,1]
	v_pk_fma_f32 v[96:97], v[86:87], v[246:247], v[96:97] op_sel:[1,0,0] op_sel_hi:[1,1,1]
	v_pk_fma_f32 v[96:97], v[88:89], v[248:249], v[96:97] op_sel_hi:[0,1,1]
	v_pk_fma_f32 v[96:97], v[88:89], v[250:251], v[96:97] op_sel:[1,0,0] op_sel_hi:[1,1,1]
	v_pk_fma_f32 v[96:97], v[90:91], v[252:253], v[96:97] op_sel_hi:[0,1,1]
	v_pk_fma_f32 v[96:97], v[90:91], v[254:255], v[96:97] op_sel:[1,0,0] op_sel_hi:[1,1,1]
	v_pk_fma_f32 v[96:97], v[92:93], v[220:221], v[96:97] op_sel_hi:[0,1,1]
	v_pk_fma_f32 v[96:97], v[92:93], v[222:223], v[96:97] op_sel:[1,0,0] op_sel_hi:[1,1,1]
	v_pk_fma_f32 v[96:97], v[94:95], v[224:225], v[96:97] op_sel_hi:[0,1,1]
	v_pk_fma_f32 v[96:97], v[94:95], v[226:227], v[96:97] op_sel:[1,0,0] op_sel_hi:[1,1,1]
	v_mul_f32_e64 v104, |v96|, s34
	v_mul_f32_e64 v105, |v97|, s34
	v_exp_f32_e32 v104, v104
	v_exp_f32_e32 v105, v105
	v_min_f32_e32 v106, 0, v96
	v_min_f32_e32 v107, 0, v97
	v_pk_add_f32 v[104:105], v[104:105], v[190:191]
	v_log_f32_e32 v104, v104
	v_log_f32_e32 v105, v105
	s_nop 0
	v_fma_f32 v106, v104, s35, v106
	v_fma_f32 v107, v105, s35, v107
	v_pk_fma_f32 v[192:193], v[106:107], v[188:189], v[192:193]
	ds_read_b128 v[80:83], v167 offset:512
	ds_read_b128 v[84:87], v167 offset:528
	ds_read_b128 v[88:91], v167 offset:544
	ds_read_b128 v[92:95], v167 offset:560
	v_pk_mul_f32 v[98:99], v[192:193], v[186:187]
	s_waitcnt vmcnt(40)
	v_lshlrev_b32_e32 v100, 16, v54
	v_exp_f32_e32 v98, v98
	v_exp_f32_e32 v99, v99
	v_and_b32_e32 v101, 0xffff0000, v54
	v_mov_b32_e32 v96, v198
	v_mov_b32_e32 v97, v199
	v_pk_mul_f32 v[102:103], v[100:101], v[98:99]
	s_waitcnt lgkmcnt(4)
	v_pk_fma_f32 v[96:97], v[64:65], v[232:233], v[96:97] op_sel_hi:[0,1,1]
	v_cvt_pk_bf16_f32 v108, v102, v103
	v_pk_fma_f32 v[96:97], v[64:65], v[234:235], v[96:97] op_sel:[1,0,0] op_sel_hi:[1,1,1]
	global_store_dword v166, v108, s[46:47]
	s_sub_u32 s46, s46, 0x3200
	s_subb_u32 s47, s47, 0
	v_pk_fma_f32 v[96:97], v[66:67], v[236:237], v[96:97] op_sel_hi:[0,1,1]
	v_pk_fma_f32 v[96:97], v[66:67], v[238:239], v[96:97] op_sel:[1,0,0] op_sel_hi:[1,1,1]
	v_pk_fma_f32 v[96:97], v[68:69], v[240:241], v[96:97] op_sel_hi:[0,1,1]
	v_pk_fma_f32 v[96:97], v[68:69], v[242:243], v[96:97] op_sel:[1,0,0] op_sel_hi:[1,1,1]
	v_pk_fma_f32 v[96:97], v[70:71], v[244:245], v[96:97] op_sel_hi:[0,1,1]
	v_pk_fma_f32 v[96:97], v[70:71], v[246:247], v[96:97] op_sel:[1,0,0] op_sel_hi:[1,1,1]
	v_pk_fma_f32 v[96:97], v[72:73], v[248:249], v[96:97] op_sel_hi:[0,1,1]
	v_pk_fma_f32 v[96:97], v[72:73], v[250:251], v[96:97] op_sel:[1,0,0] op_sel_hi:[1,1,1]
	v_pk_fma_f32 v[96:97], v[74:75], v[252:253], v[96:97] op_sel_hi:[0,1,1]
	v_pk_fma_f32 v[96:97], v[74:75], v[254:255], v[96:97] op_sel:[1,0,0] op_sel_hi:[1,1,1]
	v_pk_fma_f32 v[96:97], v[76:77], v[220:221], v[96:97] op_sel_hi:[0,1,1]
	v_pk_fma_f32 v[96:97], v[76:77], v[222:223], v[96:97] op_sel:[1,0,0] op_sel_hi:[1,1,1]
	v_pk_fma_f32 v[96:97], v[78:79], v[224:225], v[96:97] op_sel_hi:[0,1,1]
	v_pk_fma_f32 v[96:97], v[78:79], v[226:227], v[96:97] op_sel:[1,0,0] op_sel_hi:[1,1,1]
	v_mul_f32_e64 v104, |v96|, s34
	v_mul_f32_e64 v105, |v97|, s34
	v_exp_f32_e32 v104, v104
	v_exp_f32_e32 v105, v105
	v_min_f32_e32 v106, 0, v96
	v_min_f32_e32 v107, 0, v97
	v_pk_add_f32 v[104:105], v[104:105], v[190:191]
	v_log_f32_e32 v104, v104
	v_log_f32_e32 v105, v105
	s_nop 0
	v_fma_f32 v106, v104, s35, v106
	v_fma_f32 v107, v105, s35, v107
	v_pk_fma_f32 v[192:193], v[106:107], v[188:189], v[192:193]
	ds_read_b128 v[64:67], v167 offset:448
	ds_read_b128 v[68:71], v167 offset:464
	ds_read_b128 v[72:75], v167 offset:480
	ds_read_b128 v[76:79], v167 offset:496
	v_pk_mul_f32 v[98:99], v[192:193], v[186:187]
	s_waitcnt vmcnt(39)
; DI unsigned pk2(float a, float b) { f32x2 v = {a, b}; bf16v2_t r = __builtin_convertvector(v, bf16v2_t); return __builtin_bit_cast(unsigned, r); }
; DI void phase_gla_prep(const Params& p, LAS unsigned char* lds) {
;     ...
;             unsigned kw[16];
; #pragma unroll
;             for (int i = 0; i < 16; ++i) kw[i] = *(const unsigned*)(big + (tokb + tg * 16 + i) * 6400 + 1024 + ch0);
; #pragma unroll
;             for (int i = 15; i >= 0; --i) { const int tok = tg * 16 + i;
;                 float z0 = bs0, z1 = bs1;
; #pragma unroll
;                 for (int r = 0; r < 16; ++r) { const float lv = lrs[tok * 16 + r]; z0 += lv * wg0[r]; z1 += lv * wg1[r]; }
;                 *(unsigned*)(big + (tokb + tok) * 6400 + 1024 + ch0) = pk2(__uint_as_float(kw[i] << 16) * __expf(t0), __uint_as_float(kw[i] & 0xffff0000u) * __expf(t1));
;                 t0 += (fminf(z0, 0.f) - __logf(1.f + __expf(-fabsf(z0)))) * (1.f / 16.f); t1 += (fminf(z1, 0.f) - __logf(1.f + __expf(-fabsf(z1)))) * (1.f / 16.f);
	v_lshlrev_b32_e32 v100, 16, v55
	v_exp_f32_e32 v98, v98
	v_exp_f32_e32 v99, v99
	v_and_b32_e32 v101, 0xffff0000, v55
	v_mov_b32_e32 v96, v198
	v_mov_b32_e32 v97, v199
	v_pk_mul_f32 v[102:103], v[100:101], v[98:99]
	s_waitcnt lgkmcnt(4)
	v_pk_fma_f32 v[96:97], v[80:81], v[232:233], v[96:97] op_sel_hi:[0,1,1]
	v_cvt_pk_bf16_f32 v108, v102, v103
	v_pk_fma_f32 v[96:97], v[80:81], v[234:235], v[96:97] op_sel:[1,0,0] op_sel_hi:[1,1,1]
	global_store_dword v166, v108, s[46:47]
	s_sub_u32 s46, s46, 0x3200
	s_subb_u32 s47, s47, 0
	v_pk_fma_f32 v[96:97], v[82:83], v[236:237], v[96:97] op_sel_hi:[0,1,1]
	v_pk_fma_f32 v[96:97], v[82:83], v[238:239], v[96:97] op_sel:[1,0,0] op_sel_hi:[1,1,1]
	v_pk_fma_f32 v[96:97], v[84:85], v[240:241], v[96:97] op_sel_hi:[0,1,1]
	v_pk_fma_f32 v[96:97], v[84:85], v[242:243], v[96:97] op_sel:[1,0,0] op_sel_hi:[1,1,1]
	v_pk_fma_f32 v[96:97], v[86:87], v[244:245], v[96:97] op_sel_hi:[0,1,1]
	v_pk_fma_f32 v[96:97], v[86:87], v[246:247], v[96:97] op_sel:[1,0,0] op_sel_hi:[1,1,1]
	v_pk_fma_f32 v[96:97], v[88:89], v[248:249], v[96:97] op_sel_hi:[0,1,1]
	v_pk_fma_f32 v[96:97], v[88:89], v[250:251], v[96:97] op_sel:[1,0,0] op_sel_hi:[1,1,1]
	v_pk_fma_f32 v[96:97], v[90:91], v[252:253], v[96:97] op_sel_hi:[0,1,1]
	v_pk_fma_f32 v[96:97], v[90:91], v[254:255], v[96:97] op_sel:[1,0,0] op_sel_hi:[1,1,1]
	v_pk_fma_f32 v[96:97], v[92:93], v[220:221], v[96:97] op_sel_hi:[0,1,1]
	v_pk_fma_f32 v[96:97], v[92:93], v[222:223], v[96:97] op_sel:[1,0,0] op_sel_hi:[1,1,1]
	v_pk_fma_f32 v[96:97], v[94:95], v[224:225], v[96:97] op_sel_hi:[0,1,1]
	v_pk_fma_f32 v[96:97], v[94:95], v[226:227], v[96:97] op_sel:[1,0,0] op_sel_hi:[1,1,1]
	v_mul_f32_e64 v104, |v96|, s34
	v_mul_f32_e64 v105, |v97|, s34
	v_exp_f32_e32 v104, v104
	v_exp_f32_e32 v105, v105
	v_min_f32_e32 v106, 0, v96
	v_min_f32_e32 v107, 0, v97
	v_pk_add_f32 v[104:105], v[104:105], v[190:191]
	v_log_f32_e32 v104, v104
	v_log_f32_e32 v105, v105
	s_nop 0
	v_fma_f32 v106, v104, s35, v106
	v_fma_f32 v107, v105, s35, v107
	v_pk_fma_f32 v[192:193], v[106:107], v[188:189], v[192:193]
	ds_read_b128 v[80:83], v167 offset:384
	ds_read_b128 v[84:87], v167 offset:400
	ds_read_b128 v[88:91], v167 offset:416
	ds_read_b128 v[92:95], v167 offset:432
	v_pk_mul_f32 v[98:99], v[192:193], v[186:187]
	s_waitcnt vmcnt(38)
	v_lshlrev_b32_e32 v100, 16, v56
	v_exp_f32_e32 v98, v98
	v_exp_f32_e32 v99, v99
	v_and_b32_e32 v101, 0xffff0000, v56
	v_mov_b32_e32 v96, v198
	v_mov_b32_e32 v97, v199
	v_pk_mul_f32 v[102:103], v[100:101], v[98:99]
	s_waitcnt lgkmcnt(4)
	v_pk_fma_f32 v[96:97], v[64:65], v[232:233], v[96:97] op_sel_hi:[0,1,1]
	v_cvt_pk_bf16_f32 v108, v102, v103
	v_pk_fma_f32 v[96:97], v[64:65], v[234:235], v[96:97] op_sel:[1,0,0] op_sel_hi:[1,1,1]
	global_store_dword v166, v108, s[46:47]
	s_sub_u32 s46, s46, 0x3200
	s_subb_u32 s47, s47, 0
	v_pk_fma_f32 v[96:97], v[66:67], v[236:237], v[96:97] op_sel_hi:[0,1,1]
	v_pk_fma_f32 v[96:97], v[66:67], v[238:239], v[96:97] op_sel:[1,0,0] op_sel_hi:[1,1,1]
	v_pk_fma_f32 v[96:97], v[68:69], v[240:241], v[96:97] op_sel_hi:[0,1,1]
	v_pk_fma_f32 v[96:97], v[68:69], v[242:243], v[96:97] op_sel:[1,0,0] op_sel_hi:[1,1,1]
	v_pk_fma_f32 v[96:97], v[70:71], v[244:245], v[96:97] op_sel_hi:[0,1,1]
	v_pk_fma_f32 v[96:97], v[70:71], v[246:247], v[96:97] op_sel:[1,0,0] op_sel_hi:[1,1,1]
	v_pk_fma_f32 v[96:97], v[72:73], v[248:249], v[96:97] op_sel_hi:[0,1,1]
	v_pk_fma_f32 v[96:97], v[72:73], v[250:251], v[96:97] op_sel:[1,0,0] op_sel_hi:[1,1,1]
	v_pk_fma_f32 v[96:97], v[74:75], v[252:253], v[96:97] op_sel_hi:[0,1,1]
	v_pk_fma_f32 v[96:97], v[74:75], v[254:255], v[96:97] op_sel:[1,0,0] op_sel_hi:[1,1,1]
	v_pk_fma_f32 v[96:97], v[76:77], v[220:221], v[96:97] op_sel_hi:[0,1,1]
	v_pk_fma_f32 v[96:97], v[76:77], v[222:223], v[96:97] op_sel:[1,0,0] op_sel_hi:[1,1,1]
	v_pk_fma_f32 v[96:97], v[78:79], v[224:225], v[96:97] op_sel_hi:[0,1,1]
	v_pk_fma_f32 v[96:97], v[78:79], v[226:227], v[96:97] op_sel:[1,0,0] op_sel_hi:[1,1,1]
	v_mul_f32_e64 v104, |v96|, s34
	v_mul_f32_e64 v105, |v97|, s34
	v_exp_f32_e32 v104, v104
	v_exp_f32_e32 v105, v105
	v_min_f32_e32 v106, 0, v96
	v_min_f32_e32 v107, 0, v97
	v_pk_add_f32 v[104:105], v[104:105], v[190:191]
	v_log_f32_e32 v104, v104
	v_log_f32_e32 v105, v105
	s_nop 0
	v_fma_f32 v106, v104, s35, v106
	v_fma_f32 v107, v105, s35, v107
	v_pk_fma_f32 v[192:193], v[106:107], v[188:189], v[192:193]
	ds_read_b128 v[64:67], v167 offset:320
	ds_read_b128 v[68:71], v167 offset:336
	ds_read_b128 v[72:75], v167 offset:352
	ds_read_b128 v[76:79], v167 offset:368
	v_pk_mul_f32 v[98:99], v[192:193], v[186:187]
	s_waitcnt vmcnt(37)
	v_lshlrev_b32_e32 v100, 16, v57
	v_exp_f32_e32 v98, v98
	v_exp_f32_e32 v99, v99
	v_and_b32_e32 v101, 0xffff0000, v57
	v_mov_b32_e32 v96, v198
	v_mov_b32_e32 v97, v199
	v_pk_mul_f32 v[102:103], v[100:101], v[98:99]
	s_waitcnt lgkmcnt(4)
; DI unsigned pk2(float a, float b) { f32x2 v = {a, b}; bf16v2_t r = __builtin_convertvector(v, bf16v2_t); return __builtin_bit_cast(unsigned, r); }
; DI void phase_gla_prep(const Params& p, LAS unsigned char* lds) {
;     ...
;             unsigned kw[16];
; #pragma unroll
;             for (int i = 0; i < 16; ++i) kw[i] = *(const unsigned*)(big + (tokb + tg * 16 + i) * 6400 + 1024 + ch0);
; #pragma unroll
;             for (int i = 15; i >= 0; --i) { const int tok = tg * 16 + i;
;                 float z0 = bs0, z1 = bs1;
; #pragma unroll
;                 for (int r = 0; r < 16; ++r) { const float lv = lrs[tok * 16 + r]; z0 += lv * wg0[r]; z1 += lv * wg1[r]; }
;                 *(unsigned*)(big + (tokb + tok) * 6400 + 1024 + ch0) = pk2(__uint_as_float(kw[i] << 16) * __expf(t0), __uint_as_float(kw[i] & 0xffff0000u) * __expf(t1));
;                 t0 += (fminf(z0, 0.f) - __logf(1.f + __expf(-fabsf(z0)))) * (1.f / 16.f); t1 += (fminf(z1, 0.f) - __logf(1.f + __expf(-fabsf(z1)))) * (1.f / 16.f);
	v_pk_fma_f32 v[96:97], v[80:81], v[232:233], v[96:97] op_sel_hi:[0,1,1]
	v_cvt_pk_bf16_f32 v108, v102, v103
	v_pk_fma_f32 v[96:97], v[80:81], v[234:235], v[96:97] op_sel:[1,0,0] op_sel_hi:[1,1,1]
	global_store_dword v166, v108, s[46:47]
	s_sub_u32 s46, s46, 0x3200
	s_subb_u32 s47, s47, 0
	v_pk_fma_f32 v[96:97], v[82:83], v[236:237], v[96:97] op_sel_hi:[0,1,1]
	v_pk_fma_f32 v[96:97], v[82:83], v[238:239], v[96:97] op_sel:[1,0,0] op_sel_hi:[1,1,1]
	v_pk_fma_f32 v[96:97], v[84:85], v[240:241], v[96:97] op_sel_hi:[0,1,1]
	v_pk_fma_f32 v[96:97], v[84:85], v[242:243], v[96:97] op_sel:[1,0,0] op_sel_hi:[1,1,1]
	v_pk_fma_f32 v[96:97], v[86:87], v[244:245], v[96:97] op_sel_hi:[0,1,1]
	v_pk_fma_f32 v[96:97], v[86:87], v[246:247], v[96:97] op_sel:[1,0,0] op_sel_hi:[1,1,1]
	v_pk_fma_f32 v[96:97], v[88:89], v[248:249], v[96:97] op_sel_hi:[0,1,1]
	v_pk_fma_f32 v[96:97], v[88:89], v[250:251], v[96:97] op_sel:[1,0,0] op_sel_hi:[1,1,1]
	v_pk_fma_f32 v[96:97], v[90:91], v[252:253], v[96:97] op_sel_hi:[0,1,1]
	v_pk_fma_f32 v[96:97], v[90:91], v[254:255], v[96:97] op_sel:[1,0,0] op_sel_hi:[1,1,1]
	v_pk_fma_f32 v[96:97], v[92:93], v[220:221], v[96:97] op_sel_hi:[0,1,1]
	v_pk_fma_f32 v[96:97], v[92:93], v[222:223], v[96:97] op_sel:[1,0,0] op_sel_hi:[1,1,1]
	v_pk_fma_f32 v[96:97], v[94:95], v[224:225], v[96:97] op_sel_hi:[0,1,1]
	v_pk_fma_f32 v[96:97], v[94:95], v[226:227], v[96:97] op_sel:[1,0,0] op_sel_hi:[1,1,1]
	v_mul_f32_e64 v104, |v96|, s34
	v_mul_f32_e64 v105, |v97|, s34
	v_exp_f32_e32 v104, v104
	v_exp_f32_e32 v105, v105
	v_min_f32_e32 v106, 0, v96
	v_min_f32_e32 v107, 0, v97
	v_pk_add_f32 v[104:105], v[104:105], v[190:191]
	v_log_f32_e32 v104, v104
	v_log_f32_e32 v105, v105
	s_nop 0
	v_fma_f32 v106, v104, s35, v106
	v_fma_f32 v107, v105, s35, v107
	v_pk_fma_f32 v[192:193], v[106:107], v[188:189], v[192:193]
	ds_read_b128 v[80:83], v167 offset:256
	ds_read_b128 v[84:87], v167 offset:272
	ds_read_b128 v[88:91], v167 offset:288
	ds_read_b128 v[92:95], v167 offset:304
	v_pk_mul_f32 v[98:99], v[192:193], v[186:187]
	s_waitcnt vmcnt(36)
	v_lshlrev_b32_e32 v100, 16, v58
	v_exp_f32_e32 v98, v98
	v_exp_f32_e32 v99, v99
	v_and_b32_e32 v101, 0xffff0000, v58
	v_mov_b32_e32 v96, v198
	v_mov_b32_e32 v97, v199
	v_pk_mul_f32 v[102:103], v[100:101], v[98:99]
	s_waitcnt lgkmcnt(4)
	v_pk_fma_f32 v[96:97], v[64:65], v[232:233], v[96:97] op_sel_hi:[0,1,1]
	v_cvt_pk_bf16_f32 v108, v102, v103
	v_pk_fma_f32 v[96:97], v[64:65], v[234:235], v[96:97] op_sel:[1,0,0] op_sel_hi:[1,1,1]
	global_store_dword v166, v108, s[46:47]
	s_sub_u32 s46, s46, 0x3200
	s_subb_u32 s47, s47, 0
	v_pk_fma_f32 v[96:97], v[66:67], v[236:237], v[96:97] op_sel_hi:[0,1,1]
	v_pk_fma_f32 v[96:97], v[66:67], v[238:239], v[96:97] op_sel:[1,0,0] op_sel_hi:[1,1,1]
	v_pk_fma_f32 v[96:97], v[68:69], v[240:241], v[96:97] op_sel_hi:[0,1,1]
	v_pk_fma_f32 v[96:97], v[68:69], v[242:243], v[96:97] op_sel:[1,0,0] op_sel_hi:[1,1,1]
	v_pk_fma_f32 v[96:97], v[70:71], v[244:245], v[96:97] op_sel_hi:[0,1,1]
	v_pk_fma_f32 v[96:97], v[70:71], v[246:247], v[96:97] op_sel:[1,0,0] op_sel_hi:[1,1,1]
	v_pk_fma_f32 v[96:97], v[72:73], v[248:249], v[96:97] op_sel_hi:[0,1,1]
	v_pk_fma_f32 v[96:97], v[72:73], v[250:251], v[96:97] op_sel:[1,0,0] op_sel_hi:[1,1,1]
	v_pk_fma_f32 v[96:97], v[74:75], v[252:253], v[96:97] op_sel_hi:[0,1,1]
	v_pk_fma_f32 v[96:97], v[74:75], v[254:255], v[96:97] op_sel:[1,0,0] op_sel_hi:[1,1,1]
	v_pk_fma_f32 v[96:97], v[76:77], v[220:221], v[96:97] op_sel_hi:[0,1,1]
	v_pk_fma_f32 v[96:97], v[76:77], v[222:223], v[96:97] op_sel:[1,0,0] op_sel_hi:[1,1,1]
	v_pk_fma_f32 v[96:97], v[78:79], v[224:225], v[96:97] op_sel_hi:[0,1,1]
	v_pk_fma_f32 v[96:97], v[78:79], v[226:227], v[96:97] op_sel:[1,0,0] op_sel_hi:[1,1,1]
	v_mul_f32_e64 v104, |v96|, s34
	v_mul_f32_e64 v105, |v97|, s34
	v_exp_f32_e32 v104, v104
	v_exp_f32_e32 v105, v105
	v_min_f32_e32 v106, 0, v96
	v_min_f32_e32 v107, 0, v97
	v_pk_add_f32 v[104:105], v[104:105], v[190:191]
	v_log_f32_e32 v104, v104
	v_log_f32_e32 v105, v105
	s_nop 0
	v_fma_f32 v106, v104, s35, v106
	v_fma_f32 v107, v105, s35, v107
	v_pk_fma_f32 v[192:193], v[106:107], v[188:189], v[192:193]
	ds_read_b128 v[64:67], v167 offset:192
	ds_read_b128 v[68:71], v167 offset:208
	ds_read_b128 v[72:75], v167 offset:224
	ds_read_b128 v[76:79], v167 offset:240
	v_pk_mul_f32 v[98:99], v[192:193], v[186:187]
	s_waitcnt vmcnt(35)
	v_lshlrev_b32_e32 v100, 16, v59
	v_exp_f32_e32 v98, v98
	v_exp_f32_e32 v99, v99
	v_and_b32_e32 v101, 0xffff0000, v59
	v_mov_b32_e32 v96, v198
	v_mov_b32_e32 v97, v199
	v_pk_mul_f32 v[102:103], v[100:101], v[98:99]
	s_waitcnt lgkmcnt(4)
	v_pk_fma_f32 v[96:97], v[80:81], v[232:233], v[96:97] op_sel_hi:[0,1,1]
	v_cvt_pk_bf16_f32 v108, v102, v103
	v_pk_fma_f32 v[96:97], v[80:81], v[234:235], v[96:97] op_sel:[1,0,0] op_sel_hi:[1,1,1]
	global_store_dword v166, v108, s[46:47]
	s_sub_u32 s46, s46, 0x3200
	s_subb_u32 s47, s47, 0
	v_pk_fma_f32 v[96:97], v[82:83], v[236:237], v[96:97] op_sel_hi:[0,1,1]
	v_pk_fma_f32 v[96:97], v[82:83], v[238:239], v[96:97] op_sel:[1,0,0] op_sel_hi:[1,1,1]
	v_pk_fma_f32 v[96:97], v[84:85], v[240:241], v[96:97] op_sel_hi:[0,1,1]
	v_pk_fma_f32 v[96:97], v[84:85], v[242:243], v[96:97] op_sel:[1,0,0] op_sel_hi:[1,1,1]
	v_pk_fma_f32 v[96:97], v[86:87], v[244:245], v[96:97] op_sel_hi:[0,1,1]
	v_pk_fma_f32 v[96:97], v[86:87], v[246:247], v[96:97] op_sel:[1,0,0] op_sel_hi:[1,1,1]
	v_pk_fma_f32 v[96:97], v[88:89], v[248:249], v[96:97] op_sel_hi:[0,1,1]
	v_pk_fma_f32 v[96:97], v[88:89], v[250:251], v[96:97] op_sel:[1,0,0] op_sel_hi:[1,1,1]
	v_pk_fma_f32 v[96:97], v[90:91], v[252:253], v[96:97] op_sel_hi:[0,1,1]
	v_pk_fma_f32 v[96:97], v[90:91], v[254:255], v[96:97] op_sel:[1,0,0] op_sel_hi:[1,1,1]
	v_pk_fma_f32 v[96:97], v[92:93], v[220:221], v[96:97] op_sel_hi:[0,1,1]
	v_pk_fma_f32 v[96:97], v[92:93], v[222:223], v[96:97] op_sel:[1,0,0] op_sel_hi:[1,1,1]
	v_pk_fma_f32 v[96:97], v[94:95], v[224:225], v[96:97] op_sel_hi:[0,1,1]
	v_pk_fma_f32 v[96:97], v[94:95], v[226:227], v[96:97] op_sel:[1,0,0] op_sel_hi:[1,1,1]
	v_mul_f32_e64 v104, |v96|, s34
	v_mul_f32_e64 v105, |v97|, s34
	v_exp_f32_e32 v104, v104
	v_exp_f32_e32 v105, v105
	v_min_f32_e32 v106, 0, v96
	v_min_f32_e32 v107, 0, v97
	v_pk_add_f32 v[104:105], v[104:105], v[190:191]
	v_log_f32_e32 v104, v104
	v_log_f32_e32 v105, v105
	s_nop 0
	v_fma_f32 v106, v104, s35, v106
	v_fma_f32 v107, v105, s35, v107
	v_pk_fma_f32 v[192:193], v[106:107], v[188:189], v[192:193]
	ds_read_b128 v[80:83], v167 offset:128
	ds_read_b128 v[84:87], v167 offset:144
	ds_read_b128 v[88:91], v167 offset:160
	ds_read_b128 v[92:95], v167 offset:176
	v_pk_mul_f32 v[98:99], v[192:193], v[186:187]
	s_waitcnt vmcnt(34)
; DI unsigned pk2(float a, float b) { f32x2 v = {a, b}; bf16v2_t r = __builtin_convertvector(v, bf16v2_t); return __builtin_bit_cast(unsigned, r); }
; DI void phase_gla_prep(const Params& p, LAS unsigned char* lds) {
;     ...
;             unsigned kw[16];
; #pragma unroll
;             for (int i = 0; i < 16; ++i) kw[i] = *(const unsigned*)(big + (tokb + tg * 16 + i) * 6400 + 1024 + ch0);
; #pragma unroll
;             for (int i = 15; i >= 0; --i) { const int tok = tg * 16 + i;
;                 float z0 = bs0, z1 = bs1;
; #pragma unroll
;                 for (int r = 0; r < 16; ++r) { const float lv = lrs[tok * 16 + r]; z0 += lv * wg0[r]; z1 += lv * wg1[r]; }
;                 *(unsigned*)(big + (tokb + tok) * 6400 + 1024 + ch0) = pk2(__uint_as_float(kw[i] << 16) * __expf(t0), __uint_as_float(kw[i] & 0xffff0000u) * __expf(t1));
;                 t0 += (fminf(z0, 0.f) - __logf(1.f + __expf(-fabsf(z0)))) * (1.f / 16.f); t1 += (fminf(z1, 0.f) - __logf(1.f + __expf(-fabsf(z1)))) * (1.f / 16.f);
	v_lshlrev_b32_e32 v100, 16, v60
	v_exp_f32_e32 v98, v98
	v_exp_f32_e32 v99, v99
	v_and_b32_e32 v101, 0xffff0000, v60
	v_mov_b32_e32 v96, v198
	v_mov_b32_e32 v97, v199
	v_pk_mul_f32 v[102:103], v[100:101], v[98:99]
	s_waitcnt lgkmcnt(4)
	v_pk_fma_f32 v[96:97], v[64:65], v[232:233], v[96:97] op_sel_hi:[0,1,1]
	v_cvt_pk_bf16_f32 v108, v102, v103
	v_pk_fma_f32 v[96:97], v[64:65], v[234:235], v[96:97] op_sel:[1,0,0] op_sel_hi:[1,1,1]
	global_store_dword v166, v108, s[46:47]
	s_sub_u32 s46, s46, 0x3200
	s_subb_u32 s47, s47, 0
	v_pk_fma_f32 v[96:97], v[66:67], v[236:237], v[96:97] op_sel_hi:[0,1,1]
	v_pk_fma_f32 v[96:97], v[66:67], v[238:239], v[96:97] op_sel:[1,0,0] op_sel_hi:[1,1,1]
	v_pk_fma_f32 v[96:97], v[68:69], v[240:241], v[96:97] op_sel_hi:[0,1,1]
	v_pk_fma_f32 v[96:97], v[68:69], v[242:243], v[96:97] op_sel:[1,0,0] op_sel_hi:[1,1,1]
	v_pk_fma_f32 v[96:97], v[70:71], v[244:245], v[96:97] op_sel_hi:[0,1,1]
	v_pk_fma_f32 v[96:97], v[70:71], v[246:247], v[96:97] op_sel:[1,0,0] op_sel_hi:[1,1,1]
	v_pk_fma_f32 v[96:97], v[72:73], v[248:249], v[96:97] op_sel_hi:[0,1,1]
	v_pk_fma_f32 v[96:97], v[72:73], v[250:251], v[96:97] op_sel:[1,0,0] op_sel_hi:[1,1,1]
	v_pk_fma_f32 v[96:97], v[74:75], v[252:253], v[96:97] op_sel_hi:[0,1,1]
	v_pk_fma_f32 v[96:97], v[74:75], v[254:255], v[96:97] op_sel:[1,0,0] op_sel_hi:[1,1,1]
	v_pk_fma_f32 v[96:97], v[76:77], v[220:221], v[96:97] op_sel_hi:[0,1,1]
	v_pk_fma_f32 v[96:97], v[76:77], v[222:223], v[96:97] op_sel:[1,0,0] op_sel_hi:[1,1,1]
	v_pk_fma_f32 v[96:97], v[78:79], v[224:225], v[96:97] op_sel_hi:[0,1,1]
	v_pk_fma_f32 v[96:97], v[78:79], v[226:227], v[96:97] op_sel:[1,0,0] op_sel_hi:[1,1,1]
	v_mul_f32_e64 v104, |v96|, s34
	v_mul_f32_e64 v105, |v97|, s34
	v_exp_f32_e32 v104, v104
	v_exp_f32_e32 v105, v105
	v_min_f32_e32 v106, 0, v96
	v_min_f32_e32 v107, 0, v97
	v_pk_add_f32 v[104:105], v[104:105], v[190:191]
	v_log_f32_e32 v104, v104
	v_log_f32_e32 v105, v105
	s_nop 0
	v_fma_f32 v106, v104, s35, v106
	v_fma_f32 v107, v105, s35, v107
	v_pk_fma_f32 v[192:193], v[106:107], v[188:189], v[192:193]
	ds_read_b128 v[64:67], v167 offset:64
	ds_read_b128 v[68:71], v167 offset:80
	ds_read_b128 v[72:75], v167 offset:96
	ds_read_b128 v[76:79], v167 offset:112
	v_pk_mul_f32 v[98:99], v[192:193], v[186:187]
	s_waitcnt vmcnt(33)
	v_lshlrev_b32_e32 v100, 16, v61
	v_exp_f32_e32 v98, v98
	v_exp_f32_e32 v99, v99
	v_and_b32_e32 v101, 0xffff0000, v61
	v_mov_b32_e32 v96, v198
	v_mov_b32_e32 v97, v199
	v_pk_mul_f32 v[102:103], v[100:101], v[98:99]
	s_waitcnt lgkmcnt(4)
	v_pk_fma_f32 v[96:97], v[80:81], v[232:233], v[96:97] op_sel_hi:[0,1,1]
	v_cvt_pk_bf16_f32 v108, v102, v103
	v_pk_fma_f32 v[96:97], v[80:81], v[234:235], v[96:97] op_sel:[1,0,0] op_sel_hi:[1,1,1]
	global_store_dword v166, v108, s[46:47]
	s_sub_u32 s46, s46, 0x3200
	s_subb_u32 s47, s47, 0
	v_pk_fma_f32 v[96:97], v[82:83], v[236:237], v[96:97] op_sel_hi:[0,1,1]
	v_pk_fma_f32 v[96:97], v[82:83], v[238:239], v[96:97] op_sel:[1,0,0] op_sel_hi:[1,1,1]
	v_pk_fma_f32 v[96:97], v[84:85], v[240:241], v[96:97] op_sel_hi:[0,1,1]
	v_pk_fma_f32 v[96:97], v[84:85], v[242:243], v[96:97] op_sel:[1,0,0] op_sel_hi:[1,1,1]
	v_pk_fma_f32 v[96:97], v[86:87], v[244:245], v[96:97] op_sel_hi:[0,1,1]
	v_pk_fma_f32 v[96:97], v[86:87], v[246:247], v[96:97] op_sel:[1,0,0] op_sel_hi:[1,1,1]
	v_pk_fma_f32 v[96:97], v[88:89], v[248:249], v[96:97] op_sel_hi:[0,1,1]
	v_pk_fma_f32 v[96:97], v[88:89], v[250:251], v[96:97] op_sel:[1,0,0] op_sel_hi:[1,1,1]
	v_pk_fma_f32 v[96:97], v[90:91], v[252:253], v[96:97] op_sel_hi:[0,1,1]
	v_pk_fma_f32 v[96:97], v[90:91], v[254:255], v[96:97] op_sel:[1,0,0] op_sel_hi:[1,1,1]
	v_pk_fma_f32 v[96:97], v[92:93], v[220:221], v[96:97] op_sel_hi:[0,1,1]
	v_pk_fma_f32 v[96:97], v[92:93], v[222:223], v[96:97] op_sel:[1,0,0] op_sel_hi:[1,1,1]
	v_pk_fma_f32 v[96:97], v[94:95], v[224:225], v[96:97] op_sel_hi:[0,1,1]
	v_pk_fma_f32 v[96:97], v[94:95], v[226:227], v[96:97] op_sel:[1,0,0] op_sel_hi:[1,1,1]
	v_mul_f32_e64 v104, |v96|, s34
	v_mul_f32_e64 v105, |v97|, s34
	v_exp_f32_e32 v104, v104
	v_exp_f32_e32 v105, v105
	v_min_f32_e32 v106, 0, v96
	v_min_f32_e32 v107, 0, v97
	v_pk_add_f32 v[104:105], v[104:105], v[190:191]
	v_log_f32_e32 v104, v104
	v_log_f32_e32 v105, v105
	s_nop 0
	v_fma_f32 v106, v104, s35, v106
	v_fma_f32 v107, v105, s35, v107
	v_pk_fma_f32 v[192:193], v[106:107], v[188:189], v[192:193]
	ds_read_b128 v[80:83], v167 offset:0
	ds_read_b128 v[84:87], v167 offset:16
	ds_read_b128 v[88:91], v167 offset:32
	ds_read_b128 v[92:95], v167 offset:48
	v_pk_mul_f32 v[98:99], v[192:193], v[186:187]
	s_waitcnt vmcnt(32)
	v_lshlrev_b32_e32 v100, 16, v62
	v_exp_f32_e32 v98, v98
	v_exp_f32_e32 v99, v99
	v_and_b32_e32 v101, 0xffff0000, v62
	v_mov_b32_e32 v96, v198
	v_mov_b32_e32 v97, v199
	v_pk_mul_f32 v[102:103], v[100:101], v[98:99]
	s_waitcnt lgkmcnt(4)
; DI unsigned pk2(float a, float b) { f32x2 v = {a, b}; bf16v2_t r = __builtin_convertvector(v, bf16v2_t); return __builtin_bit_cast(unsigned, r); }
; DI void phase_gla_prep(const Params& p, LAS unsigned char* lds) {
;     ...
;             unsigned kw[16];
; #pragma unroll
;             for (int i = 0; i < 16; ++i) kw[i] = *(const unsigned*)(big + (tokb + tg * 16 + i) * 6400 + 1024 + ch0);
; #pragma unroll
;             for (int i = 15; i >= 0; --i) { const int tok = tg * 16 + i;
;                 float z0 = bs0, z1 = bs1;
; #pragma unroll
;                 for (int r = 0; r < 16; ++r) { const float lv = lrs[tok * 16 + r]; z0 += lv * wg0[r]; z1 += lv * wg1[r]; }
;                 *(unsigned*)(big + (tokb + tok) * 6400 + 1024 + ch0) = pk2(__uint_as_float(kw[i] << 16) * __expf(t0), __uint_as_float(kw[i] & 0xffff0000u) * __expf(t1));
;                 t0 += (fminf(z0, 0.f) - __logf(1.f + __expf(-fabsf(z0)))) * (1.f / 16.f); t1 += (fminf(z1, 0.f) - __logf(1.f + __expf(-fabsf(z1)))) * (1.f / 16.f);
;             }
;         }
;         total[(size_t)u * 1024 + ch0] = t0; total[(size_t)u * 1024 + ch0 + 1] = t1;
	v_pk_fma_f32 v[96:97], v[64:65], v[232:233], v[96:97] op_sel_hi:[0,1,1]
	v_cvt_pk_bf16_f32 v108, v102, v103
	v_pk_fma_f32 v[96:97], v[64:65], v[234:235], v[96:97] op_sel:[1,0,0] op_sel_hi:[1,1,1]
	global_store_dword v166, v108, s[46:47]
	s_sub_u32 s46, s46, 0x3200
	s_subb_u32 s47, s47, 0
	v_pk_fma_f32 v[96:97], v[66:67], v[236:237], v[96:97] op_sel_hi:[0,1,1]
	v_pk_fma_f32 v[96:97], v[66:67], v[238:239], v[96:97] op_sel:[1,0,0] op_sel_hi:[1,1,1]
	v_pk_fma_f32 v[96:97], v[68:69], v[240:241], v[96:97] op_sel_hi:[0,1,1]
	v_pk_fma_f32 v[96:97], v[68:69], v[242:243], v[96:97] op_sel:[1,0,0] op_sel_hi:[1,1,1]
	v_pk_fma_f32 v[96:97], v[70:71], v[244:245], v[96:97] op_sel_hi:[0,1,1]
	v_pk_fma_f32 v[96:97], v[70:71], v[246:247], v[96:97] op_sel:[1,0,0] op_sel_hi:[1,1,1]
	v_pk_fma_f32 v[96:97], v[72:73], v[248:249], v[96:97] op_sel_hi:[0,1,1]
	v_pk_fma_f32 v[96:97], v[72:73], v[250:251], v[96:97] op_sel:[1,0,0] op_sel_hi:[1,1,1]
	v_pk_fma_f32 v[96:97], v[74:75], v[252:253], v[96:97] op_sel_hi:[0,1,1]
	v_pk_fma_f32 v[96:97], v[74:75], v[254:255], v[96:97] op_sel:[1,0,0] op_sel_hi:[1,1,1]
	v_pk_fma_f32 v[96:97], v[76:77], v[220:221], v[96:97] op_sel_hi:[0,1,1]
	v_pk_fma_f32 v[96:97], v[76:77], v[222:223], v[96:97] op_sel:[1,0,0] op_sel_hi:[1,1,1]
	v_pk_fma_f32 v[96:97], v[78:79], v[224:225], v[96:97] op_sel_hi:[0,1,1]
	v_pk_fma_f32 v[96:97], v[78:79], v[226:227], v[96:97] op_sel:[1,0,0] op_sel_hi:[1,1,1]
	v_mul_f32_e64 v104, |v96|, s34
	v_mul_f32_e64 v105, |v97|, s34
	v_exp_f32_e32 v104, v104
	v_exp_f32_e32 v105, v105
	v_min_f32_e32 v106, 0, v96
	v_min_f32_e32 v107, 0, v97
	v_pk_add_f32 v[104:105], v[104:105], v[190:191]
	v_log_f32_e32 v104, v104
	v_log_f32_e32 v105, v105
	s_nop 0
	v_fma_f32 v106, v104, s35, v106
	v_fma_f32 v107, v105, s35, v107
	v_pk_fma_f32 v[192:193], v[106:107], v[188:189], v[192:193]
	v_pk_mul_f32 v[98:99], v[192:193], v[186:187]
	s_waitcnt vmcnt(31)
	v_lshlrev_b32_e32 v100, 16, v63
	v_exp_f32_e32 v98, v98
	v_exp_f32_e32 v99, v99
	v_and_b32_e32 v101, 0xffff0000, v63
	v_mov_b32_e32 v96, v198
	v_mov_b32_e32 v97, v199
	v_pk_mul_f32 v[102:103], v[100:101], v[98:99]
	s_waitcnt lgkmcnt(0)
	v_pk_fma_f32 v[96:97], v[80:81], v[232:233], v[96:97] op_sel_hi:[0,1,1]
	v_cvt_pk_bf16_f32 v108, v102, v103
	v_pk_fma_f32 v[96:97], v[80:81], v[234:235], v[96:97] op_sel:[1,0,0] op_sel_hi:[1,1,1]
	global_store_dword v166, v108, s[46:47]
	s_sub_u32 s46, s46, 0x3200
	s_subb_u32 s47, s47, 0
	v_pk_fma_f32 v[96:97], v[82:83], v[236:237], v[96:97] op_sel_hi:[0,1,1]
	v_pk_fma_f32 v[96:97], v[82:83], v[238:239], v[96:97] op_sel:[1,0,0] op_sel_hi:[1,1,1]
	v_pk_fma_f32 v[96:97], v[84:85], v[240:241], v[96:97] op_sel_hi:[0,1,1]
	v_pk_fma_f32 v[96:97], v[84:85], v[242:243], v[96:97] op_sel:[1,0,0] op_sel_hi:[1,1,1]
	v_pk_fma_f32 v[96:97], v[86:87], v[244:245], v[96:97] op_sel_hi:[0,1,1]
	v_pk_fma_f32 v[96:97], v[86:87], v[246:247], v[96:97] op_sel:[1,0,0] op_sel_hi:[1,1,1]
	v_pk_fma_f32 v[96:97], v[88:89], v[248:249], v[96:97] op_sel_hi:[0,1,1]
	v_pk_fma_f32 v[96:97], v[88:89], v[250:251], v[96:97] op_sel:[1,0,0] op_sel_hi:[1,1,1]
	v_pk_fma_f32 v[96:97], v[90:91], v[252:253], v[96:97] op_sel_hi:[0,1,1]
	v_pk_fma_f32 v[96:97], v[90:91], v[254:255], v[96:97] op_sel:[1,0,0] op_sel_hi:[1,1,1]
	v_pk_fma_f32 v[96:97], v[92:93], v[220:221], v[96:97] op_sel_hi:[0,1,1]
	v_pk_fma_f32 v[96:97], v[92:93], v[222:223], v[96:97] op_sel:[1,0,0] op_sel_hi:[1,1,1]
	v_pk_fma_f32 v[96:97], v[94:95], v[224:225], v[96:97] op_sel_hi:[0,1,1]
	v_pk_fma_f32 v[96:97], v[94:95], v[226:227], v[96:97] op_sel:[1,0,0] op_sel_hi:[1,1,1]
	v_mul_f32_e64 v104, |v96|, s34
	v_mul_f32_e64 v105, |v97|, s34
	v_exp_f32_e32 v104, v104
	v_exp_f32_e32 v105, v105
	v_min_f32_e32 v106, 0, v96
	v_min_f32_e32 v107, 0, v97
	v_pk_add_f32 v[104:105], v[104:105], v[190:191]
	v_log_f32_e32 v104, v104
	v_log_f32_e32 v105, v105
	s_nop 0
	v_fma_f32 v106, v104, s35, v106
	v_fma_f32 v107, v105, s35, v107
	v_pk_fma_f32 v[192:193], v[106:107], v[188:189], v[192:193]
	global_store_dwordx2 v165, v[192:193], s[48:49]
	s_branch .LBB0_517
; #define LAS __attribute__((address_space(3)))
; DI void phase_gla_prep(const Params& p, LAS unsigned char* lds) {
;     ...
;     float wg0[16], wg1[16];
; #pragma unroll
;     for (int r = 0; r < 16; ++r) { wg0[r] = p.in[9][r * 1024 + ch0]; wg1[r] = p.in[9][r * 1024 + ch0 + 1]; }
;     const float bs0 = p.in[10][ch0], bs1 = p.in[10][ch0 + 1];
;     for (int u = blockIdx.x; u < 256; u += gridDim.x) {
;         const size_t tokb = (size_t)u * 64;
;         __syncthreads();
;         {
;             LAS bf16_t* wl = (LAS bf16_t*)(lds + 8192);
;             LAS float* part = (LAS float*)(lds + 4096);
;             const bf16_t* wsrc = (const bf16_t*)(p.ws + W_B_IN) + (size_t)6144 * 2048;
; #pragma unroll
;             for (int i = 0; i < 8; ++i) { const int c = tid + i * 512; *(LAS u32x4*)(wl + (c >> 8) * 2056 + (c & 255) * 8) = *(const u32x4*)(wsrc + (size_t)c * 8); }
;             __syncthreads();
;             const int w = tid >> 6, lane = tid & 63, i16 = lane & 15, quad = lane >> 4, mt = w & 3, kh = w >> 2;
;             const bf16_t* xr = (const bf16_t*)(p.ws + XG) + (tokb + 16 * mt + i16) * DM + kh * 1024 + 8 * quad;
.Lgp_orig:
	s_load_dwordx2 s[12:13], s[0:1], 0xf0
	s_load_dwordx4 s[8:11], s[0:1], 0x48
	v_lshlrev_b32_e32 v4, 1, v0
	v_ashrrev_i32_e32 v5, 31, v4
	v_lshlrev_b64 v[2:3], 2, v[4:5]
	v_lshlrev_b32_e32 v1, 4, v0
	s_waitcnt lgkmcnt(0)
	v_lshl_add_u64 v[22:23], s[8:9], 0, v[2:3]
	v_add_co_u32_e32 v14, vcc, 0x1000, v22
	v_and_b32_e32 v1, 0xff0, v1
	s_nop 0
	v_addc_co_u32_e32 v15, vcc, 0, v23, vcc
	v_add_co_u32_e32 v16, vcc, 0x2000, v22
	v_add_u32_e32 v66, 0, v1
	s_nop 0
	v_addc_co_u32_e32 v17, vcc, 0, v23, vcc
	v_add_co_u32_e32 v18, vcc, 0x3000, v22
	v_and_b32_e32 v64, 15, v0
	s_nop 0
	v_addc_co_u32_e32 v19, vcc, 0, v23, vcc
	v_add_co_u32_e32 v28, vcc, 0x4000, v22
	global_load_dwordx2 v[6:7], v[22:23], off
	global_load_dwordx2 v[8:9], v[14:15], off
	global_load_dwordx2 v[10:11], v[16:17], off
	global_load_dwordx2 v[12:13], v[18:19], off
	v_addc_co_u32_e32 v29, vcc, 0, v23, vcc
	v_add_co_u32_e32 v30, vcc, 0x5000, v22
	v_lshrrev_b32_e32 v1, 2, v0
	s_nop 0
	v_addc_co_u32_e32 v31, vcc, 0, v23, vcc
	v_add_co_u32_e32 v32, vcc, 0x6000, v22
	v_and_b32_e32 v68, 48, v1
	s_nop 0
	v_addc_co_u32_e32 v33, vcc, 0, v23, vcc
	v_add_co_u32_e32 v34, vcc, 0x7000, v22
	s_mov_b64 s[6:7], vcc
	v_add_co_u32_e32 v24, vcc, 0x8000, v22
	v_mul_u32_u24_e32 v1, 0x1010, v64
	s_nop 0
	v_addc_co_u32_e32 v25, vcc, 0, v23, vcc
	v_add_co_u32_e32 v26, vcc, 0x9000, v22
	s_add_u32 s24, s12, 0xbf00000
	s_nop 0
	v_addc_co_u32_e32 v27, vcc, 0, v23, vcc
	v_add_co_u32_e32 v36, vcc, 0xa000, v22
	v_bfe_u32 v65, v0, 4, 2
	s_nop 0
	v_addc_co_u32_e32 v37, vcc, 0, v23, vcc
	v_add_co_u32_e32 v38, vcc, 0xb000, v22
	s_addc_u32 s25, s13, 0
	s_nop 0
	v_addc_co_u32_e32 v39, vcc, 0, v23, vcc
	v_add_co_u32_e32 v40, vcc, 0xc000, v22
	v_lshl_or_b32 v69, v65, 2, v68
	s_nop 0
	v_addc_co_u32_e32 v41, vcc, 0, v23, vcc
	v_add_co_u32_e32 v42, vcc, 0xd000, v22
	v_lshlrev_b32_e32 v79, 6, v69
	s_nop 0
	v_addc_co_u32_e32 v43, vcc, 0, v23, vcc
	v_add_co_u32_e32 v44, vcc, 0xe000, v22
	v_ashrrev_i32_e32 v67, 8, v0
	s_nop 0
	v_addc_co_u32_e32 v45, vcc, 0, v23, vcc
	v_add_co_u32_e32 v46, vcc, 0xf000, v22
	v_cmp_gt_u32_e64 s[8:9], s14, v0
	s_nop 0
	v_addc_co_u32_e32 v47, vcc, 0, v23, vcc
	global_load_dwordx2 v[14:15], v[40:41], off
	global_load_dwordx2 v[54:55], v[42:43], off
	global_load_dwordx2 v[16:17], v[44:45], off
	global_load_dwordx2 v[56:57], v[46:47], off
	global_load_dwordx2 v[18:19], v[24:25], off
	global_load_dwordx2 v[58:59], v[26:27], off
	global_load_dwordx2 v[20:21], v[36:37], off
	global_load_dwordx2 v[60:61], v[38:39], off
	v_addc_co_u32_e64 v35, vcc, 0, v23, s[6:7]
	global_load_dwordx2 v[22:23], v[28:29], off
	global_load_dwordx2 v[24:25], v[30:31], off
	global_load_dwordx2 v[26:27], v[32:33], off
	global_load_dwordx2 v[62:63], v[34:35], off
	v_lshl_add_u64 v[28:29], s[10:11], 0, v[2:3]
	global_load_dwordx2 v[28:29], v[28:29], off
	v_mul_i32_i24_e32 v32, 0xffffeff4, v64
	v_add_u32_e32 v34, 0x200, v0
	v_add3_u32 v70, 0, v1, v32
	v_lshrrev_b32_e32 v32, 8, v34
	v_add_u32_e32 v36, 0x400, v0
	v_mul_i32_i24_e32 v72, 0x1010, v32
	v_lshrrev_b32_e32 v32, 8, v36
	v_add_u32_e32 v38, 0x600, v0
	v_mul_i32_i24_e32 v73, 0x1010, v32
	v_lshrrev_b32_e32 v32, 8, v38
	v_add_u32_e32 v40, 0x800, v0
	v_mul_i32_i24_e32 v74, 0x1010, v32
	v_lshrrev_b32_e32 v32, 8, v40
	v_add_u32_e32 v42, 0xa00, v0
	v_mul_i32_i24_e32 v75, 0x1010, v32
	v_lshrrev_b32_e32 v32, 8, v42
	v_add_u32_e32 v44, 0xc00, v0
	v_mul_i32_i24_e32 v76, 0x1010, v32
	v_lshrrev_b32_e32 v32, 8, v44
	v_add_u32_e32 v46, 0xe00, v0
	v_mul_i32_i24_e32 v77, 0x1010, v32
	v_lshrrev_b32_e32 v32, 8, v46
	s_add_u32 s10, s12, 0x4000000
	v_ashrrev_i32_e32 v1, 31, v0
	v_ashrrev_i32_e32 v35, 31, v34
	v_ashrrev_i32_e32 v37, 31, v36
	v_ashrrev_i32_e32 v39, 31, v38
	v_ashrrev_i32_e32 v41, 31, v40
	v_ashrrev_i32_e32 v43, 31, v42
	v_ashrrev_i32_e32 v45, 31, v44
	v_ashrrev_i32_e32 v47, 31, v46
	v_mul_i32_i24_e32 v78, 0x1010, v32
	v_lshl_or_b32 v32, v64, 2, v79
	s_addc_u32 s11, s13, 0
	v_add_u32_e32 v130, 0, v32
	v_lshl_add_u64 v[32:33], v[0:1], 4, s[10:11]
	v_lshl_add_u64 v[34:35], v[34:35], 4, s[10:11]
	v_lshl_add_u64 v[36:37], v[36:37], 4, s[10:11]
	v_lshl_add_u64 v[38:39], v[38:39], 4, s[10:11]
	v_lshl_add_u64 v[40:41], v[40:41], 4, s[10:11]
	v_lshl_add_u64 v[42:43], v[42:43], 4, s[10:11]
	v_lshl_add_u64 v[44:45], v[44:45], 4, s[10:11]
	v_lshl_add_u64 v[46:47], v[46:47], 4, s[10:11]
	s_mov_b64 s[10:11], 0x1ff10000
	s_movk_i32 s15, 0x1010
	v_lshl_add_u64 v[2:3], s[12:13], 0, v[2:3]
	s_mov_b64 s[6:7], 0x18700000
	v_lshl_add_u64 v[30:31], v[2:3], 0, s[6:7]
	v_lshlrev_b32_e32 v2, 10, v67
	v_ashrrev_i32_e32 v3, 31, v2
	v_mul_i32_i24_e32 v71, 0x1010, v67
	s_movk_i32 s3, 0x3000
	s_movk_i32 s29, 0x6000
	s_mov_b32 s31, 0x9000
	s_mov_b32 s35, 0xd000
	v_cmp_eq_u32_e64 s[6:7], 1, v67
	v_add_u32_e32 v131, 0x80, v130
	v_add_u32_e32 v133, v66, v72
	v_add_u32_e32 v134, v66, v73
	v_add_u32_e32 v135, v66, v74
	v_add_u32_e32 v136, v66, v75
	v_add_u32_e32 v137, v66, v76
	v_add_u32_e32 v138, v66, v77
	v_add_u32_e32 v139, v66, v78
	s_mov_b64 s[26:27], 0x200
	v_add_u32_e32 v140, v70, v79
	s_mov_b32 s28, 0x3a000000
	s_waitcnt vmcnt(0)
	v_mov_b32_e32 v50, v15
	v_mov_b32_e32 v51, v55
	v_mov_b32_e32 v15, v54
	v_mov_b32_e32 v48, v17
	v_mov_b32_e32 v54, v19
	v_mov_b32_e32 v55, v59
	v_mov_b32_e32 v19, v58
	v_lshlrev_b32_e32 v58, 2, v69
	v_mov_b32_e32 v59, 0
	v_lshl_add_u64 v[0:1], s[12:13], 0, v[58:59]
	v_mov_b32_e32 v52, v21
	v_mov_b32_e32 v53, v61
	v_mov_b32_e32 v21, v60
	v_lshl_add_u64 v[60:61], v[0:1], 0, s[10:11]
	v_lshlrev_b32_e32 v0, 11, v67
	v_mad_u32_u24 v0, v64, s15, v0
	v_lshlrev_b32_e32 v1, 4, v65
	v_add3_u32 v0, v0, v1, 0
	v_add_u32_e32 v132, 0x2000, v0
	v_or_b32_e32 v0, v68, v64
	v_lshl_or_b32 v58, v0, 12, v1
	v_lshl_add_u64 v[0:1], v[2:3], 1, v[58:59]
	v_lshl_add_u64 v[0:1], s[12:13], 0, v[0:1]
	s_mov_b64 s[10:11], 0x1bf00100
	v_mov_b32_e32 v49, v57
	v_mov_b32_e32 v17, v56
	v_mov_b32_e32 v56, v27
	v_mov_b32_e32 v57, v63
	v_mov_b32_e32 v27, v62
	v_lshl_add_u64 v[62:63], v[4:5], 1, s[24:25]
	v_lshl_add_u64 v[64:65], v[0:1], 0, s[10:11]
	v_add_u32_e32 v58, v66, v71
	s_mov_b32 s30, 0x358637bd
	s_mov_b32 s42, 0x800000
	s_mov_b32 s43, 0x10000
	s_mov_b32 s44, 0x13000
	s_mov_b32 s45, 0x16000
	s_mov_b32 s46, 0x19000
	s_mov_b32 s47, 0x1c000
	s_mov_b32 s48, 0x1f000
	s_mov_b32 s49, 0x22000
	s_mov_b32 s50, 0x26000
	s_mov_b32 s51, 0x29000
	s_mov_b32 s52, 0x2c000
	s_mov_b32 s53, 0x2f000
	s_mov_b32 s54, 0xbfb8aa3b
	s_mov_b32 s55, 0x3f317217
	s_mov_b32 s56, 0x7f800000
	s_mov_b32 s34, 0x3d800000
	v_mov_b32_e32 v141, 0x3200
	v_mov_b32_e32 v142, 0x41b17218
	s_mov_b32 s36, s2
